# v68 + hyena: 65 multiply-by-(+-i) packed ops folded into their consumers via op_sel/neg modifiers (numerically checked)
# speedup vs baseline: 1.0080x; 1.0027x over previous
; #define LAS __attribute__((address_space(3)))
; #define OPAQUE_I(x) asm volatile("" : "+v"(x))
; template <int R, bool INV> DEV void dft_regs(cf (&v)[R]) {
; #pragma unroll
;     for (int s = R; s >= 2; s >>= 1) {
;         const int h = s >> 1;
; #pragma unroll
;         for (int b = 0; b < R; b += s) {
; #pragma unroll
;             for (int k = 0; k < h; ++k) {
;                 const cf a = v[b + k], c = v[b + k + h];
;                 v[b + k] = a + c;
;                 const cf d = a - c;
;                 const int m = k * (32 / s);
;                 const float wr = tw_cos(m), wi = INV ? tw_sin(m) : -tw_sin(m);
;                 v[b + k + h] = cf{d.x * wr - d.y * wi, d.x * wi + d.y * wr};
;             }
;         }
;     }
; }
; DEV void fft_f1x2(LAS cf* buf0, LAS cf* buf1, const cf (&z0)[8], const cf (&z1)[8], int tid) {
;     OPAQUE_I(tid);
;     cf v[16], u[16];
; #pragma unroll
;     for (int q = 0; q < 8; ++q) { v[q] = z0[q]; v[q + 8] = cf{0.f, 0.f}; u[q] = z1[q]; u[q + 8] = cf{0.f, 0.f}; }
;     dft_regs<16, false>(v); dft_regs<16, false>(u);
.LBB0_519:
	v_pk_mul_f32 v[16:17], v[26:27], s[16:17] op_sel_hi:[1,0]
	v_pk_add_f32 v[0:1], v[24:25], 0 op_sel_hi:[1,0]
	v_pk_fma_f32 v[18:19], v[26:27], s[84:85], v[16:17] op_sel:[0,0,1] op_sel_hi:[1,0,0] neg_hi:[0,0,1]
	v_pk_add_f32 v[16:17], v[22:23], 0 op_sel_hi:[1,0]
	v_mov_b32_e32 v4, v24
	v_mov_b32_e32 v5, v25
	v_pk_add_f32 v[80:81], v[0:1], v[16:17]
	v_pk_add_f32 v[0:1], v[0:1], v[16:17] neg_lo:[0,1] neg_hi:[0,1]
	v_pk_fma_f32 v[66:67], v[22:23], 0, v[22:23] op_sel:[0,0,1] op_sel_hi:[1,0,0] neg_hi:[0,0,1]
	v_mov_b32_e32 v5, v25
	v_pk_add_f32 v[2:3], v[30:31], 0 op_sel_hi:[1,0]
	v_pk_mul_f32 v[6:7], v[30:31], s[84:85] op_sel_hi:[1,0]
	v_pk_add_f32 v[68:69], v[32:33], 0 op_sel_hi:[1,0]
	v_pk_fma_f32 v[8:9], v[30:31], s[16:17], v[6:7] op_sel:[0,0,1] op_sel_hi:[1,0,0] neg_hi:[0,0,1]
	v_pk_add_f32 v[82:83], v[2:3], v[68:69]
	v_pk_add_f32 v[2:3], v[2:3], v[68:69] neg_lo:[0,1] neg_hi:[0,1]
	v_pk_add_f32 v[6:7], v[28:29], 0 op_sel_hi:[1,0]
	v_pk_add_f32 v[72:73], v[34:35], 0 op_sel_hi:[1,0]
	v_pk_mul_f32 v[16:17], v[2:3], s[18:19] op_sel_hi:[1,0]
	v_pk_mul_f32 v[10:11], v[28:29], s[18:19] op_sel_hi:[1,0]
	v_pk_fma_f32 v[68:69], v[2:3], s[18:19], v[16:17] op_sel:[0,0,1] op_sel_hi:[1,0,0]
	v_pk_fma_f32 v[2:3], v[2:3], s[18:19], v[16:17] op_sel_hi:[1,0,0] neg_lo:[0,0,1] neg_hi:[0,0,1]
	v_pk_add_f32 v[16:17], v[6:7], v[72:73]
	v_pk_add_f32 v[6:7], v[6:7], v[72:73] neg_lo:[0,1] neg_hi:[0,1]
	v_pk_add_f32 v[14:15], v[26:27], 0 op_sel_hi:[1,0]
	v_pk_add_f32 v[76:77], v[36:37], 0 op_sel_hi:[1,0]
	v_pk_fma_f32 v[12:13], v[28:29], s[18:19], v[10:11] op_sel:[0,0,1] op_sel_hi:[1,0,0]
	v_pk_fma_f32 v[10:11], v[28:29], s[18:19], v[10:11] op_sel_hi:[1,0,0] neg_lo:[0,0,1] neg_hi:[0,0,1]
	v_pk_add_f32 v[72:73], v[14:15], v[76:77]
	v_pk_add_f32 v[14:15], v[14:15], v[76:77] neg_lo:[0,1] neg_hi:[0,1]
	v_pk_add_f32 v[76:77], v[4:5], v[66:67]
	v_pk_add_f32 v[4:5], v[4:5], v[66:67] neg_lo:[0,1] neg_hi:[0,1]
	v_mov_b32_e32 v10, v33
	s_mov_b32 s30, s85
	s_mov_b32 s31, s0
	v_pk_mul_f32 v[70:71], v[32:33], s[84:85] op_sel_hi:[0,1]
	v_pk_fma_f32 v[70:71], v[10:11], s[30:31], v[70:71] op_sel_hi:[0,1,1] neg_lo:[0,0,1] neg_hi:[0,0,1]
	v_mul_f32_e32 v10, 0x3f3504f3, v34
	v_mov_b32_e32 v74, v35
	s_mov_b32 s28, s97
	s_mov_b32 s29, s96
	s_mov_b32 s24, s85
	s_mov_b32 s25, s84
	v_pk_add_f32 v[84:85], v[8:9], v[70:71]
	v_pk_add_f32 v[8:9], v[8:9], v[70:71] neg_lo:[0,1] neg_hi:[0,1]
	v_pk_fma_f32 v[74:75], v[74:75], s[28:29], v[10:11] op_sel_hi:[0,1,0] neg_lo:[0,0,1] neg_hi:[0,0,1]
	v_mov_b32_e32 v10, v37
	s_mov_b32 s34, s84
	s_mov_b32 s35, s88
	v_pk_mul_f32 v[78:79], v[36:37], s[24:25] op_sel_hi:[0,1]
	v_pk_mul_f32 v[66:67], v[8:9], s[18:19] op_sel_hi:[1,0]
	v_mov_b32_e32 v13, v11
	v_pk_fma_f32 v[78:79], v[10:11], s[34:35], v[78:79] op_sel_hi:[0,1,1] neg_lo:[0,0,1] neg_hi:[0,0,1]
	v_pk_fma_f32 v[70:71], v[8:9], s[18:19], v[66:67] op_sel:[0,0,1] op_sel_hi:[1,0,0] neg_hi:[0,0,1]
	v_pk_add_f32 v[10:11], v[12:13], v[74:75] neg_lo:[0,1] neg_hi:[0,1]
	v_pk_add_f32 v[66:67], v[80:81], v[16:17]
	v_pk_add_f32 v[16:17], v[80:81], v[16:17] neg_lo:[0,1] neg_hi:[0,1]
	v_pk_add_f32 v[8:9], v[12:13], v[74:75]
	v_pk_add_f32 v[12:13], v[18:19], v[78:79]
	v_pk_add_f32 v[18:19], v[18:19], v[78:79] neg_lo:[0,1] neg_hi:[0,1]
	v_mul_f32_e32 v2, 0x3f3504f3, v14
	v_pk_add_f32 v[78:79], v[82:83], v[72:73]
	v_pk_add_f32 v[82:83], v[82:83], v[72:73] neg_lo:[0,1] neg_hi:[0,1]
	v_pk_add_f32 v[74:75], v[0:1], v[6:7] op_sel:[0,1] op_sel_hi:[1,0] neg_hi:[0,1]
	v_pk_fma_f32 v[14:15], v[14:15], s[28:29], v[2:3] op_sel:[1,0,0] op_sel_hi:[1,1,0] neg_lo:[0,0,1] neg_hi:[0,0,1]
	v_pk_add_f32 v[72:73], v[0:1], v[6:7] op_sel:[0,1] op_sel_hi:[1,0] neg_lo:[0,1]
	v_mov_b32_e32 v69, v3
	v_mul_f32_e32 v2, 0x3f3504f3, v18
	v_mov_b32_e32 v80, v72
	v_mov_b32_e32 v81, v73
	v_pk_fma_f32 v[18:19], v[18:19], s[28:29], v[2:3] op_sel:[1,0,0] op_sel_hi:[1,1,0] neg_lo:[0,0,1] neg_hi:[0,0,1]
	v_pk_add_f32 v[0:1], v[68:69], v[14:15] neg_lo:[0,1] neg_hi:[0,1]
	v_pk_add_f32 v[2:3], v[68:69], v[14:15]
	v_pk_add_f32 v[14:15], v[0:1], 0 op_sel:[1,0] op_sel_hi:[0,0] neg_hi:[1,0]
	v_pk_add_f32 v[6:7], v[76:77], v[8:9]
	v_pk_add_f32 v[0:1], v[76:77], v[8:9] neg_lo:[0,1] neg_hi:[0,1]
	v_pk_add_f32 v[86:87], v[4:5], v[10:11] op_sel:[0,1] op_sel_hi:[1,0] neg_hi:[0,1]
	v_pk_add_f32 v[68:69], v[66:67], v[78:79]
	v_pk_add_f32 v[8:9], v[84:85], v[12:13]
	v_pk_add_f32 v[72:73], v[84:85], v[12:13] neg_lo:[0,1] neg_hi:[0,1]
	v_pk_add_f32 v[88:89], v[70:71], v[18:19]
	v_pk_add_f32 v[76:77], v[6:7], v[8:9]
	v_pk_add_f32 v[12:13], v[4:5], v[10:11] op_sel:[0,1] op_sel_hi:[1,0] neg_lo:[0,1]
	v_pk_add_f32 v[8:9], v[6:7], v[8:9] neg_lo:[0,1] neg_hi:[0,1]
	v_pk_add_f32 v[6:7], v[0:1], v[72:73] op_sel:[0,1] op_sel_hi:[1,0] neg_hi:[0,1]
	v_mov_b32_e32 v4, v12
	v_mov_b32_e32 v5, v13
	v_pk_add_f32 v[10:11], v[0:1], v[72:73] op_sel:[0,1] op_sel_hi:[1,0] neg_lo:[0,1]
	v_pk_add_f32 v[0:1], v[70:71], v[18:19] neg_lo:[0,1] neg_hi:[0,1]
	v_pk_add_f32 v[70:71], v[74:75], v[2:3]
	v_pk_add_f32 v[90:91], v[0:1], 0 op_sel:[1,0] op_sel_hi:[0,0] neg_hi:[1,0]
	v_pk_add_f32 v[2:3], v[74:75], v[2:3] neg_lo:[0,1] neg_hi:[0,1]
	v_pk_add_f32 v[0:1], v[66:67], v[78:79] neg_lo:[0,1] neg_hi:[0,1]
	v_pk_add_f32 v[78:79], v[16:17], v[82:83] op_sel:[0,1] op_sel_hi:[1,0] neg_hi:[0,1]
	v_pk_add_f32 v[72:73], v[16:17], v[82:83] op_sel:[0,1] op_sel_hi:[1,0] neg_lo:[0,1]
	v_mov_b32_e32 v84, v0
	v_mov_b32_e32 v85, v1
	v_mov_b32_e32 v0, v72
	v_mov_b32_e32 v1, v73
	v_mov_b32_e32 v72, v2
	v_mov_b32_e32 v73, v3
	v_pk_add_f32 v[12:13], v[80:81], v[14:15] neg_lo:[0,1] neg_hi:[0,1]
	v_pk_add_f32 v[18:19], v[80:81], v[14:15]
	v_mov_b32_e32 v2, v12
	v_mov_b32_e32 v3, v13
	v_mov_b32_e32 v12, v8
; #define LAS __attribute__((address_space(3)))
; #define OPAQUE_I(x) asm volatile("" : "+v"(x))
; template <int R, bool INV> DEV void dft_regs(cf (&v)[R]) {
; #pragma unroll
;     for (int s = R; s >= 2; s >>= 1) {
;         const int h = s >> 1;
; #pragma unroll
;         for (int b = 0; b < R; b += s) {
; #pragma unroll
;             for (int k = 0; k < h; ++k) {
;                 const cf a = v[b + k], c = v[b + k + h];
;                 v[b + k] = a + c;
;                 const cf d = a - c;
;                 const int m = k * (32 / s);
;                 const float wr = tw_cos(m), wi = INV ? tw_sin(m) : -tw_sin(m);
;                 v[b + k + h] = cf{d.x * wr - d.y * wi, d.x * wi + d.y * wr};
;             }
;         }
;     }
; }
; DEV void fft_f1x2(LAS cf* buf0, LAS cf* buf1, const cf (&z0)[8], const cf (&z1)[8], int tid) {
;     OPAQUE_I(tid);
;     cf v[16], u[16];
; #pragma unroll
;     for (int q = 0; q < 8; ++q) { v[q] = z0[q]; v[q + 8] = cf{0.f, 0.f}; u[q] = z1[q]; u[q + 8] = cf{0.f, 0.f}; }
;     dft_regs<16, false>(v); dft_regs<16, false>(u);
	v_mov_b32_e32 v13, v9
	v_mov_b32_e32 v8, v10
	v_mov_b32_e32 v9, v11
	v_pk_mul_f32 v[92:93], v[50:51], s[16:17] op_sel_hi:[1,0]
	v_pk_add_f32 v[10:11], v[86:87], v[88:89] neg_lo:[0,1] neg_hi:[0,1]
	v_pk_fma_f32 v[94:95], v[50:51], s[84:85], v[92:93] op_sel:[0,0,1] op_sel_hi:[1,0,0] neg_hi:[0,0,1]
	v_mov_b32_e32 v14, v10
	v_mov_b32_e32 v15, v11
	v_pk_add_f32 v[66:67], v[4:5], v[90:91] neg_lo:[0,1] neg_hi:[0,1]
	v_mov_b32_e32 v10, v66
	v_mov_b32_e32 v11, v67
	v_pk_add_f32 v[92:93], v[46:47], 0 op_sel_hi:[1,0]
	v_pk_add_f32 v[66:67], v[38:39], 0 op_sel_hi:[1,0]
	v_mov_b32_e32 v108, v41
	v_pk_mul_f32 v[110:111], v[40:41], s[24:25] op_sel_hi:[0,1]
	v_pk_fma_f32 v[108:109], v[108:109], s[34:35], v[110:111] op_sel_hi:[0,1,1] neg_lo:[0,0,1] neg_hi:[0,0,1]
	v_pk_add_f32 v[110:111], v[66:67], v[92:93]
	v_pk_add_f32 v[66:67], v[66:67], v[92:93] neg_lo:[0,1] neg_hi:[0,1]
	v_mov_b32_e32 v82, v38
	v_mov_b32_e32 v83, v39
	v_pk_fma_f32 v[96:97], v[46:47], 0, v[46:47] op_sel:[0,0,1] op_sel_hi:[1,0,0] neg_hi:[0,0,1]
	v_mov_b32_e32 v83, v39
	v_pk_add_f32 v[80:81], v[42:43], 0 op_sel_hi:[1,0]
	v_pk_add_f32 v[98:99], v[48:49], 0 op_sel_hi:[1,0]
	v_mov_b32_e32 v112, v66
	v_mov_b32_e32 v113, v67
	v_pk_add_f32 v[74:75], v[4:5], v[90:91]
	v_pk_mul_f32 v[4:5], v[42:43], s[84:85] op_sel_hi:[1,0]
	v_pk_add_f32 v[66:67], v[80:81], v[98:99]
	v_pk_add_f32 v[80:81], v[80:81], v[98:99] neg_lo:[0,1] neg_hi:[0,1]
	v_pk_add_f32 v[16:17], v[86:87], v[88:89]
	v_pk_fma_f32 v[86:87], v[42:43], s[16:17], v[4:5] op_sel:[0,0,1] op_sel_hi:[1,0,0] neg_hi:[0,0,1]
	v_mov_b32_e32 v100, v49
	v_pk_mul_f32 v[102:103], v[48:49], s[84:85] op_sel_hi:[0,1]
	v_pk_mul_f32 v[92:93], v[80:81], s[18:19] op_sel_hi:[1,0]
	v_pk_add_f32 v[4:5], v[44:45], 0 op_sel_hi:[1,0]
	v_pk_mul_f32 v[88:89], v[44:45], s[18:19] op_sel_hi:[1,0]
	v_pk_fma_f32 v[100:101], v[100:101], s[30:31], v[102:103] op_sel_hi:[0,1,1] neg_lo:[0,0,1] neg_hi:[0,0,1]
	v_pk_add_f32 v[102:103], v[52:53], 0 op_sel_hi:[1,0]
	v_pk_fma_f32 v[98:99], v[80:81], s[18:19], v[92:93] op_sel:[0,0,1] op_sel_hi:[1,0,0] neg_hi:[0,0,1]
	v_pk_fma_f32 v[90:91], v[44:45], s[18:19], v[88:89] op_sel:[0,0,1] op_sel_hi:[1,0,0] neg_hi:[0,0,1]
	v_mul_f32_e32 v104, 0x3f3504f3, v52
	v_mov_b32_e32 v106, v53
	v_pk_add_f32 v[80:81], v[4:5], v[102:103]
	v_pk_add_f32 v[4:5], v[4:5], v[102:103] neg_lo:[0,1] neg_hi:[0,1]
	v_pk_add_f32 v[88:89], v[50:51], 0 op_sel_hi:[1,0]
	v_pk_fma_f32 v[104:105], v[106:107], s[28:29], v[104:105] op_sel_hi:[0,1,0] neg_lo:[0,0,1] neg_hi:[0,0,1]
	v_pk_add_f32 v[106:107], v[40:41], 0 op_sel_hi:[1,0]
	v_mov_b32_e32 v114, v21
	v_pk_add_f32 v[92:93], v[88:89], v[106:107]
	v_pk_add_f32 v[88:89], v[88:89], v[106:107] neg_lo:[0,1] neg_hi:[0,1]
	s_mov_b32 s2, s86
	v_mul_f32_e32 v102, 0x3f3504f3, v88
	v_pk_fma_f32 v[88:89], v[88:89], s[28:29], v[102:103] op_sel:[1,0,0] op_sel_hi:[1,1,0] neg_lo:[0,0,1] neg_hi:[0,0,1]
	v_pk_add_f32 v[102:103], v[82:83], v[96:97]
	v_pk_add_f32 v[82:83], v[82:83], v[96:97] neg_lo:[0,1] neg_hi:[0,1]
	s_mov_b32 s3, s4
	s_mov_b32 s10, s4
	s_mov_b32 s6, s94
	v_pk_add_f32 v[106:107], v[86:87], v[100:101]
	v_pk_add_f32 v[86:87], v[86:87], v[100:101] neg_lo:[0,1] neg_hi:[0,1]
	s_mov_b32 s7, s82
	v_pk_mul_f32 v[96:97], v[86:87], s[18:19] op_sel_hi:[1,0]
	s_mov_b32 s8, s82
	v_pk_fma_f32 v[100:101], v[86:87], s[18:19], v[96:97] op_sel:[0,0,1] op_sel_hi:[1,0,0] neg_hi:[0,0,1]
	s_lshl_b32 s92, s19, 13
	v_lshl_add_u64 v[232:233], s[92:93], 2, v[54:55]
	global_load_dwordx4 v[170:173], v[232:233], off offset:48
	global_load_dwordx4 v[174:177], v[232:233], off offset:32
	global_load_dwordx4 v[178:181], v[232:233], off offset:16
	global_load_dwordx4 v[182:185], v[232:233], off
	v_pk_add_f32 v[86:87], v[90:91], v[104:105]
	v_pk_add_f32 v[90:91], v[90:91], v[104:105] neg_lo:[0,1] neg_hi:[0,1]
	s_mov_b32 s1, s85
	s_mov_b32 s89, s84
	v_pk_add_f32 v[96:97], v[94:95], v[108:109]
	v_pk_add_f32 v[94:95], v[94:95], v[108:109] neg_lo:[0,1] neg_hi:[0,1]
	v_mul_f32_e32 v104, 0x3f3504f3, v94
	v_pk_fma_f32 v[94:95], v[94:95], s[28:29], v[104:105] op_sel:[1,0,0] op_sel_hi:[1,1,0] neg_lo:[0,0,1] neg_hi:[0,0,1]
	v_pk_add_f32 v[104:105], v[110:111], v[80:81]
	v_pk_add_f32 v[80:81], v[110:111], v[80:81] neg_lo:[0,1] neg_hi:[0,1]
	v_pk_add_f32 v[110:111], v[66:67], v[92:93]
	v_pk_add_f32 v[66:67], v[66:67], v[92:93] neg_lo:[0,1] neg_hi:[0,1]
	v_pk_add_f32 v[92:93], v[66:67], 0 op_sel:[1,0] op_sel_hi:[0,0] neg_hi:[1,0]
	v_pk_add_f32 v[66:67], v[112:113], v[4:5] op_sel:[0,1] op_sel_hi:[1,0] neg_hi:[0,1]
	v_pk_add_f32 v[4:5], v[112:113], v[4:5] op_sel:[0,1] op_sel_hi:[1,0] neg_lo:[0,1]
	v_pk_add_f32 v[112:113], v[98:99], v[88:89]
	v_pk_add_f32 v[88:89], v[98:99], v[88:89] neg_lo:[0,1] neg_hi:[0,1]
	v_pk_add_f32 v[98:99], v[102:103], v[86:87]
	v_pk_add_f32 v[86:87], v[102:103], v[86:87] neg_lo:[0,1] neg_hi:[0,1]
	v_pk_add_f32 v[108:109], v[106:107], v[96:97]
	v_pk_add_f32 v[106:107], v[106:107], v[96:97] neg_lo:[0,1] neg_hi:[0,1]
	v_pk_add_f32 v[96:97], v[82:83], v[90:91] op_sel:[0,1] op_sel_hi:[1,0] neg_hi:[0,1]
	v_pk_add_f32 v[90:91], v[82:83], v[90:91] op_sel:[0,1] op_sel_hi:[1,0] neg_lo:[0,1]
	v_pk_add_f32 v[82:83], v[100:101], v[94:95]
	v_pk_add_f32 v[94:95], v[100:101], v[94:95] neg_lo:[0,1] neg_hi:[0,1]
	v_pk_add_f32 v[100:101], v[94:95], 0 op_sel:[1,0] op_sel_hi:[0,0] neg_hi:[1,0]
	v_pk_add_f32 v[94:95], v[104:105], v[110:111]
	v_pk_add_f32 v[110:111], v[104:105], v[110:111] neg_lo:[0,1] neg_hi:[0,1]
	v_pk_add_f32 v[104:105], v[80:81], v[92:93]
	v_pk_add_f32 v[92:93], v[80:81], v[92:93] neg_lo:[0,1] neg_hi:[0,1]
	v_pk_add_f32 v[80:81], v[66:67], v[112:113]
	v_pk_add_f32 v[66:67], v[66:67], v[112:113] neg_lo:[0,1] neg_hi:[0,1]
	v_mov_b32_e32 v102, v66
; #define LAS __attribute__((address_space(3)))
; #define SINCOSPI(x, s, c) do { const float hx_ = 0.5f * (x); *(s) = __builtin_amdgcn_sinf(hx_); *(c) = __builtin_amdgcn_cosf(hx_); } while (0)
; template <int R, bool INV> DEV void dft_regs(cf (&v)[R]) {
; #pragma unroll
;     for (int s = R; s >= 2; s >>= 1) {
;         const int h = s >> 1;
; #pragma unroll
;         for (int b = 0; b < R; b += s) {
; #pragma unroll
;             for (int k = 0; k < h; ++k) {
;                 const cf a = v[b + k], c = v[b + k + h];
;                 v[b + k] = a + c;
;                 const cf d = a - c;
;                 const int m = k * (32 / s);
;                 const float wr = tw_cos(m), wi = INV ? tw_sin(m) : -tw_sin(m);
;                 v[b + k + h] = cf{d.x * wr - d.y * wi, d.x * wi + d.y * wr};
;             }
;         }
;     }
; }
; DEV void fft_f1x2(LAS cf* buf0, LAS cf* buf1, const cf (&z0)[8], const cf (&z1)[8], int tid) {
;     ...
;     float sn, cs; SINCOSPI(-(float)tid * (2.0f / 8192.0f), &sn, &cs);
;     const cf w = cf{cs, sn}; cf wp = cf{1.f, 0.f};
;     LAS cf* p0 = buf0 + PADI(tid); LAS cf* p1 = buf1 + PADI(tid);
; #pragma unroll
;     for (int p = 0; p < 16; ++p) { p0[544 * p] = cmul(v[BR16[p]], wp); p1[544 * p] = cmul(u[BR16[p]], wp); wp = cmul(wp, w); }
	v_mov_b32_e32 v103, v67
	v_pk_add_f32 v[112:113], v[4:5], v[88:89] op_sel:[0,1] op_sel_hi:[1,0] neg_hi:[0,1]
	v_pk_add_f32 v[66:67], v[4:5], v[88:89] op_sel:[0,1] op_sel_hi:[1,0] neg_lo:[0,1]
	v_mov_b32_e32 v4, v66
	v_mov_b32_e32 v5, v67
	v_pk_add_f32 v[88:89], v[98:99], v[108:109]
	v_pk_add_f32 v[66:67], v[98:99], v[108:109] neg_lo:[0,1] neg_hi:[0,1]
	v_mov_b32_e32 v98, v66
	v_mov_b32_e32 v99, v67
	v_pk_add_f32 v[108:109], v[86:87], v[106:107] op_sel:[0,1] op_sel_hi:[1,0] neg_hi:[0,1]
	v_pk_add_f32 v[66:67], v[86:87], v[106:107] op_sel:[0,1] op_sel_hi:[1,0] neg_lo:[0,1]
	v_mov_b32_e32 v86, v66
	v_mov_b32_e32 v87, v67
	v_pk_add_f32 v[106:107], v[96:97], v[82:83]
	v_pk_add_f32 v[66:67], v[96:97], v[82:83] neg_lo:[0,1] neg_hi:[0,1]
	v_mov_b32_e32 v82, v66
	v_mov_b32_e32 v83, v67
	v_pk_add_f32 v[96:97], v[90:91], v[100:101]
	v_pk_add_f32 v[66:67], v[90:91], v[100:101] neg_lo:[0,1] neg_hi:[0,1]
	v_mov_b32_e32 v90, v66
	v_mov_b32_e32 v91, v67
	s_nop 0
	v_cvt_f32_i32_e32 v66, v114
	v_mul_f32_e32 v66, 0xb9800000, v66
	v_mul_f32_e32 v66, 0.5, v66
	v_sin_f32_e32 v101, v66
	v_cos_f32_e32 v100, v66
	v_ashrrev_i32_e32 v66, 4, v114
	v_add_lshl_u32 v66, v66, v114, 3
	v_add_u32_e32 v116, 0, v66
	v_add_u32_e32 v117, s33, v66
	v_mov_b64_e32 v[66:67], s[90:91]
	v_pk_mul_f32 v[114:115], v[68:69], v[66:67] op_sel:[1,1] op_sel_hi:[1,0] neg_lo:[1,0]
	v_pk_fma_f32 v[68:69], v[68:69], v[66:67], v[114:115] op_sel_hi:[0,1,1]
	ds_write_b64 v116, v[68:69]
	v_pk_mul_f32 v[114:115], v[94:95], v[66:67] op_sel:[1,1] op_sel_hi:[1,0] neg_lo:[1,0]
	v_pk_fma_f32 v[68:69], v[94:95], v[66:67], v[114:115] op_sel_hi:[0,1,1]
	ds_write_b64 v117, v[68:69]
	v_pk_mul_f32 v[68:69], v[66:67], v[100:101] op_sel:[1,1] op_sel_hi:[1,0] neg_lo:[1,0]
	v_pk_fma_f32 v[94:95], v[66:67], v[100:101], v[68:69] op_sel_hi:[0,1,1]
	v_pk_mul_f32 v[114:115], v[76:77], v[94:95] op_sel:[1,1] op_sel_hi:[1,0] neg_lo:[1,0]
	v_pk_fma_f32 v[68:69], v[76:77], v[94:95], v[114:115] op_sel_hi:[0,1,1]
	ds_write_b64 v116, v[68:69] offset:4352
	v_pk_mul_f32 v[76:77], v[88:89], v[94:95] op_sel:[1,1] op_sel_hi:[1,0] neg_lo:[1,0]
	v_pk_fma_f32 v[68:69], v[88:89], v[94:95], v[76:77] op_sel_hi:[0,1,1]
	ds_write_b64 v117, v[68:69] offset:4352
	v_pk_mul_f32 v[68:69], v[94:95], v[100:101] op_sel:[1,1] op_sel_hi:[1,0] neg_lo:[1,0]
	v_pk_fma_f32 v[76:77], v[94:95], v[100:101], v[68:69] op_sel_hi:[0,1,1]
	v_pk_mul_f32 v[94:95], v[70:71], v[76:77] op_sel:[1,1] op_sel_hi:[1,0] neg_lo:[1,0]
	v_pk_fma_f32 v[68:69], v[70:71], v[76:77], v[94:95] op_sel_hi:[0,1,1]
	ds_write_b64 v116, v[68:69] offset:8704
	v_pk_mul_f32 v[70:71], v[80:81], v[76:77] op_sel:[1,1] op_sel_hi:[1,0] neg_lo:[1,0]
	v_pk_fma_f32 v[68:69], v[80:81], v[76:77], v[70:71] op_sel_hi:[0,1,1]
	ds_write_b64 v117, v[68:69] offset:8704
	v_pk_mul_f32 v[68:69], v[76:77], v[100:101] op_sel:[1,1] op_sel_hi:[1,0] neg_lo:[1,0]
	v_pk_fma_f32 v[70:71], v[76:77], v[100:101], v[68:69] op_sel_hi:[0,1,1]
	v_pk_mul_f32 v[76:77], v[16:17], v[70:71] op_sel:[1,1] op_sel_hi:[1,0] neg_lo:[1,0]
	v_pk_fma_f32 v[68:69], v[16:17], v[70:71], v[76:77] op_sel_hi:[0,1,1]
	ds_write_b64 v116, v[68:69] offset:13056
	v_pk_mul_f32 v[76:77], v[106:107], v[70:71] op_sel:[1,1] op_sel_hi:[1,0] neg_lo:[1,0]
	v_pk_fma_f32 v[68:69], v[106:107], v[70:71], v[76:77] op_sel_hi:[0,1,1]
	ds_write_b64 v117, v[68:69] offset:13056
	v_pk_mul_f32 v[68:69], v[70:71], v[100:101] op_sel:[1,1] op_sel_hi:[1,0] neg_lo:[1,0]
	v_pk_fma_f32 v[70:71], v[70:71], v[100:101], v[68:69] op_sel_hi:[0,1,1]
	v_pk_mul_f32 v[68:69], v[78:79], v[70:71] op_sel:[1,1] op_sel_hi:[1,0] neg_lo:[1,0]
	v_pk_fma_f32 v[16:17], v[78:79], v[70:71], v[68:69] op_sel_hi:[0,1,1]
	ds_write_b64 v116, v[16:17] offset:17408
	v_pk_mul_f32 v[68:69], v[104:105], v[70:71] op_sel:[1,1] op_sel_hi:[1,0] neg_lo:[1,0]
	v_pk_fma_f32 v[16:17], v[104:105], v[70:71], v[68:69] op_sel_hi:[0,1,1]
	ds_write_b64 v117, v[16:17] offset:17408
	v_pk_mul_f32 v[16:17], v[70:71], v[100:101] op_sel:[1,1] op_sel_hi:[1,0] neg_lo:[1,0]
	v_pk_fma_f32 v[68:69], v[70:71], v[100:101], v[16:17] op_sel_hi:[0,1,1]
	v_pk_mul_f32 v[70:71], v[6:7], v[68:69] op_sel:[1,1] op_sel_hi:[1,0] neg_lo:[1,0]
	v_pk_fma_f32 v[16:17], v[6:7], v[68:69], v[70:71] op_sel_hi:[0,1,1]
	ds_write_b64 v116, v[16:17] offset:21760
	v_pk_mul_f32 v[70:71], v[108:109], v[68:69] op_sel:[1,1] op_sel_hi:[1,0] neg_lo:[1,0]
	v_pk_fma_f32 v[16:17], v[108:109], v[68:69], v[70:71] op_sel_hi:[0,1,1]
	ds_write_b64 v117, v[16:17] offset:21760
	v_pk_mul_f32 v[16:17], v[68:69], v[100:101] op_sel:[1,1] op_sel_hi:[1,0] neg_lo:[1,0]
	v_pk_fma_f32 v[68:69], v[68:69], v[100:101], v[16:17] op_sel_hi:[0,1,1]
	v_pk_mul_f32 v[70:71], v[18:19], v[68:69] op_sel:[1,1] op_sel_hi:[1,0] neg_lo:[1,0]
	v_pk_fma_f32 v[16:17], v[18:19], v[68:69], v[70:71] op_sel_hi:[0,1,1]
	ds_write_b64 v116, v[16:17] offset:26112
	v_pk_mul_f32 v[18:19], v[112:113], v[68:69] op_sel:[1,1] op_sel_hi:[1,0] neg_lo:[1,0]
	v_pk_fma_f32 v[16:17], v[112:113], v[68:69], v[18:19] op_sel_hi:[0,1,1]
	ds_write_b64 v117, v[16:17] offset:26112
	v_pk_mul_f32 v[16:17], v[68:69], v[100:101] op_sel:[1,1] op_sel_hi:[1,0] neg_lo:[1,0]
	v_pk_fma_f32 v[18:19], v[68:69], v[100:101], v[16:17] op_sel_hi:[0,1,1]
	v_pk_mul_f32 v[68:69], v[74:75], v[18:19] op_sel:[1,1] op_sel_hi:[1,0] neg_lo:[1,0]
	v_pk_fma_f32 v[16:17], v[74:75], v[18:19], v[68:69] op_sel_hi:[0,1,1]
	ds_write_b64 v116, v[16:17] offset:30464
	v_pk_mul_f32 v[68:69], v[96:97], v[18:19] op_sel:[1,1] op_sel_hi:[1,0] neg_lo:[1,0]
	v_pk_fma_f32 v[16:17], v[96:97], v[18:19], v[68:69] op_sel_hi:[0,1,1]
	ds_write_b64 v117, v[16:17] offset:30464
	v_pk_mul_f32 v[16:17], v[18:19], v[100:101] op_sel:[1,1] op_sel_hi:[1,0] neg_lo:[1,0]
; #define LAS __attribute__((address_space(3)))
; #define SINCOSPI(x, s, c) do { const float hx_ = 0.5f * (x); *(s) = __builtin_amdgcn_sinf(hx_); *(c) = __builtin_amdgcn_cosf(hx_); } while (0)
; DEV void fft_f1x2(LAS cf* buf0, LAS cf* buf1, const cf (&z0)[8], const cf (&z1)[8], int tid) {
;     ...
;     float sn, cs; SINCOSPI(-(float)tid * (2.0f / 8192.0f), &sn, &cs);
;     const cf w = cf{cs, sn}; cf wp = cf{1.f, 0.f};
;     LAS cf* p0 = buf0 + PADI(tid); LAS cf* p1 = buf1 + PADI(tid);
; #pragma unroll
;     for (int p = 0; p < 16; ++p) { p0[544 * p] = cmul(v[BR16[p]], wp); p1[544 * p] = cmul(u[BR16[p]], wp); wp = cmul(wp, w); }
	v_pk_fma_f32 v[18:19], v[18:19], v[100:101], v[16:17] op_sel_hi:[0,1,1]
	v_pk_mul_f32 v[16:17], v[84:85], v[18:19] op_sel:[1,1] op_sel_hi:[1,0] neg_lo:[1,0]
	v_pk_fma_f32 v[80:81], v[84:85], v[18:19], v[16:17] op_sel_hi:[0,1,1]
	ds_write_b64 v116, v[80:81] offset:34816
	v_pk_mul_f32 v[16:17], v[110:111], v[18:19] op_sel:[1,1] op_sel_hi:[1,0] neg_lo:[1,0]
	v_pk_fma_f32 v[80:81], v[110:111], v[18:19], v[16:17] op_sel_hi:[0,1,1]
	ds_write_b64 v117, v[80:81] offset:34816
	v_pk_mul_f32 v[80:81], v[18:19], v[100:101] op_sel:[1,1] op_sel_hi:[1,0] neg_lo:[1,0]
	v_pk_fma_f32 v[16:17], v[18:19], v[100:101], v[80:81] op_sel_hi:[0,1,1]
	v_pk_mul_f32 v[18:19], v[12:13], v[16:17] op_sel:[1,1] op_sel_hi:[1,0] neg_lo:[1,0]
	v_pk_fma_f32 v[80:81], v[12:13], v[16:17], v[18:19] op_sel_hi:[0,1,1]
	ds_write_b64 v116, v[80:81] offset:39168
	v_pk_mul_f32 v[12:13], v[98:99], v[16:17] op_sel:[1,1] op_sel_hi:[1,0] neg_lo:[1,0]
	v_pk_fma_f32 v[80:81], v[98:99], v[16:17], v[12:13] op_sel_hi:[0,1,1]
	ds_write_b64 v117, v[80:81] offset:39168
	v_pk_mul_f32 v[80:81], v[16:17], v[100:101] op_sel:[1,1] op_sel_hi:[1,0] neg_lo:[1,0]
	v_pk_fma_f32 v[12:13], v[16:17], v[100:101], v[80:81] op_sel_hi:[0,1,1]
	v_pk_mul_f32 v[16:17], v[72:73], v[12:13] op_sel:[1,1] op_sel_hi:[1,0] neg_lo:[1,0]
	v_pk_fma_f32 v[80:81], v[72:73], v[12:13], v[16:17] op_sel_hi:[0,1,1]
	ds_write_b64 v116, v[80:81] offset:43520
	v_pk_mul_f32 v[6:7], v[102:103], v[12:13] op_sel:[1,1] op_sel_hi:[1,0] neg_lo:[1,0]
	v_pk_fma_f32 v[80:81], v[102:103], v[12:13], v[6:7] op_sel_hi:[0,1,1]
	ds_write_b64 v117, v[80:81] offset:43520
	v_pk_mul_f32 v[80:81], v[12:13], v[100:101] op_sel:[1,1] op_sel_hi:[1,0] neg_lo:[1,0]
	v_pk_fma_f32 v[6:7], v[12:13], v[100:101], v[80:81] op_sel_hi:[0,1,1]
	v_pk_mul_f32 v[12:13], v[14:15], v[6:7] op_sel:[1,1] op_sel_hi:[1,0] neg_lo:[1,0]
	v_pk_fma_f32 v[80:81], v[14:15], v[6:7], v[12:13] op_sel_hi:[0,1,1]
	ds_write_b64 v116, v[80:81] offset:47872
	v_pk_mul_f32 v[12:13], v[82:83], v[6:7] op_sel:[1,1] op_sel_hi:[1,0] neg_lo:[1,0]
	v_pk_fma_f32 v[80:81], v[82:83], v[6:7], v[12:13] op_sel_hi:[0,1,1]
	ds_write_b64 v117, v[80:81] offset:47872
	v_pk_mul_f32 v[80:81], v[6:7], v[100:101] op_sel:[1,1] op_sel_hi:[1,0] neg_lo:[1,0]
	v_pk_fma_f32 v[6:7], v[6:7], v[100:101], v[80:81] op_sel_hi:[0,1,1]
	v_pk_mul_f32 v[80:81], v[0:1], v[6:7] op_sel:[1,1] op_sel_hi:[1,0] neg_lo:[1,0]
	v_pk_fma_f32 v[0:1], v[0:1], v[6:7], v[80:81] op_sel_hi:[0,1,1]
	ds_write_b64 v116, v[0:1] offset:52224
	v_pk_mul_f32 v[80:81], v[92:93], v[6:7] op_sel:[1,1] op_sel_hi:[1,0] neg_lo:[1,0]
	v_pk_fma_f32 v[0:1], v[92:93], v[6:7], v[80:81] op_sel_hi:[0,1,1]
	ds_write_b64 v117, v[0:1] offset:52224
	v_pk_mul_f32 v[0:1], v[6:7], v[100:101] op_sel:[1,1] op_sel_hi:[1,0] neg_lo:[1,0]
	v_pk_fma_f32 v[92:93], v[6:7], v[100:101], v[0:1] op_sel_hi:[0,1,1]
	v_pk_mul_f32 v[6:7], v[8:9], v[92:93] op_sel:[1,1] op_sel_hi:[1,0] neg_lo:[1,0]
	v_pk_fma_f32 v[0:1], v[8:9], v[92:93], v[6:7] op_sel_hi:[0,1,1]
	ds_write_b64 v116, v[0:1] offset:56576
	v_pk_mul_f32 v[6:7], v[86:87], v[92:93] op_sel:[1,1] op_sel_hi:[1,0] neg_lo:[1,0]
	v_pk_fma_f32 v[0:1], v[86:87], v[92:93], v[6:7] op_sel_hi:[0,1,1]
	ds_write_b64 v117, v[0:1] offset:56576
	v_pk_mul_f32 v[0:1], v[92:93], v[100:101] op_sel:[1,1] op_sel_hi:[1,0] neg_lo:[1,0]
	v_pk_fma_f32 v[92:93], v[92:93], v[100:101], v[0:1] op_sel_hi:[0,1,1]
	v_pk_mul_f32 v[6:7], v[2:3], v[92:93] op_sel:[1,1] op_sel_hi:[1,0] neg_lo:[1,0]
	v_pk_fma_f32 v[0:1], v[2:3], v[92:93], v[6:7] op_sel_hi:[0,1,1]
	ds_write_b64 v116, v[0:1] offset:60928
	v_pk_mul_f32 v[2:3], v[4:5], v[92:93] op_sel:[1,1] op_sel_hi:[1,0] neg_lo:[1,0]
	v_pk_fma_f32 v[0:1], v[4:5], v[92:93], v[2:3] op_sel_hi:[0,1,1]
	ds_write_b64 v117, v[0:1] offset:60928
	v_pk_mul_f32 v[0:1], v[92:93], v[100:101] op_sel:[1,1] op_sel_hi:[1,0] neg_lo:[1,0]
	v_pk_fma_f32 v[2:3], v[92:93], v[100:101], v[0:1] op_sel_hi:[0,1,1]
	v_pk_mul_f32 v[4:5], v[10:11], v[2:3] op_sel:[1,1] op_sel_hi:[1,0] neg_lo:[1,0]
	v_pk_fma_f32 v[0:1], v[10:11], v[2:3], v[4:5] op_sel_hi:[0,1,1]
	ds_write_b64 v116, v[0:1] offset:65280
	v_pk_mul_f32 v[4:5], v[90:91], v[2:3] op_sel:[1,1] op_sel_hi:[1,0] neg_lo:[1,0]
	v_pk_fma_f32 v[0:1], v[90:91], v[2:3], v[4:5] op_sel_hi:[0,1,1]
	ds_write_b64 v117, v[0:1] offset:65280
	v_mov_b32_e32 v0, v160
	s_waitcnt lgkmcnt(0)
	s_barrier
; #define LAS __attribute__((address_space(3)))
; #define OPAQUE_I(x) asm volatile("" : "+v"(x))
; template <int R, bool INV> DEV void dft_regs(cf (&v)[R]) {
; #pragma unroll
;     for (int s = R; s >= 2; s >>= 1) {
;         const int h = s >> 1;
; #pragma unroll
;         for (int b = 0; b < R; b += s) {
; #pragma unroll
;             for (int k = 0; k < h; ++k) {
;                 const cf a = v[b + k], c = v[b + k + h];
;                 v[b + k] = a + c;
;                 const cf d = a - c;
;                 const int m = k * (32 / s);
;                 const float wr = tw_cos(m), wi = INV ? tw_sin(m) : -tw_sin(m);
;                 v[b + k + h] = cf{d.x * wr - d.y * wi, d.x * wi + d.y * wr};
;             }
;         }
;     }
; }
; DEV void fft_f2(LAS cf* buf, int t8) {
;     OPAQUE_I(t8);
;     LAS cf* pb = buf + (t8 >> 4) * 544 + (t8 & 15);
;     cf v[32];
; #pragma unroll
;     for (int q = 0; q < 32; ++q) v[q] = pb[17 * q];
;     dft_regs<32, false>(v);
	s_nop 0
	v_lshrrev_b32_e32 v1, 4, v0
	v_and_b32_e32 v3, 15, v0
	v_mul_lo_u32 v1, v1, s15
	v_lshlrev_b32_e32 v0, 3, v3
	v_add3_u32 v2, v159, v1, v0
	ds_read2_b64 v[4:7], v2 offset1:17
	ds_read2_b64 v[8:11], v2 offset0:34 offset1:51
	ds_read2_b64 v[12:15], v2 offset0:68 offset1:85
	ds_read2_b64 v[16:19], v2 offset0:102 offset1:119
	ds_read2_b64 v[68:71], v2 offset0:136 offset1:153
	ds_read2_b64 v[72:75], v2 offset0:170 offset1:187
	ds_read2_b64 v[76:79], v2 offset0:204 offset1:221
	ds_read2_b64 v[80:83], v2 offset0:238 offset1:255
	v_add_u32_e32 v0, 0x800, v2
	ds_read2_b64 v[84:87], v0 offset0:16 offset1:33
	ds_read2_b64 v[88:91], v0 offset0:50 offset1:67
	ds_read2_b64 v[92:95], v0 offset0:84 offset1:101
	ds_read2_b64 v[96:99], v0 offset0:118 offset1:135
	ds_read2_b64 v[100:103], v0 offset0:152 offset1:169
	ds_read2_b64 v[104:107], v0 offset0:186 offset1:203
	ds_read2_b64 v[108:111], v0 offset0:220 offset1:237
	s_waitcnt lgkmcnt(6)
	v_pk_add_f32 v[116:117], v[4:5], v[84:85]
	v_pk_add_f32 v[4:5], v[4:5], v[84:85] neg_lo:[0,1] neg_hi:[0,1]
	v_add_u32_e32 v1, 0xc00, v2
	ds_read2_b64 v[112:115], v1 offset0:126 offset1:143
	v_cvt_f32_ubyte0_e32 v3, v3
	v_pk_add_f32 v[118:119], v[6:7], v[86:87]
	v_pk_add_f32 v[6:7], v[6:7], v[86:87] neg_lo:[0,1] neg_hi:[0,1]
	v_mul_f32_e32 v3, 0xbb800000, v3
	v_pk_mul_f32 v[84:85], v[6:7], s[82:83] op_sel_hi:[1,0]
	v_mul_f32_e32 v3, 0.5, v3
	v_pk_fma_f32 v[86:87], v[6:7], s[94:95], v[84:85] op_sel:[0,0,1] op_sel_hi:[1,0,0] neg_hi:[0,0,1]
	s_waitcnt lgkmcnt(6)
	v_pk_add_f32 v[6:7], v[8:9], v[88:89]
	v_pk_add_f32 v[8:9], v[8:9], v[88:89] neg_lo:[0,1] neg_hi:[0,1]
	v_pk_mul_f32 v[84:85], v[8:9], s[84:85] op_sel_hi:[1,0]
	v_pk_fma_f32 v[88:89], v[8:9], s[16:17], v[84:85] op_sel:[0,0,1] op_sel_hi:[1,0,0] neg_hi:[0,0,1]
	v_pk_add_f32 v[8:9], v[10:11], v[90:91]
	v_pk_add_f32 v[10:11], v[10:11], v[90:91] neg_lo:[0,1] neg_hi:[0,1]
	v_pk_mul_f32 v[84:85], v[10:11], s[4:5] op_sel_hi:[1,0]
	v_pk_fma_f32 v[90:91], v[10:11], s[86:87], v[84:85] op_sel:[0,0,1] op_sel_hi:[1,0,0] neg_hi:[0,0,1]
	s_waitcnt lgkmcnt(5)
	v_pk_add_f32 v[10:11], v[12:13], v[92:93]
	v_pk_add_f32 v[12:13], v[12:13], v[92:93] neg_lo:[0,1] neg_hi:[0,1]
	v_pk_mul_f32 v[84:85], v[12:13], s[18:19] op_sel_hi:[1,0]
	v_pk_fma_f32 v[92:93], v[12:13], s[18:19], v[84:85] op_sel:[0,0,1] op_sel_hi:[1,0,0] neg_hi:[0,0,1]
	v_pk_add_f32 v[12:13], v[14:15], v[94:95]
	v_pk_add_f32 v[14:15], v[14:15], v[94:95] neg_lo:[0,1] neg_hi:[0,1]
	v_pk_mul_f32 v[84:85], v[14:15], s[86:87] op_sel_hi:[1,0]
	v_pk_fma_f32 v[94:95], v[14:15], s[4:5], v[84:85] op_sel:[0,0,1] op_sel_hi:[1,0,0] neg_hi:[0,0,1]
	s_mov_b32 s5, s86
	s_waitcnt lgkmcnt(4)
	v_pk_add_f32 v[14:15], v[16:17], v[96:97]
	v_pk_add_f32 v[16:17], v[16:17], v[96:97] neg_lo:[0,1] neg_hi:[0,1]
	v_pk_mul_f32 v[84:85], v[16:17], s[16:17] op_sel_hi:[1,0]
	v_pk_fma_f32 v[96:97], v[16:17], s[84:85], v[84:85] op_sel:[0,0,1] op_sel_hi:[1,0,0] neg_hi:[0,0,1]
	v_pk_add_f32 v[16:17], v[18:19], v[98:99]
	v_pk_add_f32 v[18:19], v[18:19], v[98:99] neg_lo:[0,1] neg_hi:[0,1]
	v_pk_mul_f32 v[84:85], v[18:19], s[94:95] op_sel_hi:[1,0]
	v_pk_fma_f32 v[98:99], v[18:19], s[82:83], v[84:85] op_sel:[0,0,1] op_sel_hi:[1,0,0] neg_hi:[0,0,1]
	s_mov_b32 s83, s94
	s_waitcnt lgkmcnt(3)
	v_pk_add_f32 v[18:19], v[68:69], v[100:101]
	v_pk_add_f32 v[68:69], v[68:69], v[100:101] neg_lo:[0,1] neg_hi:[0,1]
	v_pk_add_f32 v[84:85], v[70:71], v[102:103]
	v_pk_add_f32 v[70:71], v[70:71], v[102:103] neg_lo:[0,1] neg_hi:[0,1]
	v_pk_mul_f32 v[100:101], v[70:71], s[82:83] op_sel_hi:[0,1]
	v_pk_fma_f32 v[70:71], v[70:71], s[94:95], v[100:101] op_sel:[1,0,0] neg_lo:[0,0,1] neg_hi:[0,0,1]
	s_waitcnt lgkmcnt(2)
	v_pk_add_f32 v[100:101], v[72:73], v[104:105]
	v_pk_add_f32 v[72:73], v[72:73], v[104:105] neg_lo:[0,1] neg_hi:[0,1]
	v_pk_mul_f32 v[102:103], v[72:73], s[84:85] op_sel_hi:[0,1]
	v_pk_fma_f32 v[72:73], v[72:73], s[30:31], v[102:103] op_sel:[1,0,0] neg_lo:[0,0,1] neg_hi:[0,0,1]
	v_pk_add_f32 v[102:103], v[74:75], v[106:107]
	v_pk_add_f32 v[74:75], v[74:75], v[106:107] neg_lo:[0,1] neg_hi:[0,1]
	v_pk_mul_f32 v[104:105], v[74:75], s[4:5] op_sel_hi:[0,1]
	v_pk_fma_f32 v[74:75], v[74:75], s[86:87], v[104:105] op_sel:[1,0,0] neg_lo:[0,0,1] neg_hi:[0,0,1]
	s_waitcnt lgkmcnt(1)
	v_pk_add_f32 v[104:105], v[76:77], v[108:109]
	v_pk_add_f32 v[76:77], v[76:77], v[108:109] neg_lo:[0,1] neg_hi:[0,1]
	v_mul_f32_e32 v106, 0x3f3504f3, v76
	v_pk_fma_f32 v[76:77], v[76:77], s[28:29], v[106:107] op_sel:[1,0,0] op_sel_hi:[1,1,0] neg_lo:[0,0,1] neg_hi:[0,0,1]
	v_pk_add_f32 v[106:107], v[78:79], v[110:111]
	v_pk_add_f32 v[78:79], v[78:79], v[110:111] neg_lo:[0,1] neg_hi:[0,1]
	v_pk_mul_f32 v[108:109], v[78:79], s[2:3] op_sel_hi:[0,1]
	v_pk_fma_f32 v[78:79], v[78:79], s[10:11], v[108:109] op_sel:[1,0,0] neg_lo:[0,0,1] neg_hi:[0,0,1]
	s_waitcnt lgkmcnt(0)
; template <int R, bool INV> DEV void dft_regs(cf (&v)[R]) {
; #pragma unroll
;     for (int s = R; s >= 2; s >>= 1) {
;         const int h = s >> 1;
; #pragma unroll
;         for (int b = 0; b < R; b += s) {
; #pragma unroll
;             for (int k = 0; k < h; ++k) {
;                 const cf a = v[b + k], c = v[b + k + h];
;                 v[b + k] = a + c;
;                 const cf d = a - c;
;                 const int m = k * (32 / s);
;                 const float wr = tw_cos(m), wi = INV ? tw_sin(m) : -tw_sin(m);
;                 v[b + k + h] = cf{d.x * wr - d.y * wi, d.x * wi + d.y * wr};
;             }
;         }
;     }
; }
	v_pk_add_f32 v[108:109], v[80:81], v[112:113]
	v_pk_add_f32 v[80:81], v[80:81], v[112:113] neg_lo:[0,1] neg_hi:[0,1]
	v_pk_mul_f32 v[110:111], v[80:81], s[24:25] op_sel_hi:[0,1]
	v_pk_fma_f32 v[80:81], v[80:81], s[34:35], v[110:111] op_sel:[1,0,0] neg_lo:[0,0,1] neg_hi:[0,0,1]
	v_pk_add_f32 v[110:111], v[82:83], v[114:115]
	v_pk_add_f32 v[82:83], v[82:83], v[114:115] neg_lo:[0,1] neg_hi:[0,1]
	v_pk_mul_f32 v[112:113], v[82:83], s[6:7] op_sel_hi:[0,1]
	v_pk_fma_f32 v[82:83], v[82:83], s[8:9], v[112:113] op_sel:[1,0,0] neg_lo:[0,0,1] neg_hi:[0,0,1]
	v_pk_add_f32 v[112:113], v[116:117], v[18:19]
	v_pk_add_f32 v[18:19], v[116:117], v[18:19] neg_lo:[0,1] neg_hi:[0,1]
	v_pk_add_f32 v[116:117], v[118:119], v[84:85]
	v_pk_add_f32 v[118:119], v[118:119], v[84:85] neg_lo:[0,1] neg_hi:[0,1]
	v_pk_mul_f32 v[84:85], v[118:119], s[84:85] op_sel_hi:[1,0]
	v_pk_fma_f32 v[114:115], v[118:119], s[16:17], v[84:85] op_sel:[0,0,1] op_sel_hi:[1,0,0] neg_hi:[0,0,1]
	v_pk_add_f32 v[118:119], v[6:7], v[100:101]
	v_pk_add_f32 v[6:7], v[6:7], v[100:101] neg_lo:[0,1] neg_hi:[0,1]
	v_pk_mul_f32 v[84:85], v[6:7], s[18:19] op_sel_hi:[1,0]
	v_pk_fma_f32 v[100:101], v[6:7], s[18:19], v[84:85] op_sel:[0,0,1] op_sel_hi:[1,0,0] neg_hi:[0,0,1]
	v_pk_add_f32 v[6:7], v[8:9], v[102:103]
	v_pk_add_f32 v[8:9], v[8:9], v[102:103] neg_lo:[0,1] neg_hi:[0,1]
	v_pk_mul_f32 v[84:85], v[8:9], s[16:17] op_sel_hi:[1,0]
	v_pk_fma_f32 v[102:103], v[8:9], s[84:85], v[84:85] op_sel:[0,0,1] op_sel_hi:[1,0,0] neg_hi:[0,0,1]
	v_pk_add_f32 v[8:9], v[10:11], v[104:105]
	v_pk_add_f32 v[10:11], v[10:11], v[104:105] neg_lo:[0,1] neg_hi:[0,1]
	v_pk_add_f32 v[84:85], v[12:13], v[106:107]
	v_pk_add_f32 v[12:13], v[12:13], v[106:107] neg_lo:[0,1] neg_hi:[0,1]
	v_pk_mul_f32 v[104:105], v[12:13], s[84:85] op_sel_hi:[0,1]
	v_pk_fma_f32 v[12:13], v[12:13], s[30:31], v[104:105] op_sel:[1,0,0] neg_lo:[0,0,1] neg_hi:[0,0,1]
	v_pk_add_f32 v[104:105], v[14:15], v[108:109]
	v_pk_add_f32 v[14:15], v[14:15], v[108:109] neg_lo:[0,1] neg_hi:[0,1]
	v_mul_f32_e32 v106, 0x3f3504f3, v14
	v_pk_fma_f32 v[14:15], v[14:15], s[28:29], v[106:107] op_sel:[1,0,0] op_sel_hi:[1,1,0] neg_lo:[0,0,1] neg_hi:[0,0,1]
	v_pk_add_f32 v[106:107], v[16:17], v[110:111]
	v_pk_add_f32 v[16:17], v[16:17], v[110:111] neg_lo:[0,1] neg_hi:[0,1]
	v_pk_mul_f32 v[108:109], v[16:17], s[24:25] op_sel_hi:[0,1]
	v_pk_fma_f32 v[16:17], v[16:17], s[34:35], v[108:109] op_sel:[1,0,0] neg_lo:[0,0,1] neg_hi:[0,0,1]
	v_pk_add_f32 v[108:109], v[4:5], v[68:69] op_sel:[0,1] op_sel_hi:[1,0] neg_hi:[0,1]
	v_pk_add_f32 v[68:69], v[4:5], v[68:69] op_sel:[0,1] op_sel_hi:[1,0] neg_lo:[0,1]
	v_pk_add_f32 v[4:5], v[86:87], v[70:71]
	v_pk_add_f32 v[70:71], v[86:87], v[70:71] neg_lo:[0,1] neg_hi:[0,1]
	v_pk_mul_f32 v[86:87], v[70:71], s[84:85] op_sel_hi:[1,0]
	v_pk_fma_f32 v[110:111], v[70:71], s[16:17], v[86:87] op_sel:[0,0,1] op_sel_hi:[1,0,0] neg_hi:[0,0,1]
	v_pk_add_f32 v[70:71], v[88:89], v[72:73]
	v_pk_add_f32 v[72:73], v[88:89], v[72:73] neg_lo:[0,1] neg_hi:[0,1]
	v_pk_mul_f32 v[86:87], v[72:73], s[18:19] op_sel_hi:[1,0]
	v_pk_fma_f32 v[88:89], v[72:73], s[18:19], v[86:87] op_sel:[0,0,1] op_sel_hi:[1,0,0] neg_hi:[0,0,1]
	v_pk_add_f32 v[72:73], v[90:91], v[74:75]
	v_pk_add_f32 v[74:75], v[90:91], v[74:75] neg_lo:[0,1] neg_hi:[0,1]
	v_pk_mul_f32 v[86:87], v[74:75], s[16:17] op_sel_hi:[1,0]
	v_pk_fma_f32 v[90:91], v[74:75], s[84:85], v[86:87] op_sel:[0,0,1] op_sel_hi:[1,0,0] neg_hi:[0,0,1]
	v_pk_add_f32 v[74:75], v[92:93], v[76:77]
	v_pk_add_f32 v[76:77], v[92:93], v[76:77] neg_lo:[0,1] neg_hi:[0,1]
	v_pk_add_f32 v[86:87], v[94:95], v[78:79]
	v_pk_add_f32 v[78:79], v[94:95], v[78:79] neg_lo:[0,1] neg_hi:[0,1]
	v_pk_mul_f32 v[92:93], v[78:79], s[84:85] op_sel_hi:[0,1]
	v_pk_fma_f32 v[78:79], v[78:79], s[30:31], v[92:93] op_sel:[1,0,0] neg_lo:[0,0,1] neg_hi:[0,0,1]
	v_pk_add_f32 v[92:93], v[96:97], v[80:81]
	v_pk_add_f32 v[80:81], v[96:97], v[80:81] neg_lo:[0,1] neg_hi:[0,1]
	v_mul_f32_e32 v94, 0x3f3504f3, v80
	v_pk_fma_f32 v[80:81], v[80:81], s[28:29], v[94:95] op_sel:[1,0,0] op_sel_hi:[1,1,0] neg_lo:[0,0,1] neg_hi:[0,0,1]
	v_pk_add_f32 v[94:95], v[98:99], v[82:83]
	v_pk_add_f32 v[82:83], v[98:99], v[82:83] neg_lo:[0,1] neg_hi:[0,1]
	v_pk_mul_f32 v[96:97], v[82:83], s[24:25] op_sel_hi:[0,1]
	v_pk_fma_f32 v[82:83], v[82:83], s[34:35], v[96:97] op_sel:[1,0,0] neg_lo:[0,0,1] neg_hi:[0,0,1]
	v_pk_add_f32 v[96:97], v[112:113], v[8:9]
	v_pk_add_f32 v[8:9], v[112:113], v[8:9] neg_lo:[0,1] neg_hi:[0,1]
	v_pk_add_f32 v[112:113], v[116:117], v[84:85]
	v_pk_add_f32 v[84:85], v[116:117], v[84:85] neg_lo:[0,1] neg_hi:[0,1]
	v_pk_mul_f32 v[116:117], v[84:85], s[18:19] op_sel_hi:[1,0]
	v_pk_fma_f32 v[98:99], v[84:85], s[18:19], v[116:117] op_sel:[0,0,1] op_sel_hi:[1,0,0] neg_hi:[0,0,1]
	v_pk_add_f32 v[84:85], v[118:119], v[104:105]
	v_pk_add_f32 v[118:119], v[118:119], v[104:105] neg_lo:[0,1] neg_hi:[0,1]
	v_pk_add_f32 v[116:117], v[6:7], v[106:107]
	v_pk_add_f32 v[6:7], v[6:7], v[106:107] neg_lo:[0,1] neg_hi:[0,1]
	v_mul_f32_e32 v104, 0x3f3504f3, v6
	v_pk_fma_f32 v[6:7], v[6:7], s[28:29], v[104:105] op_sel:[1,0,0] op_sel_hi:[1,1,0] neg_lo:[0,0,1] neg_hi:[0,0,1]
	v_pk_add_f32 v[104:105], v[18:19], v[10:11] op_sel:[0,1] op_sel_hi:[1,0] neg_hi:[0,1]
	v_pk_add_f32 v[10:11], v[18:19], v[10:11] op_sel:[0,1] op_sel_hi:[1,0] neg_lo:[0,1]
	v_pk_add_f32 v[18:19], v[114:115], v[12:13]
	v_pk_add_f32 v[12:13], v[114:115], v[12:13] neg_lo:[0,1] neg_hi:[0,1]
	v_pk_mul_f32 v[106:107], v[12:13], s[18:19] op_sel_hi:[1,0]
	v_pk_fma_f32 v[114:115], v[12:13], s[18:19], v[106:107] op_sel:[0,0,1] op_sel_hi:[1,0,0] neg_hi:[0,0,1]
	v_pk_add_f32 v[12:13], v[100:101], v[14:15]
; template <int R, bool INV> DEV void dft_regs(cf (&v)[R]) {
; #pragma unroll
;     for (int s = R; s >= 2; s >>= 1) {
;         const int h = s >> 1;
; #pragma unroll
;         for (int b = 0; b < R; b += s) {
; #pragma unroll
;             for (int k = 0; k < h; ++k) {
;                 const cf a = v[b + k], c = v[b + k + h];
;                 v[b + k] = a + c;
;                 const cf d = a - c;
;                 const int m = k * (32 / s);
;                 const float wr = tw_cos(m), wi = INV ? tw_sin(m) : -tw_sin(m);
;                 v[b + k + h] = cf{d.x * wr - d.y * wi, d.x * wi + d.y * wr};
;             }
;         }
;     }
; }
	v_pk_add_f32 v[14:15], v[100:101], v[14:15] neg_lo:[0,1] neg_hi:[0,1]
	v_pk_add_f32 v[100:101], v[102:103], v[16:17]
	v_pk_add_f32 v[16:17], v[102:103], v[16:17] neg_lo:[0,1] neg_hi:[0,1]
	v_mul_f32_e32 v102, 0x3f3504f3, v16
	v_pk_fma_f32 v[16:17], v[16:17], s[28:29], v[102:103] op_sel:[1,0,0] op_sel_hi:[1,1,0] neg_lo:[0,0,1] neg_hi:[0,0,1]
	v_pk_add_f32 v[102:103], v[108:109], v[74:75]
	v_pk_add_f32 v[74:75], v[108:109], v[74:75] neg_lo:[0,1] neg_hi:[0,1]
	v_pk_add_f32 v[108:109], v[4:5], v[86:87]
	v_pk_add_f32 v[86:87], v[4:5], v[86:87] neg_lo:[0,1] neg_hi:[0,1]
	v_pk_mul_f32 v[4:5], v[86:87], s[18:19] op_sel_hi:[1,0]
	v_pk_fma_f32 v[106:107], v[86:87], s[18:19], v[4:5] op_sel:[0,0,1] op_sel_hi:[1,0,0] neg_hi:[0,0,1]
	v_pk_add_f32 v[86:87], v[70:71], v[92:93]
	v_pk_add_f32 v[70:71], v[70:71], v[92:93] neg_lo:[0,1] neg_hi:[0,1]
	v_pk_add_f32 v[4:5], v[72:73], v[94:95]
	v_pk_add_f32 v[72:73], v[72:73], v[94:95] neg_lo:[0,1] neg_hi:[0,1]
	v_mul_f32_e32 v92, 0x3f3504f3, v72
	v_pk_fma_f32 v[72:73], v[72:73], s[28:29], v[92:93] op_sel:[1,0,0] op_sel_hi:[1,1,0] neg_lo:[0,0,1] neg_hi:[0,0,1]
	v_pk_add_f32 v[92:93], v[68:69], v[76:77] op_sel:[0,1] op_sel_hi:[1,0] neg_hi:[0,1]
	v_pk_add_f32 v[76:77], v[68:69], v[76:77] op_sel:[0,1] op_sel_hi:[1,0] neg_lo:[0,1]
	v_mov_b32_e32 v68, v76
	v_mov_b32_e32 v69, v77
	v_pk_add_f32 v[76:77], v[110:111], v[78:79]
	v_pk_add_f32 v[78:79], v[110:111], v[78:79] neg_lo:[0,1] neg_hi:[0,1]
	v_pk_mul_f32 v[94:95], v[78:79], s[18:19] op_sel_hi:[1,0]
	v_pk_fma_f32 v[110:111], v[78:79], s[18:19], v[94:95] op_sel:[0,0,1] op_sel_hi:[1,0,0] neg_hi:[0,0,1]
	v_pk_add_f32 v[78:79], v[88:89], v[80:81]
	v_pk_add_f32 v[80:81], v[88:89], v[80:81] neg_lo:[0,1] neg_hi:[0,1]
	v_pk_add_f32 v[88:89], v[90:91], v[82:83]
	v_pk_add_f32 v[82:83], v[90:91], v[82:83] neg_lo:[0,1] neg_hi:[0,1]
	v_mul_f32_e32 v90, 0x3f3504f3, v82
	v_pk_fma_f32 v[82:83], v[82:83], s[28:29], v[90:91] op_sel:[1,0,0] op_sel_hi:[1,1,0] neg_lo:[0,0,1] neg_hi:[0,0,1]
	v_pk_add_f32 v[90:91], v[96:97], v[84:85]
	v_pk_add_f32 v[84:85], v[96:97], v[84:85] neg_lo:[0,1] neg_hi:[0,1]
	v_pk_add_f32 v[96:97], v[112:113], v[116:117]
	v_pk_add_f32 v[116:117], v[112:113], v[116:117] neg_lo:[0,1] neg_hi:[0,1]
	v_pk_add_f32 v[112:113], v[8:9], v[118:119] op_sel:[0,1] op_sel_hi:[1,0] neg_hi:[0,1]
	v_pk_add_f32 v[118:119], v[8:9], v[118:119] op_sel:[0,1] op_sel_hi:[1,0] neg_lo:[0,1]
	v_pk_add_f32 v[8:9], v[98:99], v[6:7]
	v_pk_add_f32 v[6:7], v[98:99], v[6:7] neg_lo:[0,1] neg_hi:[0,1]
	v_pk_add_f32 v[94:95], v[104:105], v[12:13]
	v_pk_add_f32 v[12:13], v[104:105], v[12:13] neg_lo:[0,1] neg_hi:[0,1]
	v_pk_add_f32 v[98:99], v[10:11], v[14:15] op_sel:[0,1] op_sel_hi:[1,0] neg_lo:[0,1]
	v_pk_add_f32 v[104:105], v[18:19], v[100:101]
	v_pk_add_f32 v[100:101], v[18:19], v[100:101] neg_lo:[0,1] neg_hi:[0,1]
	v_pk_add_f32 v[18:19], v[10:11], v[14:15] op_sel:[0,1] op_sel_hi:[1,0] neg_hi:[0,1]
	v_pk_add_f32 v[10:11], v[114:115], v[16:17]
	v_pk_add_f32 v[16:17], v[114:115], v[16:17] neg_lo:[0,1] neg_hi:[0,1]
	v_pk_add_f32 v[14:15], v[102:103], v[86:87]
	v_pk_add_f32 v[86:87], v[102:103], v[86:87] neg_lo:[0,1] neg_hi:[0,1]
	v_pk_add_f32 v[114:115], v[108:109], v[4:5]
	v_pk_add_f32 v[4:5], v[108:109], v[4:5] neg_lo:[0,1] neg_hi:[0,1]
	v_pk_add_f32 v[108:109], v[74:75], v[70:71] op_sel:[0,1] op_sel_hi:[1,0] neg_hi:[0,1]
	v_pk_add_f32 v[70:71], v[74:75], v[70:71] op_sel:[0,1] op_sel_hi:[1,0] neg_lo:[0,1]
	v_pk_add_f32 v[74:75], v[106:107], v[72:73]
	v_pk_add_f32 v[72:73], v[106:107], v[72:73] neg_lo:[0,1] neg_hi:[0,1]
	v_pk_add_f32 v[102:103], v[92:93], v[78:79]
	v_pk_add_f32 v[78:79], v[92:93], v[78:79] neg_lo:[0,1] neg_hi:[0,1]
	v_pk_add_f32 v[106:107], v[76:77], v[88:89]
	v_pk_add_f32 v[88:89], v[76:77], v[88:89] neg_lo:[0,1] neg_hi:[0,1]
	v_pk_add_f32 v[76:77], v[68:69], v[80:81] op_sel:[0,1] op_sel_hi:[1,0] neg_hi:[0,1]
	v_pk_add_f32 v[80:81], v[68:69], v[80:81] op_sel:[0,1] op_sel_hi:[1,0] neg_lo:[0,1]
	v_pk_add_f32 v[68:69], v[110:111], v[82:83]
	v_pk_add_f32 v[82:83], v[110:111], v[82:83] neg_lo:[0,1] neg_hi:[0,1]
	v_pk_add_f32 v[92:93], v[90:91], v[96:97]
	v_pk_add_f32 v[96:97], v[90:91], v[96:97] neg_lo:[0,1] neg_hi:[0,1]
	v_pk_add_f32 v[110:111], v[84:85], v[116:117] op_sel:[0,1] op_sel_hi:[1,0] neg_hi:[0,1]
	v_pk_add_f32 v[116:117], v[84:85], v[116:117] op_sel:[0,1] op_sel_hi:[1,0] neg_lo:[0,1]
	v_pk_add_f32 v[84:85], v[112:113], v[8:9]
	v_pk_add_f32 v[112:113], v[112:113], v[8:9] neg_lo:[0,1] neg_hi:[0,1]
	v_pk_add_f32 v[8:9], v[118:119], v[6:7] op_sel:[0,1] op_sel_hi:[1,0] neg_lo:[0,1]
	v_pk_add_f32 v[90:91], v[118:119], v[6:7] op_sel:[0,1] op_sel_hi:[1,0] neg_hi:[0,1]
	v_pk_add_f32 v[118:119], v[94:95], v[104:105]
	v_pk_add_f32 v[6:7], v[94:95], v[104:105] neg_lo:[0,1] neg_hi:[0,1]
	v_pk_add_f32 v[104:105], v[12:13], v[100:101] op_sel:[0,1] op_sel_hi:[1,0] neg_lo:[0,1]
	v_pk_add_f32 v[94:95], v[12:13], v[100:101] op_sel:[0,1] op_sel_hi:[1,0] neg_hi:[0,1]
	v_pk_add_f32 v[12:13], v[18:19], v[10:11]
	v_pk_add_f32 v[100:101], v[18:19], v[10:11] neg_lo:[0,1] neg_hi:[0,1]
	v_pk_add_f32 v[18:19], v[98:99], v[16:17] op_sel:[0,1] op_sel_hi:[1,0] neg_lo:[0,1]
	v_pk_add_f32 v[10:11], v[98:99], v[16:17] op_sel:[0,1] op_sel_hi:[1,0] neg_hi:[0,1]
	v_pk_add_f32 v[98:99], v[14:15], v[114:115]
	v_pk_add_f32 v[16:17], v[14:15], v[114:115] neg_lo:[0,1] neg_hi:[0,1]
	v_pk_add_f32 v[14:15], v[86:87], v[4:5] op_sel:[0,1] op_sel_hi:[1,0] neg_hi:[0,1]
	v_pk_add_f32 v[4:5], v[86:87], v[4:5] op_sel:[0,1] op_sel_hi:[1,0] neg_lo:[0,1]
	v_pk_add_f32 v[86:87], v[108:109], v[74:75]
	v_pk_add_f32 v[108:109], v[108:109], v[74:75] neg_lo:[0,1] neg_hi:[0,1]
	v_pk_add_f32 v[114:115], v[70:71], v[72:73] op_sel:[0,1] op_sel_hi:[1,0] neg_lo:[0,1]
; #define SINCOSPI(x, s, c) do { const float hx_ = 0.5f * (x); *(s) = __builtin_amdgcn_sinf(hx_); *(c) = __builtin_amdgcn_cosf(hx_); } while (0)
; DEV void fft_f2(LAS cf* buf, int t8) {
;     ...
;     dft_regs<32, false>(v);
;     float sn, cs; SINCOSPI(-(float)(t8 & 15) * (2.0f / 512.0f), &sn, &cs);
;     const cf w = cf{cs, sn}; cf wp = cf{1.f, 0.f};
; #pragma unroll
;     for (int p = 0; p < 32; ++p) { pb[17 * p] = cmul(v[BR32[p]], wp); wp = cmul(wp, w); }
	v_pk_add_f32 v[74:75], v[70:71], v[72:73] op_sel:[0,1] op_sel_hi:[1,0] neg_hi:[0,1]
	v_pk_add_f32 v[70:71], v[102:103], v[106:107]
	v_pk_add_f32 v[72:73], v[102:103], v[106:107] neg_lo:[0,1] neg_hi:[0,1]
	v_pk_add_f32 v[106:107], v[78:79], v[88:89] op_sel:[0,1] op_sel_hi:[1,0] neg_lo:[0,1]
	v_pk_add_f32 v[102:103], v[78:79], v[88:89] op_sel:[0,1] op_sel_hi:[1,0] neg_hi:[0,1]
	v_pk_add_f32 v[78:79], v[76:77], v[68:69]
	v_pk_add_f32 v[88:89], v[76:77], v[68:69] neg_lo:[0,1] neg_hi:[0,1]
	v_pk_add_f32 v[76:77], v[80:81], v[82:83] op_sel:[0,1] op_sel_hi:[1,0] neg_lo:[0,1]
	v_pk_add_f32 v[68:69], v[80:81], v[82:83] op_sel:[0,1] op_sel_hi:[1,0] neg_hi:[0,1]
	v_mov_b32_e32 v80, v76
	v_mov_b32_e32 v81, v77
	v_pk_mul_f32 v[82:83], v[92:93], v[66:67] op_sel:[1,1] op_sel_hi:[1,0] neg_lo:[1,0]
	v_pk_fma_f32 v[92:93], v[92:93], v[66:67], v[82:83] op_sel_hi:[0,1,1]
	v_sin_f32_e32 v77, v3
	v_cos_f32_e32 v76, v3
	v_pk_mul_f32 v[82:83], v[66:67], v[76:77] op_sel:[1,1] op_sel_hi:[1,0] neg_lo:[1,0]
	v_pk_fma_f32 v[120:121], v[66:67], v[76:77], v[82:83] op_sel_hi:[0,1,1]
	v_pk_mul_f32 v[82:83], v[98:99], v[120:121] op_sel:[1,1] op_sel_hi:[1,0] neg_lo:[1,0]
	v_pk_fma_f32 v[98:99], v[98:99], v[120:121], v[82:83] op_sel_hi:[0,1,1]
	ds_write2_b64 v2, v[92:93], v[98:99] offset1:17
	v_pk_mul_f32 v[98:99], v[120:121], v[76:77] op_sel:[1,1] op_sel_hi:[1,0] neg_lo:[1,0]
	v_pk_fma_f32 v[82:83], v[120:121], v[76:77], v[98:99] op_sel_hi:[0,1,1]
	v_pk_mul_f32 v[98:99], v[118:119], v[82:83] op_sel:[1,1] op_sel_hi:[1,0] neg_lo:[1,0]
	v_pk_fma_f32 v[118:119], v[118:119], v[82:83], v[98:99] op_sel_hi:[0,1,1]
	v_pk_mul_f32 v[98:99], v[82:83], v[76:77] op_sel:[1,1] op_sel_hi:[1,0] neg_lo:[1,0]
	v_pk_fma_f32 v[82:83], v[82:83], v[76:77], v[98:99] op_sel_hi:[0,1,1]
	v_pk_mul_f32 v[92:93], v[70:71], v[82:83] op_sel:[1,1] op_sel_hi:[1,0] neg_lo:[1,0]
	v_pk_fma_f32 v[98:99], v[70:71], v[82:83], v[92:93] op_sel_hi:[0,1,1]
	ds_write2_b64 v2, v[118:119], v[98:99] offset0:34 offset1:51
	v_pk_mul_f32 v[118:119], v[82:83], v[76:77] op_sel:[1,1] op_sel_hi:[1,0] neg_lo:[1,0]
	v_pk_fma_f32 v[98:99], v[82:83], v[76:77], v[118:119] op_sel_hi:[0,1,1]
	v_pk_mul_f32 v[118:119], v[84:85], v[98:99] op_sel:[1,1] op_sel_hi:[1,0] neg_lo:[1,0]
	v_pk_fma_f32 v[84:85], v[84:85], v[98:99], v[118:119] op_sel_hi:[0,1,1]
	v_pk_mul_f32 v[118:119], v[98:99], v[76:77] op_sel:[1,1] op_sel_hi:[1,0] neg_lo:[1,0]
	v_pk_fma_f32 v[98:99], v[98:99], v[76:77], v[118:119] op_sel_hi:[0,1,1]
	v_pk_mul_f32 v[70:71], v[86:87], v[98:99] op_sel:[1,1] op_sel_hi:[1,0] neg_lo:[1,0]
	v_pk_fma_f32 v[118:119], v[86:87], v[98:99], v[70:71] op_sel_hi:[0,1,1]
	ds_write2_b64 v2, v[84:85], v[118:119] offset0:68 offset1:85
	v_pk_mul_f32 v[84:85], v[98:99], v[76:77] op_sel:[1,1] op_sel_hi:[1,0] neg_lo:[1,0]
	v_pk_fma_f32 v[118:119], v[98:99], v[76:77], v[84:85] op_sel_hi:[0,1,1]
	v_pk_mul_f32 v[98:99], v[12:13], v[118:119] op_sel:[1,1] op_sel_hi:[1,0] neg_lo:[1,0]
	v_pk_fma_f32 v[84:85], v[12:13], v[118:119], v[98:99] op_sel_hi:[0,1,1]
	v_pk_mul_f32 v[12:13], v[118:119], v[76:77] op_sel:[1,1] op_sel_hi:[1,0] neg_lo:[1,0]
	v_pk_fma_f32 v[118:119], v[118:119], v[76:77], v[12:13] op_sel_hi:[0,1,1]
	v_pk_mul_f32 v[98:99], v[78:79], v[118:119] op_sel:[1,1] op_sel_hi:[1,0] neg_lo:[1,0]
	v_pk_fma_f32 v[12:13], v[78:79], v[118:119], v[98:99] op_sel_hi:[0,1,1]
	ds_write2_b64 v2, v[84:85], v[12:13] offset0:102 offset1:119
	v_pk_mul_f32 v[84:85], v[118:119], v[76:77] op_sel:[1,1] op_sel_hi:[1,0] neg_lo:[1,0]
	v_pk_fma_f32 v[12:13], v[118:119], v[76:77], v[84:85] op_sel_hi:[0,1,1]
	v_pk_mul_f32 v[118:119], v[110:111], v[12:13] op_sel:[1,1] op_sel_hi:[1,0] neg_lo:[1,0]
	v_pk_fma_f32 v[84:85], v[110:111], v[12:13], v[118:119] op_sel_hi:[0,1,1]
	v_pk_mul_f32 v[110:111], v[12:13], v[76:77] op_sel:[1,1] op_sel_hi:[1,0] neg_lo:[1,0]
	v_pk_fma_f32 v[12:13], v[12:13], v[76:77], v[110:111] op_sel_hi:[0,1,1]
	v_pk_mul_f32 v[118:119], v[14:15], v[12:13] op_sel:[1,1] op_sel_hi:[1,0] neg_lo:[1,0]
	v_pk_fma_f32 v[110:111], v[14:15], v[12:13], v[118:119] op_sel_hi:[0,1,1]
	ds_write2_b64 v2, v[84:85], v[110:111] offset0:136 offset1:153
	v_pk_mul_f32 v[84:85], v[12:13], v[76:77] op_sel:[1,1] op_sel_hi:[1,0] neg_lo:[1,0]
	v_pk_fma_f32 v[110:111], v[12:13], v[76:77], v[84:85] op_sel_hi:[0,1,1]
	v_pk_mul_f32 v[84:85], v[94:95], v[110:111] op_sel:[1,1] op_sel_hi:[1,0] neg_lo:[1,0]
	v_pk_fma_f32 v[94:95], v[94:95], v[110:111], v[84:85] op_sel_hi:[0,1,1]
	v_pk_mul_f32 v[84:85], v[110:111], v[76:77] op_sel:[1,1] op_sel_hi:[1,0] neg_lo:[1,0]
	v_pk_fma_f32 v[110:111], v[110:111], v[76:77], v[84:85] op_sel_hi:[0,1,1]
	v_pk_mul_f32 v[12:13], v[102:103], v[110:111] op_sel:[1,1] op_sel_hi:[1,0] neg_lo:[1,0]
	v_pk_fma_f32 v[84:85], v[102:103], v[110:111], v[12:13] op_sel_hi:[0,1,1]
	ds_write2_b64 v2, v[94:95], v[84:85] offset0:170 offset1:187
	v_pk_mul_f32 v[94:95], v[110:111], v[76:77] op_sel:[1,1] op_sel_hi:[1,0] neg_lo:[1,0]
	v_pk_fma_f32 v[84:85], v[110:111], v[76:77], v[94:95] op_sel_hi:[0,1,1]
	v_pk_mul_f32 v[94:95], v[90:91], v[84:85] op_sel:[1,1] op_sel_hi:[1,0] neg_lo:[1,0]
	v_pk_fma_f32 v[90:91], v[90:91], v[84:85], v[94:95] op_sel_hi:[0,1,1]
	v_pk_mul_f32 v[94:95], v[84:85], v[76:77] op_sel:[1,1] op_sel_hi:[1,0] neg_lo:[1,0]
	v_pk_fma_f32 v[84:85], v[84:85], v[76:77], v[94:95] op_sel_hi:[0,1,1]
	v_pk_mul_f32 v[110:111], v[74:75], v[84:85] op_sel:[1,1] op_sel_hi:[1,0] neg_lo:[1,0]
	v_pk_fma_f32 v[94:95], v[74:75], v[84:85], v[110:111] op_sel_hi:[0,1,1]
	ds_write2_b64 v2, v[90:91], v[94:95] offset0:204 offset1:221
	v_pk_mul_f32 v[90:91], v[84:85], v[76:77] op_sel:[1,1] op_sel_hi:[1,0] neg_lo:[1,0]
	v_pk_fma_f32 v[94:95], v[84:85], v[76:77], v[90:91] op_sel_hi:[0,1,1]
; #define SYNC() __syncthreads()
; DEV void fft_f2(LAS cf* buf, int t8) {
;     ...
; #pragma unroll
;     for (int p = 0; p < 32; ++p) { pb[17 * p] = cmul(v[BR32[p]], wp); wp = cmul(wp, w); }
; DEV void hyena_conv_head(LAS cf* buf0, LAS cf* buf1, const unsigned* Kp, const cf (&z)[2][8], int tid, bool abl) {
;     ...
;     if (!nosync && !skip_all) SYNC();
	v_pk_mul_f32 v[84:85], v[10:11], v[94:95] op_sel:[1,1] op_sel_hi:[1,0] neg_lo:[1,0]
	v_pk_fma_f32 v[90:91], v[10:11], v[94:95], v[84:85] op_sel_hi:[0,1,1]
	v_pk_mul_f32 v[10:11], v[94:95], v[76:77] op_sel:[1,1] op_sel_hi:[1,0] neg_lo:[1,0]
	v_pk_fma_f32 v[94:95], v[94:95], v[76:77], v[10:11] op_sel_hi:[0,1,1]
	v_pk_mul_f32 v[110:111], v[68:69], v[94:95] op_sel:[1,1] op_sel_hi:[1,0] neg_lo:[1,0]
	v_pk_fma_f32 v[10:11], v[68:69], v[94:95], v[110:111] op_sel_hi:[0,1,1]
	ds_write2_b64 v2, v[90:91], v[10:11] offset0:238 offset1:255
	v_pk_mul_f32 v[2:3], v[94:95], v[76:77] op_sel:[1,1] op_sel_hi:[1,0] neg_lo:[1,0]
	v_pk_fma_f32 v[90:91], v[94:95], v[76:77], v[2:3] op_sel_hi:[0,1,1]
	v_pk_mul_f32 v[94:95], v[96:97], v[90:91] op_sel:[1,1] op_sel_hi:[1,0] neg_lo:[1,0]
	v_pk_fma_f32 v[2:3], v[96:97], v[90:91], v[94:95] op_sel_hi:[0,1,1]
	v_pk_mul_f32 v[94:95], v[90:91], v[76:77] op_sel:[1,1] op_sel_hi:[1,0] neg_lo:[1,0]
	v_pk_fma_f32 v[90:91], v[90:91], v[76:77], v[94:95] op_sel_hi:[0,1,1]
	v_pk_mul_f32 v[10:11], v[16:17], v[90:91] op_sel:[1,1] op_sel_hi:[1,0] neg_lo:[1,0]
	v_pk_fma_f32 v[94:95], v[16:17], v[90:91], v[10:11] op_sel_hi:[0,1,1]
	ds_write2_b64 v0, v[2:3], v[94:95] offset0:16 offset1:33
	v_pk_mul_f32 v[2:3], v[90:91], v[76:77] op_sel:[1,1] op_sel_hi:[1,0] neg_lo:[1,0]
	v_pk_fma_f32 v[90:91], v[90:91], v[76:77], v[2:3] op_sel_hi:[0,1,1]
	v_pk_mul_f32 v[94:95], v[6:7], v[90:91] op_sel:[1,1] op_sel_hi:[1,0] neg_lo:[1,0]
	v_pk_fma_f32 v[2:3], v[6:7], v[90:91], v[94:95] op_sel_hi:[0,1,1]
	v_pk_mul_f32 v[6:7], v[90:91], v[76:77] op_sel:[1,1] op_sel_hi:[1,0] neg_lo:[1,0]
	v_pk_fma_f32 v[90:91], v[90:91], v[76:77], v[6:7] op_sel_hi:[0,1,1]
	v_pk_mul_f32 v[10:11], v[72:73], v[90:91] op_sel:[1,1] op_sel_hi:[1,0] neg_lo:[1,0]
	v_pk_fma_f32 v[6:7], v[72:73], v[90:91], v[10:11] op_sel_hi:[0,1,1]
	ds_write2_b64 v0, v[2:3], v[6:7] offset0:50 offset1:67
	v_pk_mul_f32 v[2:3], v[90:91], v[76:77] op_sel:[1,1] op_sel_hi:[1,0] neg_lo:[1,0]
	v_pk_fma_f32 v[90:91], v[90:91], v[76:77], v[2:3] op_sel_hi:[0,1,1]
	v_pk_mul_f32 v[6:7], v[112:113], v[90:91] op_sel:[1,1] op_sel_hi:[1,0] neg_lo:[1,0]
	v_pk_fma_f32 v[2:3], v[112:113], v[90:91], v[6:7] op_sel_hi:[0,1,1]
	v_pk_mul_f32 v[6:7], v[90:91], v[76:77] op_sel:[1,1] op_sel_hi:[1,0] neg_lo:[1,0]
	v_pk_fma_f32 v[118:119], v[90:91], v[76:77], v[6:7] op_sel_hi:[0,1,1]
	v_pk_mul_f32 v[10:11], v[108:109], v[118:119] op_sel:[1,1] op_sel_hi:[1,0] neg_lo:[1,0]
	v_pk_fma_f32 v[6:7], v[108:109], v[118:119], v[10:11] op_sel_hi:[0,1,1]
	ds_write2_b64 v0, v[2:3], v[6:7] offset0:84 offset1:101
	v_pk_mul_f32 v[2:3], v[118:119], v[76:77] op_sel:[1,1] op_sel_hi:[1,0] neg_lo:[1,0]
	v_pk_fma_f32 v[118:119], v[118:119], v[76:77], v[2:3] op_sel_hi:[0,1,1]
	v_pk_mul_f32 v[6:7], v[100:101], v[118:119] op_sel:[1,1] op_sel_hi:[1,0] neg_lo:[1,0]
	v_pk_fma_f32 v[2:3], v[100:101], v[118:119], v[6:7] op_sel_hi:[0,1,1]
	v_pk_mul_f32 v[6:7], v[118:119], v[76:77] op_sel:[1,1] op_sel_hi:[1,0] neg_lo:[1,0]
	v_pk_fma_f32 v[118:119], v[118:119], v[76:77], v[6:7] op_sel_hi:[0,1,1]
	v_pk_mul_f32 v[10:11], v[88:89], v[118:119] op_sel:[1,1] op_sel_hi:[1,0] neg_lo:[1,0]
	v_pk_fma_f32 v[6:7], v[88:89], v[118:119], v[10:11] op_sel_hi:[0,1,1]
	ds_write2_b64 v0, v[2:3], v[6:7] offset0:118 offset1:135
	v_pk_mul_f32 v[2:3], v[118:119], v[76:77] op_sel:[1,1] op_sel_hi:[1,0] neg_lo:[1,0]
	v_pk_fma_f32 v[118:119], v[118:119], v[76:77], v[2:3] op_sel_hi:[0,1,1]
	v_pk_mul_f32 v[6:7], v[116:117], v[118:119] op_sel:[1,1] op_sel_hi:[1,0] neg_lo:[1,0]
	v_pk_fma_f32 v[2:3], v[116:117], v[118:119], v[6:7] op_sel_hi:[0,1,1]
	v_pk_mul_f32 v[6:7], v[118:119], v[76:77] op_sel:[1,1] op_sel_hi:[1,0] neg_lo:[1,0]
	v_pk_fma_f32 v[118:119], v[118:119], v[76:77], v[6:7] op_sel_hi:[0,1,1]
	v_pk_mul_f32 v[112:113], v[4:5], v[118:119] op_sel:[1,1] op_sel_hi:[1,0] neg_lo:[1,0]
	v_pk_fma_f32 v[6:7], v[4:5], v[118:119], v[112:113] op_sel_hi:[0,1,1]
	ds_write2_b64 v0, v[2:3], v[6:7] offset0:152 offset1:169
	v_pk_mul_f32 v[2:3], v[118:119], v[76:77] op_sel:[1,1] op_sel_hi:[1,0] neg_lo:[1,0]
	v_pk_fma_f32 v[118:119], v[118:119], v[76:77], v[2:3] op_sel_hi:[0,1,1]
	v_pk_mul_f32 v[6:7], v[104:105], v[118:119] op_sel:[1,1] op_sel_hi:[1,0] neg_lo:[1,0]
	v_pk_fma_f32 v[2:3], v[104:105], v[118:119], v[6:7] op_sel_hi:[0,1,1]
	v_pk_mul_f32 v[6:7], v[118:119], v[76:77] op_sel:[1,1] op_sel_hi:[1,0] neg_lo:[1,0]
	v_pk_fma_f32 v[118:119], v[118:119], v[76:77], v[6:7] op_sel_hi:[0,1,1]
	v_pk_mul_f32 v[112:113], v[106:107], v[118:119] op_sel:[1,1] op_sel_hi:[1,0] neg_lo:[1,0]
	v_pk_fma_f32 v[6:7], v[106:107], v[118:119], v[112:113] op_sel_hi:[0,1,1]
	ds_write2_b64 v0, v[2:3], v[6:7] offset0:186 offset1:203
	v_pk_mul_f32 v[2:3], v[118:119], v[76:77] op_sel:[1,1] op_sel_hi:[1,0] neg_lo:[1,0]
	v_pk_fma_f32 v[118:119], v[118:119], v[76:77], v[2:3] op_sel_hi:[0,1,1]
	v_pk_mul_f32 v[6:7], v[8:9], v[118:119] op_sel:[1,1] op_sel_hi:[1,0] neg_lo:[1,0]
	v_pk_fma_f32 v[2:3], v[8:9], v[118:119], v[6:7] op_sel_hi:[0,1,1]
	v_pk_mul_f32 v[6:7], v[118:119], v[76:77] op_sel:[1,1] op_sel_hi:[1,0] neg_lo:[1,0]
	v_pk_fma_f32 v[118:119], v[118:119], v[76:77], v[6:7] op_sel_hi:[0,1,1]
	v_pk_mul_f32 v[8:9], v[114:115], v[118:119] op_sel:[1,1] op_sel_hi:[1,0] neg_lo:[1,0]
	v_pk_fma_f32 v[6:7], v[114:115], v[118:119], v[8:9] op_sel_hi:[0,1,1]
	ds_write2_b64 v0, v[2:3], v[6:7] offset0:220 offset1:237
	v_pk_mul_f32 v[2:3], v[118:119], v[76:77] op_sel:[1,1] op_sel_hi:[1,0] neg_lo:[1,0]
	v_pk_fma_f32 v[118:119], v[118:119], v[76:77], v[2:3] op_sel_hi:[0,1,1]
	v_pk_mul_f32 v[6:7], v[18:19], v[118:119] op_sel:[1,1] op_sel_hi:[1,0] neg_lo:[1,0]
	v_pk_fma_f32 v[2:3], v[18:19], v[118:119], v[6:7] op_sel_hi:[0,1,1]
	v_pk_mul_f32 v[6:7], v[118:119], v[76:77] op_sel:[1,1] op_sel_hi:[1,0] neg_lo:[1,0]
	v_pk_fma_f32 v[118:119], v[118:119], v[76:77], v[6:7] op_sel_hi:[0,1,1]
	v_pk_mul_f32 v[6:7], v[80:81], v[118:119] op_sel:[1,1] op_sel_hi:[1,0] neg_lo:[1,0]
	v_pk_fma_f32 v[118:119], v[80:81], v[118:119], v[6:7] op_sel_hi:[0,1,1]
	ds_write2_b64 v1, v[2:3], v[118:119] offset0:126 offset1:143
	s_waitcnt lgkmcnt(0)
	s_barrier
; #define LAS __attribute__((address_space(3)))
; template <int R, bool INV> DEV void dft_regs(cf (&v)[R]) {
; #pragma unroll
;     for (int s = R; s >= 2; s >>= 1) {
;         const int h = s >> 1;
; #pragma unroll
;         for (int b = 0; b < R; b += s) {
; #pragma unroll
;             for (int k = 0; k < h; ++k) {
;                 const cf a = v[b + k], c = v[b + k + h];
;                 v[b + k] = a + c;
;                 const cf d = a - c;
;                 const int m = k * (32 / s);
;                 const float wr = tw_cos(m), wi = INV ? tw_sin(m) : -tw_sin(m);
;                 v[b + k + h] = cf{d.x * wr - d.y * wi, d.x * wi + d.y * wr};
;             }
;         }
;     }
; }
; DEV void fft_midx2(LAS cf* buf0, LAS cf* buf1, const unsigned* Kp, int blk) {
;     ...
;     LAS cf* p0 = buf0 + 17 * blk; LAS cf* p1 = buf1 + 17 * blk;
;     cf v[16], u[16];
; #pragma unroll
;     for (int q = 0; q < 16; ++q) { v[q] = p0[q]; u[q] = p1[q]; }
;     dft_regs<16, false>(v); dft_regs<16, false>(u);
	ds_read2_b64 v[68:71], v161 offset1:1
	ds_read2_b64 v[8:11], v162 offset1:1
	ds_read2_b64 v[72:75], v161 offset0:2 offset1:3
	ds_read2_b64 v[12:15], v162 offset0:2 offset1:3
	ds_read2_b64 v[76:79], v161 offset0:4 offset1:5
	ds_read2_b64 v[0:3], v162 offset0:4 offset1:5
	ds_read2_b64 v[80:83], v161 offset0:6 offset1:7
	ds_read2_b64 v[4:7], v162 offset0:6 offset1:7
	ds_read2_b64 v[84:87], v161 offset0:8 offset1:9
	ds_read2_b64 v[100:103], v162 offset0:8 offset1:9
	ds_read2_b64 v[88:91], v161 offset0:10 offset1:11
	ds_read2_b64 v[104:107], v162 offset0:10 offset1:11
	ds_read2_b64 v[92:95], v161 offset0:12 offset1:13
	ds_read2_b64 v[16:19], v162 offset0:12 offset1:13
	ds_read2_b64 v[96:99], v161 offset0:14 offset1:15
	ds_read2_b64 v[108:111], v162 offset0:14 offset1:15
	s_waitcnt lgkmcnt(7)
	v_pk_add_f32 v[112:113], v[68:69], v[84:85]
	v_pk_add_f32 v[68:69], v[68:69], v[84:85] neg_lo:[0,1] neg_hi:[0,1]
	v_pk_add_f32 v[114:115], v[70:71], v[86:87]
	v_pk_add_f32 v[70:71], v[70:71], v[86:87] neg_lo:[0,1] neg_hi:[0,1]
	v_pk_mul_f32 v[84:85], v[70:71], s[84:85] op_sel_hi:[1,0]
	v_pk_fma_f32 v[86:87], v[70:71], s[16:17], v[84:85] op_sel:[0,0,1] op_sel_hi:[1,0,0] neg_hi:[0,0,1]
	s_waitcnt lgkmcnt(5)
	v_pk_add_f32 v[70:71], v[72:73], v[88:89]
	v_pk_add_f32 v[72:73], v[72:73], v[88:89] neg_lo:[0,1] neg_hi:[0,1]
	v_pk_mul_f32 v[84:85], v[72:73], s[18:19] op_sel_hi:[1,0]
	v_pk_fma_f32 v[88:89], v[72:73], s[18:19], v[84:85] op_sel:[0,0,1] op_sel_hi:[1,0,0]
	v_pk_fma_f32 v[72:73], v[72:73], s[18:19], v[84:85] op_sel_hi:[1,0,0] neg_lo:[0,0,1] neg_hi:[0,0,1]
	v_pk_add_f32 v[84:85], v[74:75], v[90:91]
	v_pk_add_f32 v[74:75], v[74:75], v[90:91] neg_lo:[0,1] neg_hi:[0,1]
	v_mov_b32_e32 v89, v73
	v_pk_mul_f32 v[90:91], v[74:75], s[16:17] op_sel_hi:[1,0]
	v_pk_fma_f32 v[116:117], v[74:75], s[84:85], v[90:91] op_sel:[0,0,1] op_sel_hi:[1,0,0] neg_hi:[0,0,1]
	s_waitcnt lgkmcnt(3)
	v_pk_add_f32 v[74:75], v[76:77], v[92:93]
	v_pk_add_f32 v[76:77], v[76:77], v[92:93] neg_lo:[0,1] neg_hi:[0,1]
	v_pk_add_f32 v[90:91], v[78:79], v[94:95]
	v_pk_add_f32 v[78:79], v[78:79], v[94:95] neg_lo:[0,1] neg_hi:[0,1]
	s_waitcnt lgkmcnt(1)
	v_pk_add_f32 v[94:95], v[82:83], v[98:99]
	v_pk_mul_f32 v[92:93], v[78:79], s[84:85] op_sel_hi:[0,1]
	v_pk_add_f32 v[82:83], v[82:83], v[98:99] neg_lo:[0,1] neg_hi:[0,1]
	v_pk_fma_f32 v[78:79], v[78:79], s[30:31], v[92:93] op_sel:[1,0,0] neg_lo:[0,0,1] neg_hi:[0,0,1]
	v_pk_add_f32 v[92:93], v[80:81], v[96:97]
	v_pk_add_f32 v[80:81], v[80:81], v[96:97] neg_lo:[0,1] neg_hi:[0,1]
	v_pk_mul_f32 v[96:97], v[82:83], s[24:25] op_sel_hi:[0,1]
	v_pk_fma_f32 v[82:83], v[82:83], s[34:35], v[96:97] op_sel:[1,0,0] neg_lo:[0,0,1] neg_hi:[0,0,1]
	v_pk_add_f32 v[96:97], v[112:113], v[74:75]
	v_pk_add_f32 v[74:75], v[112:113], v[74:75] neg_lo:[0,1] neg_hi:[0,1]
	v_mul_f32_e32 v72, 0x3f3504f3, v80
	v_pk_fma_f32 v[80:81], v[80:81], s[28:29], v[72:73] op_sel:[1,0,0] op_sel_hi:[1,1,0] neg_lo:[0,0,1] neg_hi:[0,0,1]
	v_pk_add_f32 v[72:73], v[88:89], v[80:81]
	v_pk_add_f32 v[112:113], v[114:115], v[90:91]
	v_pk_add_f32 v[114:115], v[114:115], v[90:91] neg_lo:[0,1] neg_hi:[0,1]
	v_pk_mul_f32 v[90:91], v[114:115], s[18:19] op_sel_hi:[1,0]
	v_pk_fma_f32 v[98:99], v[114:115], s[18:19], v[90:91] op_sel:[0,0,1] op_sel_hi:[1,0,0]
	v_pk_fma_f32 v[114:115], v[114:115], s[18:19], v[90:91] op_sel_hi:[1,0,0] neg_lo:[0,0,1] neg_hi:[0,0,1]
	v_pk_add_f32 v[90:91], v[70:71], v[92:93]
	v_pk_add_f32 v[70:71], v[70:71], v[92:93] neg_lo:[0,1] neg_hi:[0,1]
	v_mov_b32_e32 v99, v115
	v_pk_add_f32 v[92:93], v[84:85], v[94:95]
	v_pk_add_f32 v[84:85], v[84:85], v[94:95] neg_lo:[0,1] neg_hi:[0,1]
	v_pk_add_f32 v[94:95], v[68:69], v[76:77] op_sel:[0,1] op_sel_hi:[1,0] neg_hi:[0,1]
	v_pk_add_f32 v[76:77], v[68:69], v[76:77] op_sel:[0,1] op_sel_hi:[1,0] neg_lo:[0,1]
	v_mul_f32_e32 v114, 0x3f3504f3, v84
	v_pk_fma_f32 v[84:85], v[84:85], s[28:29], v[114:115] op_sel:[1,0,0] op_sel_hi:[1,1,0] neg_lo:[0,0,1] neg_hi:[0,0,1]
	v_pk_add_f32 v[118:119], v[86:87], v[78:79]
	v_pk_add_f32 v[78:79], v[86:87], v[78:79] neg_lo:[0,1] neg_hi:[0,1]
	v_pk_mul_f32 v[86:87], v[78:79], s[18:19] op_sel_hi:[1,0]
	v_pk_fma_f32 v[68:69], v[78:79], s[18:19], v[86:87] op_sel:[0,0,1] op_sel_hi:[1,0,0] neg_hi:[0,0,1]
	v_pk_add_f32 v[78:79], v[88:89], v[80:81] neg_lo:[0,1] neg_hi:[0,1]
	v_pk_add_f32 v[88:89], v[96:97], v[90:91]
	v_pk_add_f32 v[90:91], v[96:97], v[90:91] neg_lo:[0,1] neg_hi:[0,1]
	v_pk_add_f32 v[96:97], v[112:113], v[92:93]
	v_pk_add_f32 v[92:93], v[112:113], v[92:93] neg_lo:[0,1] neg_hi:[0,1]
	v_pk_add_f32 v[80:81], v[116:117], v[82:83]
	v_pk_add_f32 v[82:83], v[116:117], v[82:83] neg_lo:[0,1] neg_hi:[0,1]
	v_pk_add_f32 v[112:113], v[74:75], v[70:71] op_sel:[0,1] op_sel_hi:[1,0] neg_lo:[0,1]
	v_pk_add_f32 v[116:117], v[74:75], v[70:71] op_sel:[0,1] op_sel_hi:[1,0] neg_hi:[0,1]
	v_mul_f32_e32 v114, 0x3f3504f3, v82
	v_pk_fma_f32 v[82:83], v[82:83], s[28:29], v[114:115] op_sel:[1,0,0] op_sel_hi:[1,1,0] neg_lo:[0,0,1] neg_hi:[0,0,1]
	v_pk_add_f32 v[70:71], v[98:99], v[84:85] neg_lo:[0,1] neg_hi:[0,1]
	v_pk_add_f32 v[114:115], v[98:99], v[84:85]
	v_pk_add_f32 v[74:75], v[94:95], v[72:73]
	v_pk_add_f32 v[98:99], v[94:95], v[72:73] neg_lo:[0,1] neg_hi:[0,1]
	v_pk_add_f32 v[122:123], v[76:77], v[78:79] op_sel:[0,1] op_sel_hi:[1,0] neg_hi:[0,1]
	v_pk_add_f32 v[124:125], v[68:69], v[82:83]
	v_pk_add_f32 v[72:73], v[118:119], v[80:81]
	v_pk_add_f32 v[120:121], v[118:119], v[80:81] neg_lo:[0,1] neg_hi:[0,1]
	v_pk_add_f32 v[86:87], v[88:89], v[96:97]
	v_pk_add_f32 v[94:95], v[74:75], v[72:73]
	v_pk_add_f32 v[80:81], v[76:77], v[78:79] op_sel:[0,1] op_sel_hi:[1,0] neg_lo:[0,1]
	v_pk_add_f32 v[72:73], v[74:75], v[72:73] neg_lo:[0,1] neg_hi:[0,1]
; template <int R, bool INV> DEV void dft_regs(cf (&v)[R]) {
; #pragma unroll
;     for (int s = R; s >= 2; s >>= 1) {
;         const int h = s >> 1;
; #pragma unroll
;         for (int b = 0; b < R; b += s) {
; #pragma unroll
;             for (int k = 0; k < h; ++k) {
;                 const cf a = v[b + k], c = v[b + k + h];
;                 v[b + k] = a + c;
;                 const cf d = a - c;
;                 const int m = k * (32 / s);
;                 const float wr = tw_cos(m), wi = INV ? tw_sin(m) : -tw_sin(m);
;                 v[b + k + h] = cf{d.x * wr - d.y * wi, d.x * wi + d.y * wr};
;             }
;         }
;     }
; }
; DEV void fft_midx2(LAS cf* buf0, LAS cf* buf1, const unsigned* Kp, int blk) {
;     ...
;     dft_regs<16, false>(v); dft_regs<16, false>(u);
	v_pk_add_f32 v[84:85], v[112:113], v[70:71] op_sel:[0,1] op_sel_hi:[1,0] neg_hi:[0,1]
	v_pk_add_f32 v[74:75], v[8:9], v[100:101]
	v_pk_add_f32 v[76:77], v[68:69], v[82:83] neg_lo:[0,1] neg_hi:[0,1]
	v_pk_add_f32 v[82:83], v[90:91], v[92:93] op_sel:[0,1] op_sel_hi:[1,0] neg_hi:[0,1]
	v_pk_add_f32 v[92:93], v[90:91], v[92:93] op_sel:[0,1] op_sel_hi:[1,0] neg_lo:[0,1]
	v_pk_add_f32 v[90:91], v[88:89], v[96:97] neg_lo:[0,1] neg_hi:[0,1]
	v_pk_add_f32 v[88:89], v[116:117], v[114:115]
	v_pk_add_f32 v[114:115], v[116:117], v[114:115] neg_lo:[0,1] neg_hi:[0,1]
	v_mov_b32_e32 v96, v90
	v_mov_b32_e32 v97, v91
	v_mov_b32_e32 v90, v92
	v_mov_b32_e32 v91, v93
	v_mov_b32_e32 v92, v114
	v_mov_b32_e32 v93, v115
	v_pk_add_f32 v[78:79], v[112:113], v[70:71] op_sel:[0,1] op_sel_hi:[1,0] neg_lo:[0,1]
	v_pk_add_f32 v[8:9], v[8:9], v[100:101] neg_lo:[0,1] neg_hi:[0,1]
	v_mov_b32_e32 v114, v78
	v_mov_b32_e32 v115, v79
	v_mov_b32_e32 v78, v72
	v_mov_b32_e32 v79, v73
	v_pk_add_f32 v[118:119], v[98:99], v[120:121] op_sel:[0,1] op_sel_hi:[1,0] neg_hi:[0,1]
	v_pk_add_f32 v[120:121], v[98:99], v[120:121] op_sel:[0,1] op_sel_hi:[1,0] neg_lo:[0,1]
	v_mov_b32_e32 v72, v120
	v_mov_b32_e32 v73, v121
	v_pk_add_f32 v[70:71], v[122:123], v[124:125] neg_lo:[0,1] neg_hi:[0,1]
	v_pk_add_f32 v[68:69], v[122:123], v[124:125]
	v_pk_add_f32 v[98:99], v[80:81], v[76:77] op_sel:[0,1] op_sel_hi:[1,0] neg_lo:[0,1]
	v_pk_add_f32 v[120:121], v[80:81], v[76:77] op_sel:[0,1] op_sel_hi:[1,0] neg_hi:[0,1]
	v_pk_add_f32 v[76:77], v[10:11], v[102:103]
	v_pk_add_f32 v[10:11], v[10:11], v[102:103] neg_lo:[0,1] neg_hi:[0,1]
	v_pk_mul_f32 v[100:101], v[10:11], s[84:85] op_sel_hi:[1,0]
	v_pk_fma_f32 v[102:103], v[10:11], s[16:17], v[100:101] op_sel:[0,0,1] op_sel_hi:[1,0,0] neg_hi:[0,0,1]
	v_pk_add_f32 v[10:11], v[12:13], v[104:105]
	v_pk_add_f32 v[12:13], v[12:13], v[104:105] neg_lo:[0,1] neg_hi:[0,1]
	v_pk_mul_f32 v[100:101], v[12:13], s[18:19] op_sel_hi:[1,0]
	v_pk_fma_f32 v[104:105], v[12:13], s[18:19], v[100:101] op_sel:[0,0,1] op_sel_hi:[1,0,0] neg_hi:[0,0,1]
	v_pk_add_f32 v[12:13], v[14:15], v[106:107]
	v_pk_add_f32 v[14:15], v[14:15], v[106:107] neg_lo:[0,1] neg_hi:[0,1]
	v_pk_mul_f32 v[100:101], v[14:15], s[16:17] op_sel_hi:[1,0]
	v_pk_fma_f32 v[106:107], v[14:15], s[84:85], v[100:101] op_sel:[0,0,1] op_sel_hi:[1,0,0] neg_hi:[0,0,1]
	v_pk_add_f32 v[14:15], v[0:1], v[16:17]
	v_pk_add_f32 v[0:1], v[0:1], v[16:17] neg_lo:[0,1] neg_hi:[0,1]
	v_pk_add_f32 v[16:17], v[2:3], v[18:19]
	v_pk_add_f32 v[2:3], v[2:3], v[18:19] neg_lo:[0,1] neg_hi:[0,1]
	v_pk_mul_f32 v[18:19], v[2:3], s[84:85] op_sel_hi:[0,1]
	v_pk_fma_f32 v[2:3], v[2:3], s[30:31], v[18:19] op_sel:[1,0,0] neg_lo:[0,0,1] neg_hi:[0,0,1]
	s_waitcnt lgkmcnt(0)
	v_pk_add_f32 v[18:19], v[4:5], v[108:109]
	v_pk_add_f32 v[4:5], v[4:5], v[108:109] neg_lo:[0,1] neg_hi:[0,1]
	v_mul_f32_e32 v100, 0x3f3504f3, v4
	v_pk_fma_f32 v[4:5], v[4:5], s[28:29], v[100:101] op_sel:[1,0,0] op_sel_hi:[1,1,0] neg_lo:[0,0,1] neg_hi:[0,0,1]
	v_pk_add_f32 v[100:101], v[6:7], v[110:111]
	v_pk_add_f32 v[6:7], v[6:7], v[110:111] neg_lo:[0,1] neg_hi:[0,1]
	v_pk_mul_f32 v[108:109], v[6:7], s[24:25] op_sel_hi:[0,1]
	v_pk_fma_f32 v[6:7], v[6:7], s[34:35], v[108:109] op_sel:[1,0,0] neg_lo:[0,0,1] neg_hi:[0,0,1]
	v_pk_add_f32 v[108:109], v[74:75], v[14:15]
	v_pk_add_f32 v[14:15], v[74:75], v[14:15] neg_lo:[0,1] neg_hi:[0,1]
	v_pk_add_f32 v[74:75], v[76:77], v[16:17]
	v_pk_add_f32 v[16:17], v[76:77], v[16:17] neg_lo:[0,1] neg_hi:[0,1]
	v_pk_mul_f32 v[76:77], v[16:17], s[18:19] op_sel_hi:[1,0]
	v_pk_fma_f32 v[110:111], v[16:17], s[18:19], v[76:77] op_sel:[0,0,1] op_sel_hi:[1,0,0] neg_hi:[0,0,1]
	v_pk_add_f32 v[76:77], v[10:11], v[18:19] neg_lo:[0,1] neg_hi:[0,1]
	v_pk_add_f32 v[16:17], v[10:11], v[18:19]
	v_pk_add_f32 v[10:11], v[12:13], v[100:101]
	v_pk_add_f32 v[12:13], v[12:13], v[100:101] neg_lo:[0,1] neg_hi:[0,1]
	v_mul_f32_e32 v18, 0x3f3504f3, v12
	v_pk_fma_f32 v[12:13], v[12:13], s[28:29], v[18:19] op_sel:[1,0,0] op_sel_hi:[1,1,0] neg_lo:[0,0,1] neg_hi:[0,0,1]
	v_pk_add_f32 v[18:19], v[8:9], v[0:1] op_sel:[0,1] op_sel_hi:[1,0] neg_hi:[0,1]
	v_pk_add_f32 v[0:1], v[8:9], v[0:1] op_sel:[0,1] op_sel_hi:[1,0] neg_lo:[0,1]
	v_pk_add_f32 v[8:9], v[102:103], v[2:3]
	v_pk_add_f32 v[2:3], v[102:103], v[2:3] neg_lo:[0,1] neg_hi:[0,1]
	v_pk_mul_f32 v[100:101], v[2:3], s[18:19] op_sel_hi:[1,0]
	v_pk_fma_f32 v[102:103], v[2:3], s[18:19], v[100:101] op_sel:[0,0,1] op_sel_hi:[1,0,0] neg_hi:[0,0,1]
	v_pk_add_f32 v[2:3], v[104:105], v[4:5]
	v_pk_add_f32 v[4:5], v[104:105], v[4:5] neg_lo:[0,1] neg_hi:[0,1]
	v_pk_add_f32 v[100:101], v[106:107], v[6:7]
	v_pk_add_f32 v[6:7], v[106:107], v[6:7] neg_lo:[0,1] neg_hi:[0,1]
	v_mul_f32_e32 v104, 0x3f3504f3, v6
	v_pk_fma_f32 v[6:7], v[6:7], s[28:29], v[104:105] op_sel:[1,0,0] op_sel_hi:[1,1,0] neg_lo:[0,0,1] neg_hi:[0,0,1]
	v_pk_add_f32 v[104:105], v[108:109], v[16:17]
	v_pk_add_f32 v[16:17], v[108:109], v[16:17] neg_lo:[0,1] neg_hi:[0,1]
	v_pk_add_f32 v[166:167], v[102:103], v[6:7]
	v_pk_add_f32 v[6:7], v[102:103], v[6:7] neg_lo:[0,1] neg_hi:[0,1]
	v_pk_add_f32 v[108:109], v[74:75], v[10:11]
	v_pk_add_f32 v[10:11], v[74:75], v[10:11] neg_lo:[0,1] neg_hi:[0,1]
	v_pk_add_f32 v[74:75], v[10:11], 0 op_sel:[1,0] op_sel_hi:[0,0] neg_hi:[1,0]
	v_pk_add_f32 v[122:123], v[104:105], v[108:109]
	v_pk_add_f32 v[10:11], v[14:15], v[76:77] op_sel:[0,1] op_sel_hi:[1,0] neg_hi:[0,1]
	v_pk_add_f32 v[76:77], v[14:15], v[76:77] op_sel:[0,1] op_sel_hi:[1,0] neg_lo:[0,1]
	v_pk_add_f32 v[108:109], v[104:105], v[108:109] neg_lo:[0,1] neg_hi:[0,1]
	v_pk_add_f32 v[116:117], v[110:111], v[12:13]
	v_pk_add_f32 v[12:13], v[110:111], v[12:13] neg_lo:[0,1] neg_hi:[0,1]
; DEV cf kunpack(unsigned w) { return cf{U2F(w << 16), U2F(w & 0xffff0000u)}; }
; DEV void fft_midx2(LAS cf* buf0, LAS cf* buf1, const unsigned* Kp, int blk) {
;     ...
;     dft_regs<16, false>(v); dft_regs<16, false>(u);
;     cf w[16], x[16];
;     u32x4 kw[4];
; #pragma unroll
;     for (int j = 0; j < 4; ++j) kw[j] = *(const u32x4*)(Kp + base + 4 * j);
; #pragma unroll
;     for (int p = 0; p < 16; ++p) { const cf k = kunpack(kw[p >> 2][p & 3]); w[p] = cmul(v[BR16[p]], k); x[p] = cmul(u[BR16[p]], k); }
	v_pk_add_f32 v[110:111], v[18:19], v[2:3]
	v_pk_add_f32 v[2:3], v[18:19], v[2:3] neg_lo:[0,1] neg_hi:[0,1]
	v_pk_add_f32 v[106:107], v[16:17], v[74:75] neg_lo:[0,1] neg_hi:[0,1]
	v_pk_add_f32 v[124:125], v[8:9], v[100:101]
	v_pk_add_f32 v[100:101], v[8:9], v[100:101] neg_lo:[0,1] neg_hi:[0,1]
	v_pk_add_f32 v[8:9], v[0:1], v[4:5] op_sel:[0,1] op_sel_hi:[1,0] neg_lo:[0,1]
	v_pk_add_f32 v[164:165], v[0:1], v[4:5] op_sel:[0,1] op_sel_hi:[1,0] neg_hi:[0,1]
	v_pk_add_f32 v[18:19], v[10:11], v[116:117] neg_lo:[0,1] neg_hi:[0,1]
	v_pk_add_f32 v[126:127], v[110:111], v[124:125]
	v_pk_add_f32 v[14:15], v[76:77], v[12:13] op_sel:[0,1] op_sel_hi:[1,0] neg_hi:[0,1]
	v_mov_b32_e32 v104, v18
	v_mov_b32_e32 v105, v19
	v_pk_add_f32 v[4:5], v[16:17], v[74:75]
	v_pk_add_f32 v[0:1], v[76:77], v[12:13] op_sel:[0,1] op_sel_hi:[1,0] neg_lo:[0,1]
	v_pk_add_f32 v[76:77], v[8:9], v[6:7] op_sel:[0,1] op_sel_hi:[1,0] neg_hi:[0,1]
	v_pk_add_f32 v[112:113], v[10:11], v[116:117]
	v_pk_add_f32 v[80:81], v[2:3], v[100:101] op_sel:[0,1] op_sel_hi:[1,0] neg_hi:[0,1]
	v_pk_add_f32 v[16:17], v[110:111], v[124:125] neg_lo:[0,1] neg_hi:[0,1]
	s_mov_b32 s28, s95
	s_mov_b32 s29, s94
	v_pk_add_f32 v[110:111], v[2:3], v[100:101] op_sel:[0,1] op_sel_hi:[1,0] neg_lo:[0,1]
	v_pk_add_f32 v[124:125], v[164:165], v[166:167]
	v_pk_add_f32 v[102:103], v[164:165], v[166:167] neg_lo:[0,1] neg_hi:[0,1]
	v_mov_b32_e32 v166, v98
	v_mov_b32_e32 v167, v99
	v_pk_add_f32 v[18:19], v[8:9], v[6:7] op_sel:[0,1] op_sel_hi:[1,0] neg_lo:[0,1]
	s_nop 0
	s_waitcnt vmcnt(0)
	v_lshlrev_b32_e32 v98, 16, v182
	v_and_b32_e32 v99, 0xffff0000, v182
	v_lshlrev_b32_e32 v12, 16, v183
	v_and_b32_e32 v13, 0xffff0000, v183
	v_pk_mul_f32 v[168:169], v[86:87], v[98:99] op_sel:[1,1] op_sel_hi:[1,0] neg_lo:[1,0]
	v_pk_fma_f32 v[164:165], v[86:87], v[98:99], v[168:169] op_sel_hi:[0,1,1]
	v_pk_mul_f32 v[168:169], v[122:123], v[98:99] op_sel:[1,1] op_sel_hi:[1,0] neg_lo:[1,0]
	v_pk_fma_f32 v[86:87], v[122:123], v[98:99], v[168:169] op_sel_hi:[0,1,1]
	v_pk_mul_f32 v[98:99], v[94:95], v[12:13] op_sel:[1,1] op_sel_hi:[1,0] neg_lo:[1,0]
	v_pk_fma_f32 v[94:95], v[94:95], v[12:13], v[98:99] op_sel_hi:[0,1,1]
	v_pk_mul_f32 v[98:99], v[126:127], v[12:13] op_sel:[1,1] op_sel_hi:[1,0] neg_lo:[1,0]
	v_pk_fma_f32 v[12:13], v[126:127], v[12:13], v[98:99] op_sel_hi:[0,1,1]
	v_lshlrev_b32_e32 v98, 16, v184
	v_and_b32_e32 v99, 0xffff0000, v184
	v_lshlrev_b32_e32 v74, 16, v185
	v_and_b32_e32 v75, 0xffff0000, v185
	v_pk_mul_f32 v[126:127], v[88:89], v[98:99] op_sel:[1,1] op_sel_hi:[1,0] neg_lo:[1,0]
	v_pk_fma_f32 v[122:123], v[88:89], v[98:99], v[126:127] op_sel_hi:[0,1,1]
	v_pk_mul_f32 v[126:127], v[112:113], v[98:99] op_sel:[1,1] op_sel_hi:[1,0] neg_lo:[1,0]
	v_pk_fma_f32 v[88:89], v[112:113], v[98:99], v[126:127] op_sel_hi:[0,1,1]
	v_pk_mul_f32 v[98:99], v[68:69], v[74:75] op_sel:[1,1] op_sel_hi:[1,0] neg_lo:[1,0]
	v_pk_fma_f32 v[10:11], v[68:69], v[74:75], v[98:99] op_sel_hi:[0,1,1]
	v_pk_mul_f32 v[98:99], v[124:125], v[74:75] op_sel:[1,1] op_sel_hi:[1,0] neg_lo:[1,0]
	v_pk_fma_f32 v[74:75], v[124:125], v[74:75], v[98:99] op_sel_hi:[0,1,1]
	v_lshlrev_b32_e32 v98, 16, v178
	v_and_b32_e32 v99, 0xffff0000, v178
	v_lshlrev_b32_e32 v68, 16, v179
	v_and_b32_e32 v69, 0xffff0000, v179
	v_pk_mul_f32 v[124:125], v[82:83], v[98:99] op_sel:[1,1] op_sel_hi:[1,0] neg_lo:[1,0]
	v_pk_fma_f32 v[112:113], v[82:83], v[98:99], v[124:125] op_sel_hi:[0,1,1]
	v_pk_mul_f32 v[124:125], v[4:5], v[98:99] op_sel:[1,1] op_sel_hi:[1,0] neg_lo:[1,0]
	v_pk_fma_f32 v[82:83], v[4:5], v[98:99], v[124:125] op_sel_hi:[0,1,1]
	v_pk_mul_f32 v[98:99], v[118:119], v[68:69] op_sel:[1,1] op_sel_hi:[1,0] neg_lo:[1,0]
	v_pk_fma_f32 v[118:119], v[118:119], v[68:69], v[98:99] op_sel_hi:[0,1,1]
	v_pk_mul_f32 v[98:99], v[80:81], v[68:69] op_sel:[1,1] op_sel_hi:[1,0] neg_lo:[1,0]
	v_pk_fma_f32 v[100:101], v[80:81], v[68:69], v[98:99] op_sel_hi:[0,1,1]
	v_lshlrev_b32_e32 v98, 16, v180
	v_and_b32_e32 v99, 0xffff0000, v180
	v_lshlrev_b32_e32 v116, 16, v181
	v_and_b32_e32 v117, 0xffff0000, v181
	v_pk_mul_f32 v[80:81], v[84:85], v[98:99] op_sel:[1,1] op_sel_hi:[1,0] neg_lo:[1,0]
	v_pk_fma_f32 v[68:69], v[84:85], v[98:99], v[80:81] op_sel_hi:[0,1,1]
	v_pk_mul_f32 v[80:81], v[14:15], v[98:99] op_sel:[1,1] op_sel_hi:[1,0] neg_lo:[1,0]
	v_pk_fma_f32 v[84:85], v[14:15], v[98:99], v[80:81] op_sel_hi:[0,1,1]
	v_pk_mul_f32 v[98:99], v[120:121], v[116:117] op_sel:[1,1] op_sel_hi:[1,0] neg_lo:[1,0]
	v_pk_fma_f32 v[80:81], v[120:121], v[116:117], v[98:99] op_sel_hi:[0,1,1]
	v_pk_mul_f32 v[98:99], v[76:77], v[116:117] op_sel:[1,1] op_sel_hi:[1,0] neg_lo:[1,0]
	v_pk_fma_f32 v[116:117], v[76:77], v[116:117], v[98:99] op_sel_hi:[0,1,1]
	v_lshlrev_b32_e32 v98, 16, v174
	v_and_b32_e32 v99, 0xffff0000, v174
	v_pk_mul_f32 v[14:15], v[96:97], v[98:99] op_sel:[1,1] op_sel_hi:[1,0] neg_lo:[1,0]
	v_pk_fma_f32 v[96:97], v[96:97], v[98:99], v[14:15] op_sel_hi:[0,1,1]
	v_lshlrev_b32_e32 v4, 16, v175
	v_pk_mul_f32 v[14:15], v[108:109], v[98:99] op_sel:[1,1] op_sel_hi:[1,0] neg_lo:[1,0]
	v_pk_fma_f32 v[98:99], v[108:109], v[98:99], v[14:15] op_sel_hi:[0,1,1]
	v_and_b32_e32 v5, 0xffff0000, v175
	v_pk_mul_f32 v[108:109], v[78:79], v[4:5] op_sel:[1,1] op_sel_hi:[1,0] neg_lo:[1,0]
	v_pk_fma_f32 v[78:79], v[78:79], v[4:5], v[108:109] op_sel_hi:[0,1,1]
	v_pk_mul_f32 v[14:15], v[16:17], v[4:5] op_sel:[1,1] op_sel_hi:[1,0] neg_lo:[1,0]
	v_pk_fma_f32 v[108:109], v[16:17], v[4:5], v[14:15] op_sel_hi:[0,1,1]
	v_lshlrev_b32_e32 v4, 16, v176
	v_and_b32_e32 v5, 0xffff0000, v176
	v_pk_mul_f32 v[8:9], v[92:93], v[4:5] op_sel:[1,1] op_sel_hi:[1,0] neg_lo:[1,0]
	v_pk_fma_f32 v[14:15], v[92:93], v[4:5], v[8:9] op_sel_hi:[0,1,1]
; DEV cf kunpack(unsigned w) { return cf{U2F(w << 16), U2F(w & 0xffff0000u)}; }
; template <int R, bool INV> DEV void dft_regs(cf (&v)[R]) {
; #pragma unroll
;     for (int s = R; s >= 2; s >>= 1) {
;         const int h = s >> 1;
; #pragma unroll
;         for (int b = 0; b < R; b += s) {
; #pragma unroll
;             for (int k = 0; k < h; ++k) {
;                 const cf a = v[b + k], c = v[b + k + h];
;                 v[b + k] = a + c;
;                 const cf d = a - c;
;                 const int m = k * (32 / s);
;                 const float wr = tw_cos(m), wi = INV ? tw_sin(m) : -tw_sin(m);
;                 v[b + k + h] = cf{d.x * wr - d.y * wi, d.x * wi + d.y * wr};
;             }
;         }
;     }
; }
; DEV void fft_midx2(LAS cf* buf0, LAS cf* buf1, const unsigned* Kp, int blk) {
;     ...
;     for (int p = 0; p < 16; ++p) { const cf k = kunpack(kw[p >> 2][p & 3]); w[p] = cmul(v[BR16[p]], k); x[p] = cmul(u[BR16[p]], k); }
;     dft_regs<16, true>(w); dft_regs<16, true>(x);
	v_pk_mul_f32 v[8:9], v[104:105], v[4:5] op_sel:[1,1] op_sel_hi:[1,0] neg_lo:[1,0]
	v_pk_fma_f32 v[104:105], v[104:105], v[4:5], v[8:9] op_sel_hi:[0,1,1]
	v_lshlrev_b32_e32 v4, 16, v177
	v_and_b32_e32 v5, 0xffff0000, v177
	v_pk_mul_f32 v[8:9], v[70:71], v[4:5] op_sel:[1,1] op_sel_hi:[1,0] neg_lo:[1,0]
	v_pk_fma_f32 v[6:7], v[70:71], v[4:5], v[8:9] op_sel_hi:[0,1,1]
	v_pk_mul_f32 v[70:71], v[102:103], v[4:5] op_sel:[1,1] op_sel_hi:[1,0] neg_lo:[1,0]
	v_pk_fma_f32 v[8:9], v[102:103], v[4:5], v[70:71] op_sel_hi:[0,1,1]
	v_lshlrev_b32_e32 v4, 16, v170
	v_and_b32_e32 v5, 0xffff0000, v170
	v_lshlrev_b32_e32 v16, 16, v171
	v_and_b32_e32 v17, 0xffff0000, v171
	v_pk_mul_f32 v[70:71], v[90:91], v[4:5] op_sel:[1,1] op_sel_hi:[1,0] neg_lo:[1,0]
	v_pk_fma_f32 v[120:121], v[90:91], v[4:5], v[70:71] op_sel_hi:[0,1,1]
	v_pk_mul_f32 v[70:71], v[106:107], v[4:5] op_sel:[1,1] op_sel_hi:[1,0] neg_lo:[1,0]
	v_pk_fma_f32 v[102:103], v[106:107], v[4:5], v[70:71] op_sel_hi:[0,1,1]
	v_pk_mul_f32 v[106:107], v[72:73], v[16:17] op_sel:[1,1] op_sel_hi:[1,0] neg_lo:[1,0]
	v_pk_fma_f32 v[4:5], v[72:73], v[16:17], v[106:107] op_sel_hi:[0,1,1]
	v_pk_mul_f32 v[106:107], v[110:111], v[16:17] op_sel:[1,1] op_sel_hi:[1,0] neg_lo:[1,0]
	v_pk_fma_f32 v[110:111], v[110:111], v[16:17], v[106:107] op_sel_hi:[0,1,1]
	v_lshlrev_b32_e32 v16, 16, v172
	v_and_b32_e32 v17, 0xffff0000, v172
	v_pk_mul_f32 v[72:73], v[114:115], v[16:17] op_sel:[1,1] op_sel_hi:[1,0] neg_lo:[1,0]
	v_pk_fma_f32 v[106:107], v[114:115], v[16:17], v[72:73] op_sel_hi:[0,1,1]
	v_pk_mul_f32 v[114:115], v[0:1], v[16:17] op_sel:[1,1] op_sel_hi:[1,0] neg_lo:[1,0]
	v_pk_fma_f32 v[92:93], v[0:1], v[16:17], v[114:115] op_sel_hi:[0,1,1]
	v_lshlrev_b32_e32 v16, 16, v173
	v_and_b32_e32 v17, 0xffff0000, v173
	v_pk_mul_f32 v[0:1], v[166:167], v[16:17] op_sel:[1,1] op_sel_hi:[1,0] neg_lo:[1,0]
	v_pk_fma_f32 v[2:3], v[166:167], v[16:17], v[0:1] op_sel_hi:[0,1,1]
	v_pk_mul_f32 v[0:1], v[18:19], v[16:17] op_sel:[1,1] op_sel_hi:[1,0] neg_lo:[1,0]
	v_pk_fma_f32 v[18:19], v[18:19], v[16:17], v[0:1] op_sel_hi:[0,1,1]
	v_pk_add_f32 v[0:1], v[164:165], v[96:97]
	v_pk_add_f32 v[16:17], v[164:165], v[96:97] neg_lo:[0,1] neg_hi:[0,1]
	v_pk_add_f32 v[114:115], v[94:95], v[78:79] neg_lo:[0,1] neg_hi:[0,1]
	v_pk_mul_f32 v[96:97], v[114:115], s[84:85] op_sel_hi:[1,0]
	v_pk_add_f32 v[72:73], v[94:95], v[78:79]
	v_pk_fma_f32 v[70:71], v[114:115], s[16:17], v[96:97] op_sel:[0,0,1] op_sel_hi:[1,0,0] neg_lo:[0,0,1]
	v_pk_add_f32 v[114:115], v[122:123], v[14:15]
	v_pk_add_f32 v[14:15], v[122:123], v[14:15] neg_lo:[0,1] neg_hi:[0,1]
	v_pk_mul_f32 v[96:97], v[14:15], s[18:19] op_sel_hi:[1,0]
	v_pk_fma_f32 v[78:79], v[14:15], s[18:19], v[96:97] op_sel:[0,0,1] op_sel_hi:[1,0,0] neg_lo:[0,0,1]
	v_pk_add_f32 v[14:15], v[10:11], v[6:7]
	v_pk_add_f32 v[6:7], v[10:11], v[6:7] neg_lo:[0,1] neg_hi:[0,1]
	v_pk_mul_f32 v[96:97], v[6:7], s[16:17] op_sel_hi:[1,0]
	v_pk_fma_f32 v[94:95], v[6:7], s[84:85], v[96:97] op_sel:[0,0,1] op_sel_hi:[1,0,0] neg_lo:[0,0,1]
	v_pk_add_f32 v[6:7], v[112:113], v[120:121]
	v_pk_add_f32 v[120:121], v[112:113], v[120:121] neg_lo:[0,1] neg_hi:[0,1]
	v_pk_add_f32 v[112:113], v[118:119], v[4:5]
	v_pk_add_f32 v[4:5], v[118:119], v[4:5] neg_lo:[0,1] neg_hi:[0,1]
	v_pk_mul_f32 v[90:91], v[4:5], s[24:25] op_sel:[1,0]
	v_pk_fma_f32 v[4:5], v[4:5], s[0:1], v[90:91] op_sel_hi:[0,1,1] neg_lo:[0,0,1] neg_hi:[0,0,1]
	v_pk_add_f32 v[90:91], v[68:69], v[106:107]
	v_pk_add_f32 v[106:107], v[68:69], v[106:107] neg_lo:[0,1] neg_hi:[0,1]
	v_mul_f32_e32 v10, 0x3f3504f3, v107
	v_pk_fma_f32 v[106:107], v[106:107], s[96:97], v[10:11] op_sel_hi:[0,1,0] neg_lo:[0,0,1] neg_hi:[0,0,1]
	v_pk_add_f32 v[76:77], v[80:81], v[2:3]
	v_pk_add_f32 v[2:3], v[80:81], v[2:3] neg_lo:[0,1] neg_hi:[0,1]
	v_pk_mul_f32 v[80:81], v[2:3], s[84:85] op_sel:[1,0]
	v_pk_fma_f32 v[2:3], v[2:3], s[88:89], v[80:81] op_sel_hi:[0,1,1] neg_lo:[0,0,1] neg_hi:[0,0,1]
	v_pk_add_f32 v[80:81], v[0:1], v[6:7]
	v_pk_add_f32 v[0:1], v[0:1], v[6:7] neg_lo:[0,1] neg_hi:[0,1]
	v_pk_add_f32 v[6:7], v[72:73], v[112:113] neg_lo:[0,1] neg_hi:[0,1]
	v_pk_add_f32 v[68:69], v[72:73], v[112:113]
	v_pk_mul_f32 v[72:73], v[6:7], s[18:19] op_sel_hi:[1,0]
	v_pk_fma_f32 v[112:113], v[6:7], s[18:19], v[72:73] op_sel:[0,0,1] op_sel_hi:[1,0,0] neg_lo:[0,0,1]
	v_pk_add_f32 v[72:73], v[114:115], v[90:91] neg_lo:[0,1] neg_hi:[0,1]
	v_pk_add_f32 v[6:7], v[114:115], v[90:91]
	v_pk_add_f32 v[114:115], v[14:15], v[76:77]
	v_pk_add_f32 v[14:15], v[14:15], v[76:77] neg_lo:[0,1] neg_hi:[0,1]
	v_mul_f32_e32 v90, 0x3f3504f3, v15
	v_pk_fma_f32 v[14:15], v[14:15], s[96:97], v[90:91] op_sel_hi:[0,1,0] neg_lo:[0,0,1] neg_hi:[0,0,1]
	v_pk_add_f32 v[90:91], v[16:17], v[120:121] op_sel:[0,1] op_sel_hi:[1,0] neg_lo:[0,1]
	v_pk_add_f32 v[16:17], v[16:17], v[120:121] op_sel:[0,1] op_sel_hi:[1,0] neg_hi:[0,1]
	v_pk_add_f32 v[76:77], v[70:71], v[4:5]
	v_pk_add_f32 v[4:5], v[70:71], v[4:5] neg_lo:[0,1] neg_hi:[0,1]
	v_pk_mul_f32 v[96:97], v[4:5], s[18:19] op_sel_hi:[1,0]
	v_pk_fma_f32 v[70:71], v[4:5], s[18:19], v[96:97] op_sel:[0,0,1] op_sel_hi:[1,0,0] neg_lo:[0,0,1]
	v_pk_add_f32 v[4:5], v[78:79], v[106:107]
	v_pk_add_f32 v[106:107], v[78:79], v[106:107] neg_lo:[0,1] neg_hi:[0,1]
	v_pk_add_f32 v[10:11], v[90:91], v[4:5]
	v_pk_add_f32 v[96:97], v[106:107], 0 op_sel:[1,0] op_sel_hi:[0,0] neg_lo:[1,0]
	v_pk_add_f32 v[4:5], v[90:91], v[4:5] neg_lo:[0,1] neg_hi:[0,1]
	v_pk_add_f32 v[106:107], v[94:95], v[2:3]
	v_pk_add_f32 v[2:3], v[94:95], v[2:3] neg_lo:[0,1] neg_hi:[0,1]
	v_pk_add_f32 v[118:119], v[76:77], v[106:107]
	v_mul_f32_e32 v78, 0x3f3504f3, v3
	v_pk_fma_f32 v[2:3], v[2:3], s[96:97], v[78:79] op_sel_hi:[0,1,0] neg_lo:[0,0,1] neg_hi:[0,0,1]
; template <int R, bool INV> DEV void dft_regs(cf (&v)[R]) {
; #pragma unroll
;     for (int s = R; s >= 2; s >>= 1) {
;         const int h = s >> 1;
; #pragma unroll
;         for (int b = 0; b < R; b += s) {
; #pragma unroll
;             for (int k = 0; k < h; ++k) {
;                 const cf a = v[b + k], c = v[b + k + h];
;                 v[b + k] = a + c;
;                 const cf d = a - c;
;                 const int m = k * (32 / s);
;                 const float wr = tw_cos(m), wi = INV ? tw_sin(m) : -tw_sin(m);
;                 v[b + k + h] = cf{d.x * wr - d.y * wi, d.x * wi + d.y * wr};
;             }
;         }
;     }
; }
	v_pk_add_f32 v[78:79], v[80:81], v[6:7]
	v_pk_add_f32 v[6:7], v[80:81], v[6:7] neg_lo:[0,1] neg_hi:[0,1]
	v_pk_add_f32 v[122:123], v[70:71], v[2:3]
	v_pk_add_f32 v[2:3], v[70:71], v[2:3] neg_lo:[0,1] neg_hi:[0,1]
	v_pk_add_f32 v[80:81], v[2:3], 0 op_sel:[1,0] op_sel_hi:[0,0] neg_lo:[1,0]
	v_pk_add_f32 v[94:95], v[68:69], v[114:115]
	v_pk_add_f32 v[68:69], v[68:69], v[114:115] neg_lo:[0,1] neg_hi:[0,1]
	v_pk_add_f32 v[120:121], v[16:17], v[96:97]
	v_pk_add_f32 v[114:115], v[0:1], v[72:73] op_sel:[0,1] op_sel_hi:[1,0] neg_lo:[0,1]
	v_pk_add_f32 v[72:73], v[0:1], v[72:73] op_sel:[0,1] op_sel_hi:[1,0] neg_hi:[0,1]
	v_pk_add_f32 v[2:3], v[78:79], v[94:95] neg_lo:[0,1] neg_hi:[0,1]
	v_pk_add_f32 v[70:71], v[112:113], v[14:15]
	v_pk_add_f32 v[0:1], v[112:113], v[14:15] neg_lo:[0,1] neg_hi:[0,1]
	v_pk_add_f32 v[124:125], v[78:79], v[94:95]
	v_pk_add_f32 v[14:15], v[0:1], 0 op_sel:[1,0] op_sel_hi:[0,0] neg_lo:[1,0]
	v_pk_add_f32 v[78:79], v[6:7], v[68:69] op_sel:[0,1] op_sel_hi:[1,0] neg_lo:[0,1]
	v_pk_add_f32 v[90:91], v[76:77], v[106:107] neg_lo:[0,1] neg_hi:[0,1]
	v_pk_add_f32 v[76:77], v[16:17], v[96:97] neg_lo:[0,1] neg_hi:[0,1]
	v_pk_add_f32 v[126:127], v[4:5], v[90:91] op_sel:[0,1] op_sel_hi:[1,0] neg_lo:[0,1]
	v_pk_add_f32 v[16:17], v[4:5], v[90:91] op_sel:[0,1] op_sel_hi:[1,0] neg_hi:[0,1]
	v_pk_add_f32 v[90:91], v[120:121], v[122:123]
	v_pk_add_f32 v[164:165], v[76:77], v[80:81]
	v_mov_b32_e32 v106, v2
	v_mov_b32_e32 v107, v3
	v_mov_b32_e32 v0, v2
	v_mov_b32_e32 v1, v3
	v_pk_add_f32 v[4:5], v[6:7], v[68:69] op_sel:[0,1] op_sel_hi:[1,0] neg_hi:[0,1]
	v_pk_add_f32 v[94:95], v[114:115], v[70:71]
	v_pk_add_f32 v[68:69], v[114:115], v[70:71] neg_lo:[0,1] neg_hi:[0,1]
	v_mov_b32_e32 v2, v4
	v_mov_b32_e32 v3, v5
	v_pk_add_f32 v[112:113], v[72:73], v[14:15]
	v_mov_b32_e32 v70, v68
	v_mov_b32_e32 v71, v69
	v_pk_add_f32 v[6:7], v[72:73], v[14:15] neg_lo:[0,1] neg_hi:[0,1]
	v_pk_add_f32 v[72:73], v[10:11], v[118:119]
	v_pk_add_f32 v[80:81], v[76:77], v[80:81] neg_lo:[0,1] neg_hi:[0,1]
	v_mov_b32_e32 v114, v6
	v_mov_b32_e32 v115, v7
	v_pk_add_f32 v[14:15], v[10:11], v[118:119] neg_lo:[0,1] neg_hi:[0,1]
	v_mov_b32_e32 v10, v14
	v_mov_b32_e32 v11, v15
	v_mov_b32_e32 v118, v14
	v_mov_b32_e32 v119, v15
	v_mov_b32_e32 v107, v1
	v_mov_b32_e32 v96, v16
	v_mov_b32_e32 v97, v17
	v_pk_add_f32 v[14:15], v[120:121], v[122:123] neg_lo:[0,1] neg_hi:[0,1]
	v_mov_b32_e32 v11, v119
	v_mov_b32_e32 v69, v71
	v_mov_b32_e32 v122, v14
	v_mov_b32_e32 v123, v15
	v_mov_b32_e32 v120, v14
	v_mov_b32_e32 v121, v15
	v_pk_add_f32 v[76:77], v[86:87], v[98:99]
	v_pk_add_f32 v[86:87], v[86:87], v[98:99] neg_lo:[0,1] neg_hi:[0,1]
	v_mov_b32_e32 v123, v121
	v_mov_b32_e32 v166, v86
	v_mov_b32_e32 v167, v87
	v_pk_add_f32 v[86:87], v[12:13], v[108:109]
	v_pk_add_f32 v[12:13], v[12:13], v[108:109] neg_lo:[0,1] neg_hi:[0,1]
	v_mov_b32_e32 v17, v97
	v_pk_mul_f32 v[98:99], v[12:13], s[84:85] op_sel_hi:[1,0]
	v_pk_fma_f32 v[108:109], v[12:13], s[16:17], v[98:99] op_sel:[0,0,1] op_sel_hi:[1,0,0] neg_lo:[0,0,1]
	v_pk_add_f32 v[12:13], v[88:89], v[104:105]
	v_pk_add_f32 v[88:89], v[88:89], v[104:105] neg_lo:[0,1] neg_hi:[0,1]
	v_pk_mul_f32 v[98:99], v[88:89], s[18:19] op_sel_hi:[1,0]
	v_pk_fma_f32 v[104:105], v[88:89], s[18:19], v[98:99] op_sel:[0,0,1] op_sel_hi:[1,0,0] neg_lo:[0,0,1]
	v_pk_add_f32 v[88:89], v[74:75], v[8:9]
	v_pk_add_f32 v[74:75], v[74:75], v[8:9] neg_lo:[0,1] neg_hi:[0,1]
	v_pk_mul_f32 v[98:99], v[74:75], s[16:17] op_sel_hi:[1,0]
	v_pk_fma_f32 v[8:9], v[74:75], s[84:85], v[98:99] op_sel:[0,0,1] op_sel_hi:[1,0,0] neg_lo:[0,0,1]
	v_pk_add_f32 v[74:75], v[82:83], v[102:103]
	v_pk_add_f32 v[82:83], v[82:83], v[102:103] neg_lo:[0,1] neg_hi:[0,1]
	v_pk_add_f32 v[102:103], v[116:117], v[18:19]
	v_pk_add_f32 v[116:117], v[116:117], v[18:19] neg_lo:[0,1] neg_hi:[0,1]
	v_pk_mul_f32 v[18:19], v[116:117], s[84:85] op_sel:[1,0]
	v_pk_add_f32 v[98:99], v[100:101], v[110:111]
	v_pk_add_f32 v[100:101], v[100:101], v[110:111] neg_lo:[0,1] neg_hi:[0,1]
	v_pk_fma_f32 v[116:117], v[116:117], s[88:89], v[18:19] op_sel_hi:[0,1,1] neg_lo:[0,0,1] neg_hi:[0,0,1]
	v_pk_add_f32 v[18:19], v[76:77], v[74:75]
	v_pk_add_f32 v[74:75], v[76:77], v[74:75] neg_lo:[0,1] neg_hi:[0,1]
	v_pk_mul_f32 v[110:111], v[100:101], s[24:25] op_sel:[1,0]
	v_pk_fma_f32 v[100:101], v[100:101], s[0:1], v[110:111] op_sel_hi:[0,1,1] neg_lo:[0,0,1] neg_hi:[0,0,1]
	v_pk_add_f32 v[110:111], v[84:85], v[92:93]
	v_pk_add_f32 v[84:85], v[84:85], v[92:93] neg_lo:[0,1] neg_hi:[0,1]
	v_mul_f32_e32 v4, 0x3f3504f3, v85
	v_pk_add_f32 v[92:93], v[86:87], v[98:99]
	v_pk_add_f32 v[98:99], v[86:87], v[98:99] neg_lo:[0,1] neg_hi:[0,1]
	v_pk_fma_f32 v[84:85], v[84:85], s[96:97], v[4:5] op_sel_hi:[0,1,0] neg_lo:[0,0,1] neg_hi:[0,0,1]
	v_pk_mul_f32 v[86:87], v[98:99], s[18:19] op_sel_hi:[1,0]
	v_pk_fma_f32 v[96:97], v[98:99], s[18:19], v[86:87] op_sel:[0,0,1] op_sel_hi:[1,0,0] neg_lo:[0,0,1]
	v_pk_add_f32 v[98:99], v[12:13], v[110:111]
	v_pk_add_f32 v[12:13], v[12:13], v[110:111] neg_lo:[0,1] neg_hi:[0,1]
	v_pk_add_f32 v[110:111], v[166:167], v[82:83] op_sel:[0,1] op_sel_hi:[1,0] neg_lo:[0,1]
	v_pk_add_f32 v[82:83], v[166:167], v[82:83] op_sel:[0,1] op_sel_hi:[1,0] neg_hi:[0,1]
	v_pk_add_f32 v[86:87], v[88:89], v[102:103]
	v_pk_add_f32 v[88:89], v[88:89], v[102:103] neg_lo:[0,1] neg_hi:[0,1]
	v_mul_f32_e32 v4, 0x3f3504f3, v89
	v_pk_fma_f32 v[88:89], v[88:89], s[96:97], v[4:5] op_sel_hi:[0,1,0] neg_lo:[0,0,1] neg_hi:[0,0,1]
	v_pk_add_f32 v[166:167], v[108:109], v[100:101]
	v_pk_add_f32 v[100:101], v[108:109], v[100:101] neg_lo:[0,1] neg_hi:[0,1]
	v_pk_mul_f32 v[108:109], v[100:101], s[18:19] op_sel_hi:[1,0]
; #define LAS __attribute__((address_space(3)))
; #define SINCOSPI(x, s, c) do { const float hx_ = 0.5f * (x); *(s) = __builtin_amdgcn_sinf(hx_); *(c) = __builtin_amdgcn_cosf(hx_); } while (0)
; #define OPAQUE_I(x) asm volatile("" : "+v"(x))
; DEV void fft_midx2(LAS cf* buf0, LAS cf* buf1, const unsigned* Kp, int blk) {
;     ...
;     dft_regs<16, true>(w); dft_regs<16, true>(x);
; #pragma unroll
;     for (int q = 0; q < 16; ++q) { p0[q] = w[BR16[q]]; p1[q] = x[BR16[q]]; }
; }
; DEV void fft_i2(LAS cf* buf, int t8) {
;     OPAQUE_I(t8);
;     LAS cf* pb = buf + (t8 >> 4) * 544 + (t8 & 15);
;     float sn, cs; SINCOSPI(-(float)(t8 & 15) * (2.0f / 512.0f), &sn, &cs);
;     const cf w = cf{cs, sn}; cf wp = cf{1.f, 0.f};
;     cf v[32];
; #pragma unroll
;     for (int p = 0; p < 32; ++p) { v[p] = cmulc(pb[17 * p], wp); wp = cmul(wp, w); }
; DEV void hyena_issue_rows(const bf16_t* UT, int s, int c, u32x4 (&r)[4], int tid) {
; #pragma unroll
;     for (int b = 0; b < 4; ++b) r[b] = *(const u32x4*)(UT + ((size_t)(b * 3072 + s * 1024 + c)) * 4096 + tid * 8);
; }
	v_pk_fma_f32 v[102:103], v[100:101], s[18:19], v[108:109] op_sel:[0,0,1] op_sel_hi:[1,0,0] neg_lo:[0,0,1]
	v_pk_add_f32 v[108:109], v[18:19], v[98:99]
	v_pk_add_f32 v[100:101], v[104:105], v[84:85]
	v_pk_add_f32 v[84:85], v[104:105], v[84:85] neg_lo:[0,1] neg_hi:[0,1]
	v_pk_add_f32 v[98:99], v[18:19], v[98:99] neg_lo:[0,1] neg_hi:[0,1]
	v_pk_add_f32 v[104:105], v[8:9], v[116:117]
	v_pk_add_f32 v[116:117], v[8:9], v[116:117] neg_lo:[0,1] neg_hi:[0,1]
	v_mul_f32_e32 v4, 0x3f3504f3, v117
	v_pk_add_f32 v[8:9], v[92:93], v[86:87]
	v_pk_add_f32 v[86:87], v[92:93], v[86:87] neg_lo:[0,1] neg_hi:[0,1]
	v_pk_fma_f32 v[116:117], v[116:117], s[96:97], v[4:5] op_sel_hi:[0,1,0] neg_lo:[0,0,1] neg_hi:[0,0,1]
	v_pk_add_f32 v[92:93], v[74:75], v[12:13] op_sel:[0,1] op_sel_hi:[1,0] neg_lo:[0,1]
	v_pk_add_f32 v[12:13], v[74:75], v[12:13] op_sel:[0,1] op_sel_hi:[1,0] neg_hi:[0,1]
	v_pk_add_f32 v[74:75], v[96:97], v[88:89]
	v_pk_add_f32 v[88:89], v[96:97], v[88:89] neg_lo:[0,1] neg_hi:[0,1]
	v_pk_add_f32 v[96:97], v[110:111], v[100:101]
	v_pk_add_f32 v[18:19], v[110:111], v[100:101] neg_lo:[0,1] neg_hi:[0,1]
	v_pk_add_f32 v[100:101], v[82:83], v[84:85] op_sel:[0,1] op_sel_hi:[1,0] neg_hi:[0,1]
	v_pk_add_f32 v[110:111], v[166:167], v[104:105]
	v_pk_add_f32 v[104:105], v[166:167], v[104:105] neg_lo:[0,1] neg_hi:[0,1]
	v_pk_add_f32 v[166:167], v[82:83], v[84:85] op_sel:[0,1] op_sel_hi:[1,0] neg_lo:[0,1]
	v_pk_add_f32 v[82:83], v[102:103], v[116:117]
	v_pk_add_f32 v[116:117], v[102:103], v[116:117] neg_lo:[0,1] neg_hi:[0,1]
	v_pk_add_f32 v[84:85], v[108:109], v[8:9]
	v_pk_add_f32 v[8:9], v[108:109], v[8:9] neg_lo:[0,1] neg_hi:[0,1]
	v_pk_add_f32 v[108:109], v[98:99], v[86:87] op_sel:[0,1] op_sel_hi:[1,0] neg_lo:[0,1]
	v_pk_add_f32 v[86:87], v[98:99], v[86:87] op_sel:[0,1] op_sel_hi:[1,0] neg_hi:[0,1]
	v_pk_add_f32 v[102:103], v[92:93], v[74:75]
	v_pk_add_f32 v[92:93], v[92:93], v[74:75] neg_lo:[0,1] neg_hi:[0,1]
	v_pk_add_f32 v[74:75], v[12:13], v[88:89] op_sel:[0,1] op_sel_hi:[1,0] neg_lo:[0,1]
	v_pk_add_f32 v[88:89], v[12:13], v[88:89] op_sel:[0,1] op_sel_hi:[1,0] neg_hi:[0,1]
	v_pk_add_f32 v[168:169], v[96:97], v[110:111]
	v_pk_add_f32 v[110:111], v[96:97], v[110:111] neg_lo:[0,1] neg_hi:[0,1]
	v_pk_add_f32 v[96:97], v[18:19], v[104:105] op_sel:[0,1] op_sel_hi:[1,0] neg_lo:[0,1]
	v_pk_add_f32 v[104:105], v[18:19], v[104:105] op_sel:[0,1] op_sel_hi:[1,0] neg_hi:[0,1]
	v_mov_b32_e32 v176, v104
	v_mov_b32_e32 v177, v105
	v_pk_add_f32 v[174:175], v[166:167], v[82:83]
	v_pk_add_f32 v[104:105], v[166:167], v[82:83] neg_lo:[0,1] neg_hi:[0,1]
	v_pk_add_f32 v[98:99], v[100:101], v[116:117] op_sel:[0,1] op_sel_hi:[1,0] neg_lo:[0,1]
	v_pk_add_f32 v[116:117], v[100:101], v[116:117] op_sel:[0,1] op_sel_hi:[1,0] neg_hi:[0,1]
	ds_write2_b64 v161, v[124:125], v[72:73] offset1:1
	ds_write2_b64 v162, v[84:85], v[168:169] offset1:1
	ds_write2_b64 v161, v[94:95], v[90:91] offset0:2 offset1:3
	ds_write2_b64 v162, v[102:103], v[174:175] offset0:2 offset1:3
	ds_write2_b64 v161, v[78:79], v[126:127] offset0:4 offset1:5
	ds_write2_b64 v162, v[108:109], v[96:97] offset0:4 offset1:5
	ds_write2_b64 v161, v[112:113], v[164:165] offset0:6 offset1:7
	ds_write2_b64 v162, v[74:75], v[98:99] offset0:6 offset1:7
	ds_write2_b64 v161, v[114:115], v[80:81] offset0:14 offset1:15
	v_mov_b32_e32 v114, v160
	ds_write2_b64 v161, v[106:107], v[10:11] offset0:8 offset1:9
	ds_write2_b64 v162, v[8:9], v[110:111] offset0:8 offset1:9
	ds_write2_b64 v161, v[68:69], v[122:123] offset0:10 offset1:11
	ds_write2_b64 v162, v[92:93], v[104:105] offset0:10 offset1:11
	ds_write2_b64 v161, v[2:3], v[16:17] offset0:12 offset1:13
	ds_write2_b64 v162, v[86:87], v[176:177] offset0:12 offset1:13
	ds_write2_b64 v162, v[88:89], v[116:117] offset0:14 offset1:15
	s_waitcnt lgkmcnt(0)
	s_barrier
	s_lshl_b32 s100, s19, 10
	s_add_i32 s100, s79, s100
	s_ashr_i32 s101, s100, 31
	s_lshl_b64 s[100:101], s[100:101], 13
	v_lshl_add_u64 v[218:219], v[56:57], 0, s[100:101]
	global_load_dwordx4 v[222:225], v[218:219], off
	s_add_u32 s100, s100, 0x1800000
	s_addc_u32 s101, s101, 0
	v_lshl_add_u64 v[220:221], v[56:57], 0, s[100:101]
	global_load_dwordx4 v[226:229], v[220:221], off
	s_add_u32 s100, s100, 0x1800000
	s_addc_u32 s101, s101, 0
	v_lshl_add_u64 v[218:219], v[56:57], 0, s[100:101]
	global_load_dwordx4 v[236:239], v[218:219], off
	s_add_u32 s100, s100, 0x1800000
	s_addc_u32 s101, s101, 0
	v_lshl_add_u64 v[220:221], v[56:57], 0, s[100:101]
	global_load_dwordx4 v[240:243], v[220:221], off
	s_nop 0
	v_lshrrev_b32_e32 v115, 4, v114
	v_and_b32_e32 v114, 15, v114
	v_mul_lo_u32 v115, v115, s15
	v_lshlrev_b32_e32 v2, 3, v114
	v_cvt_f32_ubyte0_e32 v114, v114
	v_add3_u32 v74, v159, v115, v2
	v_mul_f32_e32 v114, 0xbb800000, v114
	v_mul_f32_e32 v114, 0.5, v114
	v_add_u32_e32 v232, 0x800, v74
	v_add_u32_e32 v233, 0xc00, v74
	ds_read2_b64 v[166:169], v74 offset1:17
	ds_read2_b64 v[170:173], v74 offset0:34 offset1:51
	ds_read2_b64 v[174:177], v74 offset0:68 offset1:85
	ds_read2_b64 v[178:181], v74 offset0:102 offset1:119
	ds_read2_b64 v[182:185], v74 offset0:136 offset1:153
	ds_read2_b64 v[186:189], v74 offset0:170 offset1:187
	ds_read2_b64 v[190:193], v74 offset0:204 offset1:221
	ds_read2_b64 v[194:197], v74 offset0:238 offset1:255
	ds_read2_b64 v[198:201], v232 offset0:16 offset1:33
	ds_read2_b64 v[202:205], v232 offset0:50 offset1:67
	ds_read2_b64 v[208:211], v232 offset0:84 offset1:101
	ds_read2_b64 v[214:217], v232 offset0:118 offset1:135
	ds_read2_b64 v[218:221], v232 offset0:152 offset1:169
	v_sin_f32_e32 v115, v114
	v_cos_f32_e32 v114, v114
	s_waitcnt lgkmcnt(12)
; #define SINCOSPI(x, s, c) do { const float hx_ = 0.5f * (x); *(s) = __builtin_amdgcn_sinf(hx_); *(c) = __builtin_amdgcn_cosf(hx_); } while (0)
; DEV void fft_i2(LAS cf* buf, int t8) {
;     ...
;     float sn, cs; SINCOSPI(-(float)(t8 & 15) * (2.0f / 512.0f), &sn, &cs);
;     const cf w = cf{cs, sn}; cf wp = cf{1.f, 0.f};
;     cf v[32];
; #pragma unroll
;     for (int p = 0; p < 32; ++p) { v[p] = cmulc(pb[17 * p], wp); wp = cmul(wp, w); }
	v_pk_mul_f32 v[2:3], v[166:167], v[66:67] op_sel:[1,1] op_sel_hi:[1,0]
	v_pk_fma_f32 v[4:5], v[166:167], v[66:67], v[2:3] op_sel_hi:[0,1,1] neg_hi:[1,0,0]
	v_add_u32_e32 v75, 0x800, v74
	v_pk_mul_f32 v[2:3], v[66:67], v[114:115] op_sel:[1,1] op_sel_hi:[1,0] neg_lo:[1,0]
	v_pk_fma_f32 v[8:9], v[66:67], v[114:115], v[2:3] op_sel_hi:[0,1,1]
	v_pk_mul_f32 v[10:11], v[168:169], v[8:9] op_sel:[1,1] op_sel_hi:[1,0]
	v_pk_fma_f32 v[2:3], v[168:169], v[8:9], v[10:11] op_sel_hi:[0,1,1] neg_hi:[1,0,0]
	v_pk_mul_f32 v[6:7], v[8:9], v[114:115] op_sel:[1,1] op_sel_hi:[1,0] neg_lo:[1,0]
	v_pk_fma_f32 v[12:13], v[8:9], v[114:115], v[6:7] op_sel_hi:[0,1,1]
	ds_read2_b64 v[166:169], v232 offset0:186 offset1:203
	s_waitcnt lgkmcnt(12)
	v_pk_mul_f32 v[14:15], v[170:171], v[12:13] op_sel:[1,1] op_sel_hi:[1,0]
	v_pk_fma_f32 v[10:11], v[170:171], v[12:13], v[14:15] op_sel_hi:[0,1,1] neg_hi:[1,0,0]
	v_pk_mul_f32 v[6:7], v[12:13], v[114:115] op_sel:[1,1] op_sel_hi:[1,0] neg_lo:[1,0]
	v_pk_fma_f32 v[12:13], v[12:13], v[114:115], v[6:7] op_sel_hi:[0,1,1]
	v_pk_mul_f32 v[14:15], v[172:173], v[12:13] op_sel:[1,1] op_sel_hi:[1,0]
	v_pk_fma_f32 v[6:7], v[172:173], v[12:13], v[14:15] op_sel_hi:[0,1,1] neg_hi:[1,0,0]
	v_pk_mul_f32 v[8:9], v[12:13], v[114:115] op_sel:[1,1] op_sel_hi:[1,0] neg_lo:[1,0]
	v_pk_fma_f32 v[16:17], v[12:13], v[114:115], v[8:9] op_sel_hi:[0,1,1]
	ds_read2_b64 v[170:173], v232 offset0:220 offset1:237
	s_waitcnt lgkmcnt(12)
	v_pk_mul_f32 v[8:9], v[174:175], v[16:17] op_sel:[1,1] op_sel_hi:[1,0]
	v_pk_fma_f32 v[12:13], v[174:175], v[16:17], v[8:9] op_sel_hi:[0,1,1] neg_hi:[1,0,0]
	v_pk_mul_f32 v[8:9], v[16:17], v[114:115] op_sel:[1,1] op_sel_hi:[1,0] neg_lo:[1,0]
	v_pk_fma_f32 v[16:17], v[16:17], v[114:115], v[8:9] op_sel_hi:[0,1,1]
	v_pk_mul_f32 v[18:19], v[176:177], v[16:17] op_sel:[1,1] op_sel_hi:[1,0]
	v_pk_fma_f32 v[8:9], v[176:177], v[16:17], v[18:19] op_sel_hi:[0,1,1] neg_hi:[1,0,0]
	v_pk_mul_f32 v[14:15], v[16:17], v[114:115] op_sel:[1,1] op_sel_hi:[1,0] neg_lo:[1,0]
	v_pk_fma_f32 v[68:69], v[16:17], v[114:115], v[14:15] op_sel_hi:[0,1,1]
	ds_read2_b64 v[174:177], v233 offset0:126 offset1:143
	s_waitcnt lgkmcnt(12)
	v_pk_mul_f32 v[14:15], v[178:179], v[68:69] op_sel:[1,1] op_sel_hi:[1,0]
	v_pk_fma_f32 v[16:17], v[178:179], v[68:69], v[14:15] op_sel_hi:[0,1,1] neg_hi:[1,0,0]
	v_pk_mul_f32 v[14:15], v[68:69], v[114:115] op_sel:[1,1] op_sel_hi:[1,0] neg_lo:[1,0]
	v_pk_fma_f32 v[68:69], v[68:69], v[114:115], v[14:15] op_sel_hi:[0,1,1]
	v_pk_mul_f32 v[70:71], v[180:181], v[68:69] op_sel:[1,1] op_sel_hi:[1,0]
	v_pk_fma_f32 v[14:15], v[180:181], v[68:69], v[70:71] op_sel_hi:[0,1,1] neg_hi:[1,0,0]
	v_pk_mul_f32 v[18:19], v[68:69], v[114:115] op_sel:[1,1] op_sel_hi:[1,0] neg_lo:[1,0]
	v_pk_fma_f32 v[72:73], v[68:69], v[114:115], v[18:19] op_sel_hi:[0,1,1]
	s_waitcnt lgkmcnt(11)
	v_pk_mul_f32 v[18:19], v[182:183], v[72:73] op_sel:[1,1] op_sel_hi:[1,0]
	v_pk_fma_f32 v[68:69], v[182:183], v[72:73], v[18:19] op_sel_hi:[0,1,1] neg_hi:[1,0,0]
	v_pk_mul_f32 v[18:19], v[72:73], v[114:115] op_sel:[1,1] op_sel_hi:[1,0] neg_lo:[1,0]
	v_pk_fma_f32 v[72:73], v[72:73], v[114:115], v[18:19] op_sel_hi:[0,1,1]
	v_pk_mul_f32 v[86:87], v[184:185], v[72:73] op_sel:[1,1] op_sel_hi:[1,0]
	v_pk_fma_f32 v[18:19], v[184:185], v[72:73], v[86:87] op_sel_hi:[0,1,1] neg_hi:[1,0,0]
	v_pk_mul_f32 v[70:71], v[72:73], v[114:115] op_sel:[1,1] op_sel_hi:[1,0] neg_lo:[1,0]
	v_pk_fma_f32 v[76:77], v[72:73], v[114:115], v[70:71] op_sel_hi:[0,1,1]
	s_waitcnt lgkmcnt(10)
	v_pk_mul_f32 v[70:71], v[186:187], v[76:77] op_sel:[1,1] op_sel_hi:[1,0]
	v_pk_fma_f32 v[72:73], v[186:187], v[76:77], v[70:71] op_sel_hi:[0,1,1] neg_hi:[1,0,0]
	v_pk_mul_f32 v[70:71], v[76:77], v[114:115] op_sel:[1,1] op_sel_hi:[1,0] neg_lo:[1,0]
	v_pk_fma_f32 v[76:77], v[76:77], v[114:115], v[70:71] op_sel_hi:[0,1,1]
	v_pk_mul_f32 v[78:79], v[188:189], v[76:77] op_sel:[1,1] op_sel_hi:[1,0]
	v_pk_fma_f32 v[70:71], v[188:189], v[76:77], v[78:79] op_sel_hi:[0,1,1] neg_hi:[1,0,0]
	v_pk_mul_f32 v[86:87], v[76:77], v[114:115] op_sel:[1,1] op_sel_hi:[1,0] neg_lo:[1,0]
	v_pk_fma_f32 v[80:81], v[76:77], v[114:115], v[86:87] op_sel_hi:[0,1,1]
	s_waitcnt lgkmcnt(9)
	v_pk_mul_f32 v[86:87], v[190:191], v[80:81] op_sel:[1,1] op_sel_hi:[1,0]
	v_pk_fma_f32 v[76:77], v[190:191], v[80:81], v[86:87] op_sel_hi:[0,1,1] neg_hi:[1,0,0]
	v_pk_mul_f32 v[86:87], v[80:81], v[114:115] op_sel:[1,1] op_sel_hi:[1,0] neg_lo:[1,0]
	v_pk_fma_f32 v[80:81], v[80:81], v[114:115], v[86:87] op_sel_hi:[0,1,1]
	v_pk_mul_f32 v[82:83], v[192:193], v[80:81] op_sel:[1,1] op_sel_hi:[1,0]
	v_pk_fma_f32 v[86:87], v[192:193], v[80:81], v[82:83] op_sel_hi:[0,1,1] neg_hi:[1,0,0]
	v_pk_mul_f32 v[78:79], v[80:81], v[114:115] op_sel:[1,1] op_sel_hi:[1,0] neg_lo:[1,0]
	v_pk_fma_f32 v[84:85], v[80:81], v[114:115], v[78:79] op_sel_hi:[0,1,1]
	s_waitcnt lgkmcnt(8)
	v_pk_mul_f32 v[78:79], v[194:195], v[84:85] op_sel:[1,1] op_sel_hi:[1,0]
	v_pk_fma_f32 v[80:81], v[194:195], v[84:85], v[78:79] op_sel_hi:[0,1,1] neg_hi:[1,0,0]
	v_pk_mul_f32 v[78:79], v[84:85], v[114:115] op_sel:[1,1] op_sel_hi:[1,0] neg_lo:[1,0]
	v_pk_fma_f32 v[84:85], v[84:85], v[114:115], v[78:79] op_sel_hi:[0,1,1]
	v_pk_mul_f32 v[88:89], v[196:197], v[84:85] op_sel:[1,1] op_sel_hi:[1,0]
	v_pk_fma_f32 v[78:79], v[196:197], v[84:85], v[88:89] op_sel_hi:[0,1,1] neg_hi:[1,0,0]
	v_pk_mul_f32 v[82:83], v[84:85], v[114:115] op_sel:[1,1] op_sel_hi:[1,0] neg_lo:[1,0]
	v_pk_fma_f32 v[92:93], v[84:85], v[114:115], v[82:83] op_sel_hi:[0,1,1]
	s_waitcnt lgkmcnt(7)
; #define SINCOSPI(x, s, c) do { const float hx_ = 0.5f * (x); *(s) = __builtin_amdgcn_sinf(hx_); *(c) = __builtin_amdgcn_cosf(hx_); } while (0)
; DEV void fft_i2(LAS cf* buf, int t8) {
;     ...
;     float sn, cs; SINCOSPI(-(float)(t8 & 15) * (2.0f / 512.0f), &sn, &cs);
;     const cf w = cf{cs, sn}; cf wp = cf{1.f, 0.f};
;     cf v[32];
; #pragma unroll
;     for (int p = 0; p < 32; ++p) { v[p] = cmulc(pb[17 * p], wp); wp = cmul(wp, w); }
	v_pk_mul_f32 v[82:83], v[198:199], v[92:93] op_sel:[1,1] op_sel_hi:[1,0]
	v_pk_fma_f32 v[84:85], v[198:199], v[92:93], v[82:83] op_sel_hi:[0,1,1] neg_hi:[1,0,0]
	v_pk_mul_f32 v[82:83], v[92:93], v[114:115] op_sel:[1,1] op_sel_hi:[1,0] neg_lo:[1,0]
	v_pk_fma_f32 v[88:89], v[92:93], v[114:115], v[82:83] op_sel_hi:[0,1,1]
	v_pk_mul_f32 v[92:93], v[200:201], v[88:89] op_sel:[1,1] op_sel_hi:[1,0]
	v_pk_fma_f32 v[82:83], v[200:201], v[88:89], v[92:93] op_sel_hi:[0,1,1] neg_hi:[1,0,0]
	v_pk_mul_f32 v[90:91], v[88:89], v[114:115] op_sel:[1,1] op_sel_hi:[1,0] neg_lo:[1,0]
	v_pk_fma_f32 v[92:93], v[88:89], v[114:115], v[90:91] op_sel_hi:[0,1,1]
	s_waitcnt lgkmcnt(6)
	v_pk_mul_f32 v[96:97], v[202:203], v[92:93] op_sel:[1,1] op_sel_hi:[1,0]
	v_pk_fma_f32 v[94:95], v[202:203], v[92:93], v[96:97] op_sel_hi:[0,1,1] neg_hi:[1,0,0]
	v_pk_mul_f32 v[88:89], v[92:93], v[114:115] op_sel:[1,1] op_sel_hi:[1,0] neg_lo:[1,0]
	v_pk_fma_f32 v[92:93], v[92:93], v[114:115], v[88:89] op_sel_hi:[0,1,1]
	v_pk_mul_f32 v[88:89], v[204:205], v[92:93] op_sel:[1,1] op_sel_hi:[1,0]
	v_pk_fma_f32 v[96:97], v[204:205], v[92:93], v[88:89] op_sel_hi:[0,1,1] neg_hi:[1,0,0]
	v_pk_mul_f32 v[88:89], v[92:93], v[114:115] op_sel:[1,1] op_sel_hi:[1,0] neg_lo:[1,0]
	v_pk_fma_f32 v[92:93], v[92:93], v[114:115], v[88:89] op_sel_hi:[0,1,1]
	s_waitcnt lgkmcnt(5)
	v_pk_mul_f32 v[100:101], v[208:209], v[92:93] op_sel:[1,1] op_sel_hi:[1,0]
	v_pk_fma_f32 v[98:99], v[208:209], v[92:93], v[100:101] op_sel_hi:[0,1,1] neg_hi:[1,0,0]
	v_pk_mul_f32 v[88:89], v[92:93], v[114:115] op_sel:[1,1] op_sel_hi:[1,0] neg_lo:[1,0]
	v_pk_fma_f32 v[92:93], v[92:93], v[114:115], v[88:89] op_sel_hi:[0,1,1]
	v_pk_mul_f32 v[88:89], v[210:211], v[92:93] op_sel:[1,1] op_sel_hi:[1,0]
	v_pk_fma_f32 v[100:101], v[210:211], v[92:93], v[88:89] op_sel_hi:[0,1,1] neg_hi:[1,0,0]
	v_pk_mul_f32 v[88:89], v[92:93], v[114:115] op_sel:[1,1] op_sel_hi:[1,0] neg_lo:[1,0]
	v_pk_fma_f32 v[92:93], v[92:93], v[114:115], v[88:89] op_sel_hi:[0,1,1]
	s_waitcnt lgkmcnt(4)
	v_pk_mul_f32 v[104:105], v[214:215], v[92:93] op_sel:[1,1] op_sel_hi:[1,0]
	v_pk_fma_f32 v[102:103], v[214:215], v[92:93], v[104:105] op_sel_hi:[0,1,1] neg_hi:[1,0,0]
	v_pk_mul_f32 v[88:89], v[92:93], v[114:115] op_sel:[1,1] op_sel_hi:[1,0] neg_lo:[1,0]
	v_pk_fma_f32 v[92:93], v[92:93], v[114:115], v[88:89] op_sel_hi:[0,1,1]
	v_pk_mul_f32 v[88:89], v[216:217], v[92:93] op_sel:[1,1] op_sel_hi:[1,0]
	v_pk_fma_f32 v[104:105], v[216:217], v[92:93], v[88:89] op_sel_hi:[0,1,1] neg_hi:[1,0,0]
	v_pk_mul_f32 v[88:89], v[92:93], v[114:115] op_sel:[1,1] op_sel_hi:[1,0] neg_lo:[1,0]
	v_pk_fma_f32 v[92:93], v[92:93], v[114:115], v[88:89] op_sel_hi:[0,1,1]
	s_waitcnt lgkmcnt(3)
	v_pk_mul_f32 v[108:109], v[218:219], v[92:93] op_sel:[1,1] op_sel_hi:[1,0]
	v_pk_fma_f32 v[106:107], v[218:219], v[92:93], v[108:109] op_sel_hi:[0,1,1] neg_hi:[1,0,0]
	v_pk_mul_f32 v[88:89], v[92:93], v[114:115] op_sel:[1,1] op_sel_hi:[1,0] neg_lo:[1,0]
	v_pk_fma_f32 v[92:93], v[92:93], v[114:115], v[88:89] op_sel_hi:[0,1,1]
	v_pk_mul_f32 v[88:89], v[220:221], v[92:93] op_sel:[1,1] op_sel_hi:[1,0]
	v_pk_fma_f32 v[108:109], v[220:221], v[92:93], v[88:89] op_sel_hi:[0,1,1] neg_hi:[1,0,0]
	v_pk_mul_f32 v[88:89], v[92:93], v[114:115] op_sel:[1,1] op_sel_hi:[1,0] neg_lo:[1,0]
	v_pk_fma_f32 v[92:93], v[92:93], v[114:115], v[88:89] op_sel_hi:[0,1,1]
	s_waitcnt lgkmcnt(2)
	v_pk_mul_f32 v[112:113], v[166:167], v[92:93] op_sel:[1,1] op_sel_hi:[1,0]
	v_pk_fma_f32 v[110:111], v[166:167], v[92:93], v[112:113] op_sel_hi:[0,1,1] neg_hi:[1,0,0]
	v_pk_mul_f32 v[88:89], v[92:93], v[114:115] op_sel:[1,1] op_sel_hi:[1,0] neg_lo:[1,0]
	v_pk_fma_f32 v[92:93], v[92:93], v[114:115], v[88:89] op_sel_hi:[0,1,1]
	v_pk_mul_f32 v[88:89], v[168:169], v[92:93] op_sel:[1,1] op_sel_hi:[1,0]
	v_pk_fma_f32 v[112:113], v[168:169], v[92:93], v[88:89] op_sel_hi:[0,1,1] neg_hi:[1,0,0]
	v_pk_mul_f32 v[88:89], v[92:93], v[114:115] op_sel:[1,1] op_sel_hi:[1,0] neg_lo:[1,0]
	v_pk_fma_f32 v[92:93], v[92:93], v[114:115], v[88:89] op_sel_hi:[0,1,1]
	s_waitcnt lgkmcnt(1)
	v_pk_mul_f32 v[116:117], v[170:171], v[92:93] op_sel:[1,1] op_sel_hi:[1,0]
	v_pk_fma_f32 v[0:1], v[170:171], v[92:93], v[116:117] op_sel_hi:[0,1,1] neg_hi:[1,0,0]
	v_pk_mul_f32 v[88:89], v[92:93], v[114:115] op_sel:[1,1] op_sel_hi:[1,0] neg_lo:[1,0]
	v_pk_fma_f32 v[92:93], v[92:93], v[114:115], v[88:89] op_sel_hi:[0,1,1]
	v_pk_mul_f32 v[88:89], v[172:173], v[92:93] op_sel:[1,1] op_sel_hi:[1,0]
	v_pk_fma_f32 v[116:117], v[172:173], v[92:93], v[88:89] op_sel_hi:[0,1,1] neg_hi:[1,0,0]
	v_pk_mul_f32 v[88:89], v[92:93], v[114:115] op_sel:[1,1] op_sel_hi:[1,0] neg_lo:[1,0]
	v_pk_fma_f32 v[118:119], v[92:93], v[114:115], v[88:89] op_sel_hi:[0,1,1]
	v_add_u32_e32 v88, 0xc00, v74
	v_pk_mul_f32 v[120:121], v[118:119], v[114:115] op_sel:[1,1] op_sel_hi:[1,0] neg_lo:[1,0]
	v_pk_fma_f32 v[114:115], v[118:119], v[114:115], v[120:121] op_sel_hi:[0,1,1]
	s_waitcnt lgkmcnt(0)
; template <int R, bool INV> DEV void dft_regs(cf (&v)[R]) {
; #pragma unroll
;     for (int s = R; s >= 2; s >>= 1) {
;         const int h = s >> 1;
; #pragma unroll
;         for (int b = 0; b < R; b += s) {
; #pragma unroll
;             for (int k = 0; k < h; ++k) {
;                 const cf a = v[b + k], c = v[b + k + h];
;                 v[b + k] = a + c;
;                 const cf d = a - c;
;                 const int m = k * (32 / s);
;                 const float wr = tw_cos(m), wi = INV ? tw_sin(m) : -tw_sin(m);
;                 v[b + k + h] = cf{d.x * wr - d.y * wi, d.x * wi + d.y * wr};
;             }
;         }
;     }
; }
; DEV void fft_i2(LAS cf* buf, int t8) {
;     ...
;     for (int p = 0; p < 32; ++p) { v[p] = cmulc(pb[17 * p], wp); wp = cmul(wp, w); }
;     dft_regs<32, true>(v);
	v_pk_mul_f32 v[120:121], v[174:175], v[118:119] op_sel:[1,1] op_sel_hi:[1,0]
	v_pk_fma_f32 v[90:91], v[174:175], v[118:119], v[120:121] op_sel_hi:[0,1,1] neg_hi:[1,0,0]
	v_pk_mul_f32 v[118:119], v[176:177], v[114:115] op_sel:[1,1] op_sel_hi:[1,0]
	v_pk_fma_f32 v[114:115], v[176:177], v[114:115], v[118:119] op_sel_hi:[0,1,1] neg_hi:[1,0,0]
	v_pk_add_f32 v[92:93], v[4:5], v[84:85]
	v_pk_add_f32 v[4:5], v[4:5], v[84:85] neg_lo:[0,1] neg_hi:[0,1]
	v_mov_b32_e32 v118, v4
	v_mov_b32_e32 v119, v5
	v_pk_add_f32 v[4:5], v[2:3], v[82:83]
	v_pk_add_f32 v[2:3], v[2:3], v[82:83] neg_lo:[0,1] neg_hi:[0,1]
	v_pk_mul_f32 v[82:83], v[2:3], s[82:83] op_sel_hi:[1,0]
	v_pk_fma_f32 v[84:85], v[2:3], s[94:95], v[82:83] op_sel:[0,0,1] op_sel_hi:[1,0,0] neg_lo:[0,0,1]
	v_pk_add_f32 v[2:3], v[10:11], v[94:95]
	v_pk_add_f32 v[10:11], v[10:11], v[94:95] neg_lo:[0,1] neg_hi:[0,1]
	v_pk_mul_f32 v[82:83], v[10:11], s[84:85] op_sel_hi:[1,0]
	v_pk_fma_f32 v[94:95], v[10:11], s[16:17], v[82:83] op_sel:[0,0,1] op_sel_hi:[1,0,0] neg_lo:[0,0,1]
	v_pk_add_f32 v[10:11], v[6:7], v[96:97]
	v_pk_add_f32 v[6:7], v[6:7], v[96:97] neg_lo:[0,1] neg_hi:[0,1]
	v_pk_mul_f32 v[82:83], v[6:7], s[4:5] op_sel_hi:[1,0]
	v_pk_fma_f32 v[96:97], v[6:7], s[86:87], v[82:83] op_sel:[0,0,1] op_sel_hi:[1,0,0] neg_lo:[0,0,1]
	v_pk_add_f32 v[6:7], v[12:13], v[98:99]
	v_pk_add_f32 v[12:13], v[12:13], v[98:99] neg_lo:[0,1] neg_hi:[0,1]
	v_pk_mul_f32 v[82:83], v[12:13], s[18:19] op_sel_hi:[1,0]
	v_pk_fma_f32 v[98:99], v[12:13], s[18:19], v[82:83] op_sel:[0,0,1] op_sel_hi:[1,0,0] neg_lo:[0,0,1]
	v_pk_add_f32 v[12:13], v[8:9], v[100:101]
	v_pk_add_f32 v[8:9], v[8:9], v[100:101] neg_lo:[0,1] neg_hi:[0,1]
	v_pk_mul_f32 v[82:83], v[8:9], s[86:87] op_sel_hi:[1,0]
	v_pk_fma_f32 v[100:101], v[8:9], s[4:5], v[82:83] op_sel:[0,0,1] op_sel_hi:[1,0,0] neg_lo:[0,0,1]
	v_pk_add_f32 v[8:9], v[16:17], v[102:103]
	v_pk_add_f32 v[16:17], v[16:17], v[102:103] neg_lo:[0,1] neg_hi:[0,1]
	v_pk_mul_f32 v[82:83], v[16:17], s[16:17] op_sel_hi:[1,0]
	v_pk_fma_f32 v[102:103], v[16:17], s[84:85], v[82:83] op_sel:[0,0,1] op_sel_hi:[1,0,0] neg_lo:[0,0,1]
	v_pk_add_f32 v[16:17], v[14:15], v[104:105]
	v_pk_add_f32 v[14:15], v[14:15], v[104:105] neg_lo:[0,1] neg_hi:[0,1]
	v_pk_mul_f32 v[82:83], v[14:15], s[94:95] op_sel_hi:[1,0]
	v_pk_fma_f32 v[104:105], v[14:15], s[82:83], v[82:83] op_sel:[0,0,1] op_sel_hi:[1,0,0] neg_lo:[0,0,1]
	v_pk_add_f32 v[14:15], v[68:69], v[106:107]
	v_pk_add_f32 v[68:69], v[68:69], v[106:107] neg_lo:[0,1] neg_hi:[0,1]
	v_pk_add_f32 v[82:83], v[18:19], v[108:109]
	v_pk_add_f32 v[18:19], v[18:19], v[108:109] neg_lo:[0,1] neg_hi:[0,1]
	v_pk_mul_f32 v[106:107], v[18:19], s[6:7] op_sel:[1,0]
	s_mov_b32 s6, s87
	v_pk_fma_f32 v[18:19], v[18:19], s[28:29], v[106:107] op_sel_hi:[0,1,1] neg_lo:[0,0,1] neg_hi:[0,0,1]
	v_pk_add_f32 v[106:107], v[72:73], v[110:111]
	v_pk_add_f32 v[72:73], v[72:73], v[110:111] neg_lo:[0,1] neg_hi:[0,1]
	s_mov_b32 s7, s86
	v_pk_mul_f32 v[108:109], v[72:73], s[24:25] op_sel:[1,0]
	v_pk_fma_f32 v[72:73], v[72:73], s[0:1], v[108:109] op_sel_hi:[0,1,1] neg_lo:[0,0,1] neg_hi:[0,0,1]
	v_pk_add_f32 v[108:109], v[70:71], v[112:113]
	v_pk_add_f32 v[70:71], v[70:71], v[112:113] neg_lo:[0,1] neg_hi:[0,1]
	v_pk_mul_f32 v[110:111], v[70:71], s[2:3] op_sel:[1,0]
	s_mov_b32 s2, s11
	v_pk_fma_f32 v[70:71], v[70:71], s[6:7], v[110:111] op_sel_hi:[0,1,1] neg_lo:[0,0,1] neg_hi:[0,0,1]
	v_pk_add_f32 v[110:111], v[76:77], v[0:1]
	v_pk_add_f32 v[76:77], v[76:77], v[0:1] neg_lo:[0,1] neg_hi:[0,1]
	v_mul_f32_e32 v112, 0x3f3504f3, v77
	v_pk_fma_f32 v[76:77], v[76:77], s[96:97], v[112:113] op_sel_hi:[0,1,0] neg_lo:[0,0,1] neg_hi:[0,0,1]
	v_pk_add_f32 v[112:113], v[86:87], v[116:117]
	v_pk_add_f32 v[86:87], v[86:87], v[116:117] neg_lo:[0,1] neg_hi:[0,1]
	v_pk_mul_f32 v[0:1], v[86:87], s[4:5] op_sel:[1,0]
	s_lshl_b32 s5, s19, 10
	v_pk_fma_f32 v[86:87], v[86:87], s[2:3], v[0:1] op_sel_hi:[0,1,1] neg_lo:[0,0,1] neg_hi:[0,0,1]
	v_pk_add_f32 v[0:1], v[80:81], v[90:91]
	v_pk_add_f32 v[80:81], v[80:81], v[90:91] neg_lo:[0,1] neg_hi:[0,1]
	s_mov_b32 s2, s9
	v_pk_mul_f32 v[90:91], v[80:81], s[84:85] op_sel:[1,0]
	s_mov_b32 s3, s82
	v_pk_fma_f32 v[80:81], v[80:81], s[88:89], v[90:91] op_sel_hi:[0,1,1] neg_lo:[0,0,1] neg_hi:[0,0,1]
	v_pk_add_f32 v[90:91], v[78:79], v[114:115]
	v_pk_add_f32 v[114:115], v[78:79], v[114:115] neg_lo:[0,1] neg_hi:[0,1]
	s_add_i32 s6, s79, s5
	v_pk_mul_f32 v[78:79], v[114:115], s[82:83] op_sel:[1,0]
	s_ashr_i32 s7, s6, 31
	v_pk_fma_f32 v[114:115], v[114:115], s[2:3], v[78:79] op_sel_hi:[0,1,1] neg_lo:[0,0,1] neg_hi:[0,0,1]
	v_pk_add_f32 v[78:79], v[92:93], v[14:15]
	v_pk_add_f32 v[14:15], v[92:93], v[14:15] neg_lo:[0,1] neg_hi:[0,1]
	s_lshl_b64 s[2:3], s[6:7], 13
	v_mov_b32_e32 v116, v14
	v_mov_b32_e32 v117, v15
	v_pk_add_f32 v[14:15], v[4:5], v[82:83]
	v_pk_add_f32 v[4:5], v[4:5], v[82:83] neg_lo:[0,1] neg_hi:[0,1]
	v_pk_mul_f32 v[82:83], v[4:5], s[84:85] op_sel_hi:[1,0]
	v_pk_fma_f32 v[92:93], v[4:5], s[16:17], v[82:83] op_sel:[0,0,1] op_sel_hi:[1,0,0] neg_lo:[0,0,1]
	v_pk_add_f32 v[4:5], v[2:3], v[106:107]
	v_pk_add_f32 v[2:3], v[2:3], v[106:107] neg_lo:[0,1] neg_hi:[0,1]
	v_pk_mul_f32 v[82:83], v[2:3], s[18:19] op_sel_hi:[1,0]
	v_pk_fma_f32 v[106:107], v[2:3], s[18:19], v[82:83] op_sel:[0,0,1] op_sel_hi:[1,0,0] neg_lo:[0,0,1]
	v_pk_add_f32 v[2:3], v[10:11], v[108:109]
	v_pk_add_f32 v[10:11], v[10:11], v[108:109] neg_lo:[0,1] neg_hi:[0,1]
	v_pk_mul_f32 v[82:83], v[10:11], s[16:17] op_sel_hi:[1,0]
	v_pk_fma_f32 v[108:109], v[10:11], s[84:85], v[82:83] op_sel:[0,0,1] op_sel_hi:[1,0,0] neg_lo:[0,0,1]
	v_pk_add_f32 v[10:11], v[6:7], v[110:111]
	v_pk_add_f32 v[6:7], v[6:7], v[110:111] neg_lo:[0,1] neg_hi:[0,1]
; template <int R, bool INV> DEV void dft_regs(cf (&v)[R]) {
; #pragma unroll
;     for (int s = R; s >= 2; s >>= 1) {
;         const int h = s >> 1;
; #pragma unroll
;         for (int b = 0; b < R; b += s) {
; #pragma unroll
;             for (int k = 0; k < h; ++k) {
;                 const cf a = v[b + k], c = v[b + k + h];
;                 v[b + k] = a + c;
;                 const cf d = a - c;
;                 const int m = k * (32 / s);
;                 const float wr = tw_cos(m), wi = INV ? tw_sin(m) : -tw_sin(m);
;                 v[b + k + h] = cf{d.x * wr - d.y * wi, d.x * wi + d.y * wr};
;             }
;         }
;     }
; }
	v_pk_add_f32 v[82:83], v[6:7], 0 op_sel:[1,0] op_sel_hi:[0,0] neg_lo:[1,0]
	v_pk_add_f32 v[6:7], v[12:13], v[112:113]
	v_pk_add_f32 v[12:13], v[12:13], v[112:113] neg_lo:[0,1] neg_hi:[0,1]
	v_pk_mul_f32 v[110:111], v[12:13], s[24:25] op_sel:[1,0]
	v_pk_fma_f32 v[12:13], v[12:13], s[0:1], v[110:111] op_sel_hi:[0,1,1] neg_lo:[0,0,1] neg_hi:[0,0,1]
	v_pk_add_f32 v[110:111], v[8:9], v[0:1]
	v_pk_add_f32 v[8:9], v[8:9], v[0:1] neg_lo:[0,1] neg_hi:[0,1]
	v_mul_f32_e32 v112, 0x3f3504f3, v9
	v_pk_fma_f32 v[8:9], v[8:9], s[96:97], v[112:113] op_sel_hi:[0,1,0] neg_lo:[0,0,1] neg_hi:[0,0,1]
	v_pk_add_f32 v[112:113], v[16:17], v[90:91]
	v_pk_add_f32 v[16:17], v[16:17], v[90:91] neg_lo:[0,1] neg_hi:[0,1]
	v_pk_mul_f32 v[90:91], v[16:17], s[84:85] op_sel:[1,0]
	v_pk_fma_f32 v[16:17], v[16:17], s[88:89], v[90:91] op_sel_hi:[0,1,1] neg_lo:[0,0,1] neg_hi:[0,0,1]
	v_pk_add_f32 v[90:91], v[118:119], v[68:69] op_sel:[0,1] op_sel_hi:[1,0] neg_lo:[0,1]
	v_pk_add_f32 v[68:69], v[118:119], v[68:69] op_sel:[0,1] op_sel_hi:[1,0] neg_hi:[0,1]
	v_pk_add_f32 v[118:119], v[84:85], v[18:19]
	v_pk_add_f32 v[18:19], v[84:85], v[18:19] neg_lo:[0,1] neg_hi:[0,1]
	v_pk_mul_f32 v[84:85], v[18:19], s[84:85] op_sel_hi:[1,0]
	v_pk_fma_f32 v[0:1], v[18:19], s[16:17], v[84:85] op_sel:[0,0,1] op_sel_hi:[1,0,0] neg_lo:[0,0,1]
	v_pk_add_f32 v[18:19], v[94:95], v[72:73]
	v_pk_add_f32 v[72:73], v[94:95], v[72:73] neg_lo:[0,1] neg_hi:[0,1]
	v_pk_mul_f32 v[84:85], v[72:73], s[18:19] op_sel_hi:[1,0]
	v_pk_fma_f32 v[94:95], v[72:73], s[18:19], v[84:85] op_sel:[0,0,1] op_sel_hi:[1,0,0] neg_lo:[0,0,1]
	v_pk_add_f32 v[72:73], v[96:97], v[70:71]
	v_pk_add_f32 v[70:71], v[96:97], v[70:71] neg_lo:[0,1] neg_hi:[0,1]
	v_pk_mul_f32 v[84:85], v[70:71], s[16:17] op_sel_hi:[1,0]
	v_pk_fma_f32 v[96:97], v[70:71], s[84:85], v[84:85] op_sel:[0,0,1] op_sel_hi:[1,0,0] neg_lo:[0,0,1]
	v_pk_add_f32 v[70:71], v[98:99], v[76:77]
	v_pk_add_f32 v[76:77], v[98:99], v[76:77] neg_lo:[0,1] neg_hi:[0,1]
	v_pk_add_f32 v[84:85], v[100:101], v[86:87]
	v_pk_add_f32 v[86:87], v[100:101], v[86:87] neg_lo:[0,1] neg_hi:[0,1]
	v_pk_mul_f32 v[98:99], v[86:87], s[24:25] op_sel:[1,0]
	v_pk_fma_f32 v[86:87], v[86:87], s[0:1], v[98:99] op_sel_hi:[0,1,1] neg_lo:[0,0,1] neg_hi:[0,0,1]
	v_pk_add_f32 v[98:99], v[102:103], v[80:81]
	v_pk_add_f32 v[80:81], v[102:103], v[80:81] neg_lo:[0,1] neg_hi:[0,1]
	v_mul_f32_e32 v100, 0x3f3504f3, v81
	v_pk_fma_f32 v[80:81], v[80:81], s[96:97], v[100:101] op_sel_hi:[0,1,0] neg_lo:[0,0,1] neg_hi:[0,0,1]
	v_pk_add_f32 v[100:101], v[104:105], v[114:115]
	v_pk_add_f32 v[114:115], v[104:105], v[114:115] neg_lo:[0,1] neg_hi:[0,1]
	v_pk_mul_f32 v[102:103], v[114:115], s[84:85] op_sel:[1,0]
	v_pk_fma_f32 v[114:115], v[114:115], s[88:89], v[102:103] op_sel_hi:[0,1,1] neg_lo:[0,0,1] neg_hi:[0,0,1]
	v_pk_add_f32 v[102:103], v[78:79], v[10:11]
	v_pk_add_f32 v[10:11], v[78:79], v[10:11] neg_lo:[0,1] neg_hi:[0,1]
	v_mov_b32_e32 v104, v10
	v_mov_b32_e32 v105, v11
	v_pk_add_f32 v[10:11], v[14:15], v[6:7]
	v_pk_add_f32 v[6:7], v[14:15], v[6:7] neg_lo:[0,1] neg_hi:[0,1]
	v_pk_mul_f32 v[14:15], v[6:7], s[18:19] op_sel_hi:[1,0]
	v_pk_fma_f32 v[78:79], v[6:7], s[18:19], v[14:15] op_sel:[0,0,1] op_sel_hi:[1,0,0] neg_lo:[0,0,1]
	v_pk_add_f32 v[6:7], v[4:5], v[110:111]
	v_pk_add_f32 v[4:5], v[4:5], v[110:111] neg_lo:[0,1] neg_hi:[0,1]
	v_pk_add_f32 v[14:15], v[2:3], v[112:113]
	v_pk_add_f32 v[2:3], v[2:3], v[112:113] neg_lo:[0,1] neg_hi:[0,1]
	v_mul_f32_e32 v110, 0x3f3504f3, v3
	v_pk_fma_f32 v[2:3], v[2:3], s[96:97], v[110:111] op_sel_hi:[0,1,0] neg_lo:[0,0,1] neg_hi:[0,0,1]
	v_pk_add_f32 v[110:111], v[116:117], v[82:83]
	v_pk_add_f32 v[82:83], v[116:117], v[82:83] neg_lo:[0,1] neg_hi:[0,1]
	v_pk_add_f32 v[116:117], v[92:93], v[12:13]
	v_pk_add_f32 v[12:13], v[92:93], v[12:13] neg_lo:[0,1] neg_hi:[0,1]
	v_pk_mul_f32 v[92:93], v[12:13], s[18:19] op_sel_hi:[1,0]
	v_pk_fma_f32 v[112:113], v[12:13], s[18:19], v[92:93] op_sel:[0,0,1] op_sel_hi:[1,0,0] neg_lo:[0,0,1]
	v_pk_add_f32 v[12:13], v[106:107], v[8:9]
	v_pk_add_f32 v[8:9], v[106:107], v[8:9] neg_lo:[0,1] neg_hi:[0,1]
	v_pk_add_f32 v[92:93], v[8:9], 0 op_sel:[1,0] op_sel_hi:[0,0] neg_lo:[1,0]
	v_pk_add_f32 v[8:9], v[108:109], v[16:17]
	v_pk_add_f32 v[16:17], v[108:109], v[16:17] neg_lo:[0,1] neg_hi:[0,1]
	v_mul_f32_e32 v106, 0x3f3504f3, v17
	v_pk_fma_f32 v[16:17], v[16:17], s[96:97], v[106:107] op_sel_hi:[0,1,0] neg_lo:[0,0,1] neg_hi:[0,0,1]
	v_pk_add_f32 v[106:107], v[90:91], v[70:71]
	v_pk_add_f32 v[70:71], v[90:91], v[70:71] neg_lo:[0,1] neg_hi:[0,1]
	v_pk_add_f32 v[108:109], v[118:119], v[84:85]
	v_pk_add_f32 v[84:85], v[118:119], v[84:85] neg_lo:[0,1] neg_hi:[0,1]
	v_pk_mul_f32 v[118:119], v[84:85], s[18:19] op_sel_hi:[1,0]
	v_pk_fma_f32 v[90:91], v[84:85], s[18:19], v[118:119] op_sel:[0,0,1] op_sel_hi:[1,0,0] neg_lo:[0,0,1]
	v_pk_add_f32 v[84:85], v[18:19], v[98:99]
	v_pk_add_f32 v[18:19], v[18:19], v[98:99] neg_lo:[0,1] neg_hi:[0,1]
	v_pk_add_f32 v[118:119], v[72:73], v[100:101]
	v_pk_add_f32 v[72:73], v[72:73], v[100:101] neg_lo:[0,1] neg_hi:[0,1]
	v_mul_f32_e32 v98, 0x3f3504f3, v73
	v_pk_fma_f32 v[72:73], v[72:73], s[96:97], v[98:99] op_sel_hi:[0,1,0] neg_lo:[0,0,1] neg_hi:[0,0,1]
	v_pk_add_f32 v[98:99], v[68:69], v[76:77] op_sel:[0,1] op_sel_hi:[1,0] neg_lo:[0,1]
	v_pk_add_f32 v[76:77], v[68:69], v[76:77] op_sel:[0,1] op_sel_hi:[1,0] neg_hi:[0,1]
	v_pk_add_f32 v[68:69], v[0:1], v[86:87]
	v_pk_add_f32 v[86:87], v[0:1], v[86:87] neg_lo:[0,1] neg_hi:[0,1]
	v_pk_mul_f32 v[100:101], v[86:87], s[18:19] op_sel_hi:[1,0]
	v_pk_fma_f32 v[0:1], v[86:87], s[18:19], v[100:101] op_sel:[0,0,1] op_sel_hi:[1,0,0] neg_lo:[0,0,1]
	v_pk_add_f32 v[86:87], v[94:95], v[80:81]
; template <int R, bool INV> DEV void dft_regs(cf (&v)[R]) {
; #pragma unroll
;     for (int s = R; s >= 2; s >>= 1) {
;         const int h = s >> 1;
; #pragma unroll
;         for (int b = 0; b < R; b += s) {
; #pragma unroll
;             for (int k = 0; k < h; ++k) {
;                 const cf a = v[b + k], c = v[b + k + h];
;                 v[b + k] = a + c;
;                 const cf d = a - c;
;                 const int m = k * (32 / s);
;                 const float wr = tw_cos(m), wi = INV ? tw_sin(m) : -tw_sin(m);
;                 v[b + k + h] = cf{d.x * wr - d.y * wi, d.x * wi + d.y * wr};
;             }
;         }
;     }
; }
; DEV void fft_i2(LAS cf* buf, int t8) {
;     ...
;     dft_regs<32, true>(v);
; #pragma unroll
;     for (int q = 0; q < 32; ++q) pb[17 * q] = v[BR32[q]];
	v_pk_add_f32 v[80:81], v[94:95], v[80:81] neg_lo:[0,1] neg_hi:[0,1]
	v_pk_add_f32 v[94:95], v[96:97], v[114:115]
	v_pk_add_f32 v[114:115], v[96:97], v[114:115] neg_lo:[0,1] neg_hi:[0,1]
	v_mul_f32_e32 v96, 0x3f3504f3, v115
	v_pk_fma_f32 v[114:115], v[114:115], s[96:97], v[96:97] op_sel_hi:[0,1,0] neg_lo:[0,0,1] neg_hi:[0,0,1]
	v_pk_add_f32 v[96:97], v[102:103], v[6:7]
	v_pk_add_f32 v[6:7], v[102:103], v[6:7] neg_lo:[0,1] neg_hi:[0,1]
	v_mov_b32_e32 v102, v6
	v_mov_b32_e32 v103, v7
	v_pk_add_f32 v[6:7], v[10:11], v[14:15]
	v_pk_add_f32 v[14:15], v[10:11], v[14:15] neg_lo:[0,1] neg_hi:[0,1]
	v_pk_add_f32 v[10:11], v[14:15], 0 op_sel:[1,0] op_sel_hi:[0,0] neg_lo:[1,0]
	v_pk_add_f32 v[14:15], v[104:105], v[4:5] op_sel:[0,1] op_sel_hi:[1,0] neg_lo:[0,1]
	v_pk_add_f32 v[4:5], v[104:105], v[4:5] op_sel:[0,1] op_sel_hi:[1,0] neg_hi:[0,1]
	v_mov_b32_e32 v104, v4
	v_mov_b32_e32 v105, v5
	v_pk_add_f32 v[4:5], v[78:79], v[2:3]
	v_pk_add_f32 v[2:3], v[78:79], v[2:3] neg_lo:[0,1] neg_hi:[0,1]
	v_pk_add_f32 v[78:79], v[110:111], v[12:13]
	v_pk_add_f32 v[12:13], v[110:111], v[12:13] neg_lo:[0,1] neg_hi:[0,1]
	v_mov_b32_e32 v110, v12
	v_mov_b32_e32 v111, v13
	v_pk_add_f32 v[12:13], v[116:117], v[8:9]
	v_pk_add_f32 v[8:9], v[116:117], v[8:9] neg_lo:[0,1] neg_hi:[0,1]
	v_pk_add_f32 v[116:117], v[82:83], v[92:93]
	v_pk_add_f32 v[92:93], v[82:83], v[92:93] neg_lo:[0,1] neg_hi:[0,1]
	v_mov_b32_e32 v82, v92
	v_mov_b32_e32 v83, v93
	v_pk_add_f32 v[92:93], v[112:113], v[16:17]
	v_pk_add_f32 v[16:17], v[112:113], v[16:17] neg_lo:[0,1] neg_hi:[0,1]
	v_pk_add_f32 v[100:101], v[106:107], v[84:85]
	v_pk_add_f32 v[84:85], v[106:107], v[84:85] neg_lo:[0,1] neg_hi:[0,1]
	v_pk_add_f32 v[112:113], v[108:109], v[118:119]
	v_pk_add_f32 v[118:119], v[108:109], v[118:119] neg_lo:[0,1] neg_hi:[0,1]
	v_pk_add_f32 v[108:109], v[70:71], v[18:19] op_sel:[0,1] op_sel_hi:[1,0] neg_lo:[0,1]
	v_pk_add_f32 v[18:19], v[70:71], v[18:19] op_sel:[0,1] op_sel_hi:[1,0] neg_hi:[0,1]
	v_pk_add_f32 v[70:71], v[90:91], v[72:73]
	v_pk_add_f32 v[72:73], v[90:91], v[72:73] neg_lo:[0,1] neg_hi:[0,1]
	v_pk_add_f32 v[90:91], v[98:99], v[86:87]
	v_pk_add_f32 v[86:87], v[98:99], v[86:87] neg_lo:[0,1] neg_hi:[0,1]
	v_pk_add_f32 v[106:107], v[68:69], v[94:95]
	v_pk_add_f32 v[94:95], v[68:69], v[94:95] neg_lo:[0,1] neg_hi:[0,1]
	v_pk_add_f32 v[68:69], v[76:77], v[80:81] op_sel:[0,1] op_sel_hi:[1,0] neg_lo:[0,1]
	v_pk_add_f32 v[80:81], v[76:77], v[80:81] op_sel:[0,1] op_sel_hi:[1,0] neg_hi:[0,1]
	v_pk_add_f32 v[76:77], v[0:1], v[114:115]
	v_pk_add_f32 v[114:115], v[0:1], v[114:115] neg_lo:[0,1] neg_hi:[0,1]
	v_pk_add_f32 v[98:99], v[114:115], 0 op_sel:[1,0] op_sel_hi:[0,0] neg_lo:[1,0]
	v_pk_add_f32 v[0:1], v[96:97], v[6:7]
	v_pk_add_f32 v[6:7], v[96:97], v[6:7] neg_lo:[0,1] neg_hi:[0,1]
	v_mov_b32_e32 v114, v6
	v_mov_b32_e32 v115, v7
	v_pk_add_f32 v[6:7], v[102:103], v[10:11]
	v_pk_add_f32 v[10:11], v[102:103], v[10:11] neg_lo:[0,1] neg_hi:[0,1]
	v_mov_b32_e32 v102, v10
	v_mov_b32_e32 v103, v11
	v_pk_add_f32 v[10:11], v[14:15], v[4:5]
	v_pk_add_f32 v[14:15], v[14:15], v[4:5] neg_lo:[0,1] neg_hi:[0,1]
	v_mov_b32_e32 v96, v14
	v_mov_b32_e32 v97, v15
	v_pk_add_f32 v[14:15], v[104:105], v[2:3] op_sel:[0,1] op_sel_hi:[1,0] neg_hi:[0,1]
	v_pk_add_f32 v[4:5], v[104:105], v[2:3] op_sel:[0,1] op_sel_hi:[1,0] neg_lo:[0,1]
	v_mov_b32_e32 v104, v14
	v_mov_b32_e32 v105, v15
	v_pk_add_f32 v[14:15], v[78:79], v[12:13]
	v_pk_add_f32 v[2:3], v[78:79], v[12:13] neg_lo:[0,1] neg_hi:[0,1]
	v_mov_b32_e32 v78, v2
	v_mov_b32_e32 v79, v3
	v_pk_add_f32 v[12:13], v[110:111], v[8:9] op_sel:[0,1] op_sel_hi:[1,0] neg_hi:[0,1]
	v_pk_add_f32 v[2:3], v[110:111], v[8:9] op_sel:[0,1] op_sel_hi:[1,0] neg_lo:[0,1]
	v_mov_b32_e32 v110, v12
	v_mov_b32_e32 v111, v13
	v_pk_add_f32 v[12:13], v[116:117], v[92:93]
	v_pk_add_f32 v[8:9], v[116:117], v[92:93] neg_lo:[0,1] neg_hi:[0,1]
	v_mov_b32_e32 v92, v8
	v_mov_b32_e32 v93, v9
	v_pk_add_f32 v[116:117], v[82:83], v[16:17] op_sel:[0,1] op_sel_hi:[1,0] neg_hi:[0,1]
	v_pk_add_f32 v[8:9], v[82:83], v[16:17] op_sel:[0,1] op_sel_hi:[1,0] neg_lo:[0,1]
	v_pk_add_f32 v[82:83], v[100:101], v[112:113]
	v_pk_add_f32 v[16:17], v[100:101], v[112:113] neg_lo:[0,1] neg_hi:[0,1]
	v_pk_add_f32 v[100:101], v[84:85], v[118:119] op_sel:[0,1] op_sel_hi:[1,0] neg_lo:[0,1]
	v_pk_add_f32 v[118:119], v[84:85], v[118:119] op_sel:[0,1] op_sel_hi:[1,0] neg_hi:[0,1]
	v_pk_add_f32 v[84:85], v[108:109], v[70:71]
	v_pk_add_f32 v[108:109], v[108:109], v[70:71] neg_lo:[0,1] neg_hi:[0,1]
	v_pk_add_f32 v[112:113], v[18:19], v[72:73] op_sel:[0,1] op_sel_hi:[1,0] neg_hi:[0,1]
	v_pk_add_f32 v[70:71], v[18:19], v[72:73] op_sel:[0,1] op_sel_hi:[1,0] neg_lo:[0,1]
	v_pk_add_f32 v[18:19], v[90:91], v[106:107]
	v_pk_add_f32 v[72:73], v[90:91], v[106:107] neg_lo:[0,1] neg_hi:[0,1]
	v_pk_add_f32 v[106:107], v[86:87], v[94:95] op_sel:[0,1] op_sel_hi:[1,0] neg_hi:[0,1]
	v_pk_add_f32 v[90:91], v[86:87], v[94:95] op_sel:[0,1] op_sel_hi:[1,0] neg_lo:[0,1]
	v_pk_add_f32 v[86:87], v[68:69], v[76:77]
	v_pk_add_f32 v[94:95], v[68:69], v[76:77] neg_lo:[0,1] neg_hi:[0,1]
	v_pk_add_f32 v[68:69], v[80:81], v[98:99] neg_lo:[0,1] neg_hi:[0,1]
	v_pk_add_f32 v[76:77], v[80:81], v[98:99]
	v_mov_b32_e32 v80, v68
	v_mov_b32_e32 v81, v69
	ds_write2_b64 v74, v[0:1], v[82:83] offset1:17
	ds_write2_b64 v74, v[14:15], v[18:19] offset0:34 offset1:51
	ds_write2_b64 v74, v[10:11], v[84:85] offset0:68 offset1:85
	ds_write2_b64 v74, v[12:13], v[86:87] offset0:102 offset1:119
	ds_write2_b64 v74, v[6:7], v[100:101] offset0:136 offset1:153
	ds_write2_b64 v74, v[2:3], v[90:91] offset0:170 offset1:187
	ds_write2_b64 v74, v[4:5], v[70:71] offset0:204 offset1:221
	ds_write2_b64 v74, v[8:9], v[76:77] offset0:238 offset1:255
	ds_write2_b64 v75, v[114:115], v[16:17] offset0:16 offset1:33
	ds_write2_b64 v75, v[78:79], v[72:73] offset0:50 offset1:67
	ds_write2_b64 v75, v[96:97], v[108:109] offset0:84 offset1:101
	ds_write2_b64 v75, v[92:93], v[94:95] offset0:118 offset1:135
	ds_write2_b64 v75, v[102:103], v[118:119] offset0:152 offset1:169
	ds_write2_b64 v75, v[110:111], v[106:107] offset0:186 offset1:203
	ds_write2_b64 v75, v[104:105], v[112:113] offset0:220 offset1:237
	ds_write2_b64 v88, v[116:117], v[80:81] offset0:126 offset1:143
	s_mov_b32 s2, 0x1800000
	s_mov_b32 s2, 0x3000000
	s_nop 0
	s_mov_b32 s2, 0x4800000
	s_nop 0
	s_waitcnt lgkmcnt(0)
	s_barrier
; #define LAS __attribute__((address_space(3)))
; #define SINCOSPI(x, s, c) do { const float hx_ = 0.5f * (x); *(s) = __builtin_amdgcn_sinf(hx_); *(c) = __builtin_amdgcn_cosf(hx_); } while (0)
; #define OPAQUE_I(x) asm volatile("" : "+v"(x))
; DEV void fft_i1x2(LAS cf* buf0, LAS cf* buf1, cf (&y0)[8], cf (&y1)[8], int tid) {
;     OPAQUE_I(tid);
;     float sn, cs; SINCOSPI(-(float)tid * (2.0f / 8192.0f), &sn, &cs);
;     const cf w = cf{cs, sn}; cf wp = cf{1.f, 0.f};
;     cf v[16], u[16];
;     const LAS cf* p0 = buf0 + PADI(tid); const LAS cf* p1 = buf1 + PADI(tid);
; #pragma unroll
;     for (int p = 0; p < 16; ++p) { v[p] = cmulc(p0[544 * p], wp); u[p] = cmulc(p1[544 * p], wp); wp = cmul(wp, w); }
	s_nop 0
	v_mov_b32_e32 v100, v21
	s_andn2_b64 vcc, exec, s[26:27]
	v_cvt_f32_i32_e32 v101, v100
	v_mul_f32_e32 v101, 0xb9800000, v101
	v_mul_f32_e32 v101, 0.5, v101
	v_sin_f32_e32 v93, v101
	v_cos_f32_e32 v92, v101
	v_ashrrev_i32_e32 v101, 4, v100
	v_add_lshl_u32 v100, v101, v100, 3
	v_add_u32_e32 v163, 0, v100
	v_add_u32_e32 v164, s33, v100
	ds_read_b64 v[166:167], v163
	ds_read_b64 v[168:169], v164
	ds_read_b64 v[170:171], v163 offset:4352
	ds_read_b64 v[172:173], v164 offset:4352
	ds_read_b64 v[174:175], v163 offset:8704
	ds_read_b64 v[176:177], v164 offset:8704
	ds_read_b64 v[178:179], v163 offset:13056
	ds_read_b64 v[180:181], v164 offset:13056
	ds_read_b64 v[182:183], v163 offset:17408
	ds_read_b64 v[184:185], v164 offset:17408
	ds_read_b64 v[186:187], v163 offset:21760
	ds_read_b64 v[188:189], v164 offset:21760
	ds_read_b64 v[190:191], v163 offset:26112
	s_waitcnt lgkmcnt(12)
	v_pk_mul_f32 v[18:19], v[166:167], v[66:67] op_sel:[1,1] op_sel_hi:[1,0]
	v_pk_fma_f32 v[76:77], v[166:167], v[66:67], v[18:19] op_sel_hi:[0,1,1] neg_hi:[1,0,0]
	ds_read_b64 v[166:167], v164 offset:26112
	s_waitcnt lgkmcnt(12)
	v_pk_mul_f32 v[18:19], v[168:169], v[66:67] op_sel:[1,1] op_sel_hi:[1,0]
	v_pk_fma_f32 v[16:17], v[168:169], v[66:67], v[18:19] op_sel_hi:[0,1,1] neg_hi:[1,0,0]
	v_pk_mul_f32 v[18:19], v[66:67], v[92:93] op_sel:[1,1] op_sel_hi:[1,0] neg_lo:[1,0]
	v_pk_fma_f32 v[66:67], v[66:67], v[92:93], v[18:19] op_sel_hi:[0,1,1]
	ds_read_b64 v[168:169], v163 offset:30464
	s_waitcnt lgkmcnt(12)
	v_pk_mul_f32 v[68:69], v[170:171], v[66:67] op_sel:[1,1] op_sel_hi:[1,0]
	v_pk_fma_f32 v[78:79], v[170:171], v[66:67], v[68:69] op_sel_hi:[0,1,1] neg_hi:[1,0,0]
	ds_read_b64 v[170:171], v164 offset:30464
	s_waitcnt lgkmcnt(12)
	v_pk_mul_f32 v[68:69], v[172:173], v[66:67] op_sel:[1,1] op_sel_hi:[1,0]
	v_pk_fma_f32 v[18:19], v[172:173], v[66:67], v[68:69] op_sel_hi:[0,1,1] neg_hi:[1,0,0]
	v_pk_mul_f32 v[68:69], v[66:67], v[92:93] op_sel:[1,1] op_sel_hi:[1,0] neg_lo:[1,0]
	v_pk_fma_f32 v[70:71], v[66:67], v[92:93], v[68:69] op_sel_hi:[0,1,1]
	ds_read_b64 v[172:173], v163 offset:34816
	s_waitcnt lgkmcnt(12)
	v_pk_mul_f32 v[68:69], v[174:175], v[70:71] op_sel:[1,1] op_sel_hi:[1,0]
	v_pk_fma_f32 v[82:83], v[174:175], v[70:71], v[68:69] op_sel_hi:[0,1,1] neg_hi:[1,0,0]
	ds_read_b64 v[174:175], v164 offset:34816
	s_waitcnt lgkmcnt(12)
	v_pk_mul_f32 v[68:69], v[176:177], v[70:71] op_sel:[1,1] op_sel_hi:[1,0]
	v_pk_fma_f32 v[66:67], v[176:177], v[70:71], v[68:69] op_sel_hi:[0,1,1] neg_hi:[1,0,0]
	v_pk_mul_f32 v[68:69], v[70:71], v[92:93] op_sel:[1,1] op_sel_hi:[1,0] neg_lo:[1,0]
	v_pk_fma_f32 v[70:71], v[70:71], v[92:93], v[68:69] op_sel_hi:[0,1,1]
	ds_read_b64 v[176:177], v163 offset:39168
	s_waitcnt lgkmcnt(12)
	v_pk_mul_f32 v[72:73], v[178:179], v[70:71] op_sel:[1,1] op_sel_hi:[1,0]
	v_pk_fma_f32 v[84:85], v[178:179], v[70:71], v[72:73] op_sel_hi:[0,1,1] neg_hi:[1,0,0]
	ds_read_b64 v[178:179], v164 offset:39168
	s_waitcnt lgkmcnt(12)
	v_pk_mul_f32 v[72:73], v[180:181], v[70:71] op_sel:[1,1] op_sel_hi:[1,0]
	v_pk_fma_f32 v[68:69], v[180:181], v[70:71], v[72:73] op_sel_hi:[0,1,1] neg_hi:[1,0,0]
	v_pk_mul_f32 v[72:73], v[70:71], v[92:93] op_sel:[1,1] op_sel_hi:[1,0] neg_lo:[1,0]
	v_pk_fma_f32 v[74:75], v[70:71], v[92:93], v[72:73] op_sel_hi:[0,1,1]
	ds_read_b64 v[180:181], v163 offset:43520
	s_waitcnt lgkmcnt(12)
	v_pk_mul_f32 v[72:73], v[182:183], v[74:75] op_sel:[1,1] op_sel_hi:[1,0]
	v_pk_fma_f32 v[86:87], v[182:183], v[74:75], v[72:73] op_sel_hi:[0,1,1] neg_hi:[1,0,0]
	ds_read_b64 v[182:183], v164 offset:43520
	s_waitcnt lgkmcnt(12)
	v_pk_mul_f32 v[72:73], v[184:185], v[74:75] op_sel:[1,1] op_sel_hi:[1,0]
	v_pk_fma_f32 v[70:71], v[184:185], v[74:75], v[72:73] op_sel_hi:[0,1,1] neg_hi:[1,0,0]
	v_pk_mul_f32 v[72:73], v[74:75], v[92:93] op_sel:[1,1] op_sel_hi:[1,0] neg_lo:[1,0]
	v_pk_fma_f32 v[74:75], v[74:75], v[92:93], v[72:73] op_sel_hi:[0,1,1]
	ds_read_b64 v[184:185], v163 offset:47872
	s_waitcnt lgkmcnt(12)
	v_pk_mul_f32 v[80:81], v[186:187], v[74:75] op_sel:[1,1] op_sel_hi:[1,0]
	v_pk_fma_f32 v[90:91], v[186:187], v[74:75], v[80:81] op_sel_hi:[0,1,1] neg_hi:[1,0,0]
	ds_read_b64 v[186:187], v164 offset:47872
	s_waitcnt lgkmcnt(12)
	v_pk_mul_f32 v[80:81], v[188:189], v[74:75] op_sel:[1,1] op_sel_hi:[1,0]
	v_pk_fma_f32 v[72:73], v[188:189], v[74:75], v[80:81] op_sel_hi:[0,1,1] neg_hi:[1,0,0]
	v_pk_mul_f32 v[80:81], v[74:75], v[92:93] op_sel:[1,1] op_sel_hi:[1,0] neg_lo:[1,0]
	v_pk_fma_f32 v[88:89], v[74:75], v[92:93], v[80:81] op_sel_hi:[0,1,1]
	ds_read_b64 v[188:189], v163 offset:52224
	s_waitcnt lgkmcnt(12)
	v_pk_mul_f32 v[80:81], v[190:191], v[88:89] op_sel:[1,1] op_sel_hi:[1,0]
	v_pk_fma_f32 v[94:95], v[190:191], v[88:89], v[80:81] op_sel_hi:[0,1,1] neg_hi:[1,0,0]
	ds_read_b64 v[190:191], v164 offset:52224
	s_waitcnt lgkmcnt(12)
	v_pk_mul_f32 v[80:81], v[166:167], v[88:89] op_sel:[1,1] op_sel_hi:[1,0]
	v_pk_fma_f32 v[74:75], v[166:167], v[88:89], v[80:81] op_sel_hi:[0,1,1] neg_hi:[1,0,0]
	v_pk_mul_f32 v[80:81], v[88:89], v[92:93] op_sel:[1,1] op_sel_hi:[1,0] neg_lo:[1,0]
	v_pk_fma_f32 v[88:89], v[88:89], v[92:93], v[80:81] op_sel_hi:[0,1,1]
	ds_read_b64 v[166:167], v163 offset:56576
	s_waitcnt lgkmcnt(12)
	v_pk_mul_f32 v[96:97], v[168:169], v[88:89] op_sel:[1,1] op_sel_hi:[1,0]
	v_pk_fma_f32 v[98:99], v[168:169], v[88:89], v[96:97] op_sel_hi:[0,1,1] neg_hi:[1,0,0]
	ds_read_b64 v[168:169], v164 offset:56576
	s_waitcnt lgkmcnt(12)
; #define LAS __attribute__((address_space(3)))
; #define SYNC() __syncthreads()
; DEV void fft_i1x2(LAS cf* buf0, LAS cf* buf1, cf (&y0)[8], cf (&y1)[8], int tid) {
;     ...
;     const LAS cf* p0 = buf0 + PADI(tid); const LAS cf* p1 = buf1 + PADI(tid);
; #pragma unroll
;     for (int p = 0; p < 16; ++p) { v[p] = cmulc(p0[544 * p], wp); u[p] = cmulc(p1[544 * p], wp); wp = cmul(wp, w); }
; DEV void hyena_units(int c0, int cstride, const bf16_t* UT, bf16_t* YHT, const unsigned* KF, const float* convw  , const float* convb  , const float* hyb  , LAS unsigned char* lds, int tid, bool abl = false) {
;     ...
;             SYNC();
;             hyena_commit_rows(lds, r, tid);
;             if (o == 1 && c + cstride < 1024) hyena_issue_rows(UT, 0, c + cstride, r, tid);
	v_pk_mul_f32 v[96:97], v[170:171], v[88:89] op_sel:[1,1] op_sel_hi:[1,0]
	v_pk_fma_f32 v[80:81], v[170:171], v[88:89], v[96:97] op_sel_hi:[0,1,1] neg_hi:[1,0,0]
	v_pk_mul_f32 v[96:97], v[88:89], v[92:93] op_sel:[1,1] op_sel_hi:[1,0] neg_lo:[1,0]
	v_pk_fma_f32 v[102:103], v[88:89], v[92:93], v[96:97] op_sel_hi:[0,1,1]
	ds_read_b64 v[170:171], v163 offset:60928
	s_waitcnt lgkmcnt(12)
	v_pk_mul_f32 v[96:97], v[172:173], v[102:103] op_sel:[1,1] op_sel_hi:[1,0]
	v_pk_fma_f32 v[100:101], v[172:173], v[102:103], v[96:97] op_sel_hi:[0,1,1] neg_hi:[1,0,0]
	ds_read_b64 v[172:173], v164 offset:60928
	s_waitcnt lgkmcnt(12)
	v_pk_mul_f32 v[96:97], v[174:175], v[102:103] op_sel:[1,1] op_sel_hi:[1,0]
	v_pk_fma_f32 v[88:89], v[174:175], v[102:103], v[96:97] op_sel_hi:[0,1,1] neg_hi:[1,0,0]
	v_pk_mul_f32 v[96:97], v[102:103], v[92:93] op_sel:[1,1] op_sel_hi:[1,0] neg_lo:[1,0]
	v_pk_fma_f32 v[102:103], v[102:103], v[92:93], v[96:97] op_sel_hi:[0,1,1]
	ds_read_b64 v[174:175], v163 offset:65280
	s_waitcnt lgkmcnt(12)
	v_pk_mul_f32 v[104:105], v[176:177], v[102:103] op_sel:[1,1] op_sel_hi:[1,0]
	v_pk_fma_f32 v[112:113], v[176:177], v[102:103], v[104:105] op_sel_hi:[0,1,1] neg_hi:[1,0,0]
	ds_read_b64 v[176:177], v164 offset:65280
	s_waitcnt lgkmcnt(12)
	v_pk_mul_f32 v[104:105], v[178:179], v[102:103] op_sel:[1,1] op_sel_hi:[1,0]
	v_pk_fma_f32 v[96:97], v[178:179], v[102:103], v[104:105] op_sel_hi:[0,1,1] neg_hi:[1,0,0]
	v_pk_mul_f32 v[104:105], v[102:103], v[92:93] op_sel:[1,1] op_sel_hi:[1,0] neg_lo:[1,0]
	v_pk_fma_f32 v[106:107], v[102:103], v[92:93], v[104:105] op_sel_hi:[0,1,1]
	s_waitcnt lgkmcnt(11)
	v_pk_mul_f32 v[104:105], v[180:181], v[106:107] op_sel:[1,1] op_sel_hi:[1,0]
	v_pk_fma_f32 v[116:117], v[180:181], v[106:107], v[104:105] op_sel_hi:[0,1,1] neg_hi:[1,0,0]
	s_waitcnt lgkmcnt(10)
	v_pk_mul_f32 v[104:105], v[182:183], v[106:107] op_sel:[1,1] op_sel_hi:[1,0]
	v_pk_fma_f32 v[102:103], v[182:183], v[106:107], v[104:105] op_sel_hi:[0,1,1] neg_hi:[1,0,0]
	v_pk_mul_f32 v[104:105], v[106:107], v[92:93] op_sel:[1,1] op_sel_hi:[1,0] neg_lo:[1,0]
	v_pk_fma_f32 v[106:107], v[106:107], v[92:93], v[104:105] op_sel_hi:[0,1,1]
	s_waitcnt lgkmcnt(9)
	v_pk_mul_f32 v[108:109], v[184:185], v[106:107] op_sel:[1,1] op_sel_hi:[1,0]
	v_pk_fma_f32 v[118:119], v[184:185], v[106:107], v[108:109] op_sel_hi:[0,1,1] neg_hi:[1,0,0]
	s_waitcnt lgkmcnt(8)
	v_pk_mul_f32 v[108:109], v[186:187], v[106:107] op_sel:[1,1] op_sel_hi:[1,0]
	v_pk_fma_f32 v[104:105], v[186:187], v[106:107], v[108:109] op_sel_hi:[0,1,1] neg_hi:[1,0,0]
	v_pk_mul_f32 v[108:109], v[106:107], v[92:93] op_sel:[1,1] op_sel_hi:[1,0] neg_lo:[1,0]
	v_pk_fma_f32 v[110:111], v[106:107], v[92:93], v[108:109] op_sel_hi:[0,1,1]
	s_waitcnt lgkmcnt(7)
	v_pk_mul_f32 v[108:109], v[188:189], v[110:111] op_sel:[1,1] op_sel_hi:[1,0]
	v_pk_fma_f32 v[120:121], v[188:189], v[110:111], v[108:109] op_sel_hi:[0,1,1] neg_hi:[1,0,0]
	s_waitcnt lgkmcnt(6)
	v_pk_mul_f32 v[108:109], v[190:191], v[110:111] op_sel:[1,1] op_sel_hi:[1,0]
	v_pk_fma_f32 v[106:107], v[190:191], v[110:111], v[108:109] op_sel_hi:[0,1,1] neg_hi:[1,0,0]
	v_pk_mul_f32 v[108:109], v[110:111], v[92:93] op_sel:[1,1] op_sel_hi:[1,0] neg_lo:[1,0]
	v_pk_fma_f32 v[110:111], v[110:111], v[92:93], v[108:109] op_sel_hi:[0,1,1]
	s_waitcnt lgkmcnt(5)
	v_pk_mul_f32 v[114:115], v[166:167], v[110:111] op_sel:[1,1] op_sel_hi:[1,0]
	v_pk_fma_f32 v[122:123], v[166:167], v[110:111], v[114:115] op_sel_hi:[0,1,1] neg_hi:[1,0,0]
	s_waitcnt lgkmcnt(4)
	v_pk_mul_f32 v[114:115], v[168:169], v[110:111] op_sel:[1,1] op_sel_hi:[1,0]
	v_pk_fma_f32 v[108:109], v[168:169], v[110:111], v[114:115] op_sel_hi:[0,1,1] neg_hi:[1,0,0]
	v_pk_mul_f32 v[114:115], v[110:111], v[92:93] op_sel:[1,1] op_sel_hi:[1,0] neg_lo:[1,0]
	v_pk_fma_f32 v[126:127], v[110:111], v[92:93], v[114:115] op_sel_hi:[0,1,1]
	s_waitcnt lgkmcnt(3)
	v_pk_mul_f32 v[114:115], v[170:171], v[126:127] op_sel:[1,1] op_sel_hi:[1,0]
	v_pk_fma_f32 v[124:125], v[170:171], v[126:127], v[114:115] op_sel_hi:[0,1,1] neg_hi:[1,0,0]
	s_waitcnt lgkmcnt(2)
	v_pk_mul_f32 v[114:115], v[172:173], v[126:127] op_sel:[1,1] op_sel_hi:[1,0]
	v_pk_fma_f32 v[110:111], v[172:173], v[126:127], v[114:115] op_sel_hi:[0,1,1] neg_hi:[1,0,0]
	v_pk_mul_f32 v[114:115], v[126:127], v[92:93] op_sel:[1,1] op_sel_hi:[1,0] neg_lo:[1,0]
	v_pk_fma_f32 v[126:127], v[126:127], v[92:93], v[114:115] op_sel_hi:[0,1,1]
	s_waitcnt lgkmcnt(1)
	v_pk_mul_f32 v[114:115], v[174:175], v[126:127] op_sel:[1,1] op_sel_hi:[1,0]
	v_pk_fma_f32 v[92:93], v[174:175], v[126:127], v[114:115] op_sel_hi:[0,1,1] neg_hi:[1,0,0]
	s_waitcnt lgkmcnt(0)
	v_pk_mul_f32 v[164:165], v[176:177], v[126:127] op_sel:[1,1] op_sel_hi:[1,0]
	v_pk_fma_f32 v[114:115], v[176:177], v[126:127], v[164:165] op_sel_hi:[0,1,1] neg_hi:[1,0,0]
	s_barrier
	s_waitcnt vmcnt(3)
	ds_write_b128 v128, v[222:225]
	s_waitcnt vmcnt(2)
	ds_write_b128 v128, v[226:229] offset:8192
	s_waitcnt vmcnt(1)
	ds_write_b128 v128, v[236:239] offset:16384
	s_waitcnt vmcnt(0)
	ds_write_b128 v128, v[240:243] offset:24576
	s_cbranch_vccnz .LBB0_518
	s_andn2_b64 vcc, exec, s[20:21]
	s_cbranch_vccnz .LBB0_518
	global_load_dwordx4 v[0:3], v[58:59], off
	global_load_dwordx4 v[4:7], v[60:61], off
	global_load_dwordx4 v[8:11], v[62:63], off
	global_load_dwordx4 v[12:15], v[64:65], off
	s_branch .LBB0_518
